# hybrid: setprio 1 before the pre-MMA barrier, setprio 0 before the post-MMA barrier (rest = v24)
# speedup vs baseline: 1.0048x; 1.0048x over previous
; #define PG8_WAIT_V(n) asm volatile("s_waitcnt vmcnt(" #n ")" ::: "memory")
; template <class Epi, bool ALIGN_EPI, bool SP2, class Hook>
; __device__ __forceinline__ void gemm_phase(LAS unsigned char* lds, const Gemm g, const StaticOrder& S, const Epi& E, Acc& acc, const bool fresh, const Hook& H, const int wave_id) {
;     ...
;         if constexpr (SP2 && Epi::NSTORE > 0) {
;             const Src a1 = cA + kstep, a2 = cA + 2 * kstep, b2 = cB + 2 * kstep, a3 = a2 + kstep, b3 = b2 + kstep;
;             if constexpr (Epi::NSTORE == 16) PG8_TRIP_SP2(PG8_WAIT_V(24)); else PG8_TRIP_SP2(PG8_WAIT_V(16));
.LBB0_382:
	ds_read_b128 v[2:5], v150
	ds_read_b128 v[6:9], v150 offset:1024
	ds_read_b128 v[10:13], v150 offset:2048
	ds_read_b128 v[14:17], v150 offset:3072
	ds_read_b128 v[18:21], v151
	ds_read_b128 v[22:25], v151 offset:1024
	ds_read_b128 v[26:29], v151 offset:2048
	ds_read_b128 v[30:33], v151 offset:3072
	s_or_b32 s9, s68, 0x100
	s_or_b32 s8, s68, 0x180
	s_or_b32 s10, s69, 0x100
	s_or_b32 s11, s68, 0x40080
	s_mov_b32 m0, s45
	ds_read_b128 v[34:37], v149
	ds_read_b128 v[38:41], v149 offset:1024
	ds_read_b128 v[42:45], v149 offset:2048
	ds_read_b128 v[46:49], v149 offset:3072
	ds_read_b128 v[50:53], v149 offset:4096
	ds_read_b128 v[54:57], v149 offset:5120
	ds_read_b128 v[58:61], v149 offset:6144
	ds_read_b128 v[62:65], v149 offset:7168
	buffer_load_dwordx4 v144, s[0:3], s11 offen lds
	s_mov_b32 m0, s46
	s_nop 0
	buffer_load_dwordx4 v146, s[0:3], s11 offen lds
	s_waitcnt vmcnt(24)
	s_waitcnt lgkmcnt(0)
	s_setprio 1
	s_barrier
	v_mfma_f32_16x16x32_bf16 v[86:89], v[10:13], v[50:53], 0
	v_mfma_f32_16x16x32_bf16 v[92:95], v[14:17], v[54:57], v[86:89]
	v_mfma_f32_16x16x32_bf16 v[86:89], v[2:5], v[58:61], 0
	v_mfma_f32_16x16x32_bf16 v[66:69], v[2:5], v[34:37], 0
	v_mfma_f32_16x16x32_bf16 v[70:73], v[10:13], v[34:37], 0
	v_mfma_f32_16x16x32_bf16 v[74:77], v[2:5], v[42:45], 0
	v_mfma_f32_16x16x32_bf16 v[78:81], v[10:13], v[42:45], 0
	v_mfma_f32_16x16x32_bf16 v[82:85], v[2:5], v[50:53], 0
	v_mfma_f32_16x16x32_bf16 v[96:99], v[6:9], v[62:65], v[86:89]
	v_mfma_f32_16x16x32_bf16 v[86:89], v[10:13], v[58:61], 0
	v_mfma_f32_16x16x32_bf16 v[66:69], v[6:9], v[38:41], v[66:69]
	v_mfma_f32_16x16x32_bf16 v[70:73], v[14:17], v[38:41], v[70:73]
	v_mfma_f32_16x16x32_bf16 v[74:77], v[6:9], v[46:49], v[74:77]
	v_mfma_f32_16x16x32_bf16 v[78:81], v[14:17], v[46:49], v[78:81]
	v_mfma_f32_16x16x32_bf16 v[82:85], v[6:9], v[54:57], v[82:85]
	v_mfma_f32_16x16x32_bf16 v[104:107], v[14:17], v[62:65], v[86:89]
	v_mfma_f32_16x16x32_bf16 v[86:89], v[18:21], v[34:37], 0
	v_mfma_f32_16x16x32_bf16 v[34:37], v[26:29], v[34:37], 0
	v_mfma_f32_16x16x32_bf16 v[116:119], v[30:33], v[38:41], v[34:37]
	v_mfma_f32_16x16x32_bf16 v[34:37], v[18:21], v[42:45], 0
	v_mfma_f32_16x16x32_bf16 v[132:135], v[22:25], v[46:49], v[34:37]
	v_mfma_f32_16x16x32_bf16 v[34:37], v[26:29], v[42:45], 0
	v_mfma_f32_16x16x32_bf16 v[108:111], v[22:25], v[38:41], v[86:89]
	v_mfma_f32_16x16x32_bf16 v[40:43], v[30:33], v[46:49], v[34:37]
	v_mfma_f32_16x16x32_bf16 v[34:37], v[18:21], v[50:53], 0
	v_mfma_f32_16x16x32_bf16 v[44:47], v[22:25], v[54:57], v[34:37]
	v_mfma_f32_16x16x32_bf16 v[34:37], v[26:29], v[50:53], 0
	v_mfma_f32_16x16x32_bf16 v[48:51], v[30:33], v[54:57], v[34:37]
	v_mfma_f32_16x16x32_bf16 v[34:37], v[18:21], v[58:61], 0
	v_mfma_f32_16x16x32_bf16 v[52:55], v[22:25], v[62:65], v[34:37]
	v_mfma_f32_16x16x32_bf16 v[34:37], v[26:29], v[58:61], 0
	v_mfma_f32_16x16x32_bf16 v[60:63], v[30:33], v[62:65], v[34:37]
	s_setprio 0
	s_barrier
	s_mov_b32 m0, s92
	s_nop 3
	ds_read_b128 v[34:37], v149 offset:16384
	ds_read_b128 v[56:59], v149 offset:17408
	ds_read_b128 v[86:89], v149 offset:18432
	ds_read_b128 v[100:103], v149 offset:19456
	ds_read_b128 v[112:115], v149 offset:20480
	ds_read_b128 v[120:123], v149 offset:21504
	ds_read_b128 v[124:127], v149 offset:22528
	ds_read_b128 v[128:131], v149 offset:23552
	buffer_load_dwordx4 v145, s[4:7], s10 offen lds
	s_mov_b32 m0, s93
	s_nop 0
	buffer_load_dwordx4 v147, s[4:7], s10 offen lds
	s_or_b32 s10, s69, 0x40100
	s_mov_b32 m0, s94
	s_nop 0
	buffer_load_dwordx4 v145, s[4:7], s10 offen lds
	s_mov_b32 m0, s95
	s_nop 0
	buffer_load_dwordx4 v147, s[4:7], s10 offen lds
	s_mov_b32 m0, s44
	s_nop 0
	buffer_load_dwordx4 v144, s[0:3], s9 offen lds
	s_mov_b32 m0, s36
	s_nop 0
	buffer_load_dwordx4 v146, s[0:3], s9 offen lds
	s_waitcnt vmcnt(24)
	s_waitcnt lgkmcnt(0)
	s_setprio 1
	s_barrier
	v_mfma_f32_16x16x32_bf16 v[136:139], v[2:5], v[34:37], 0
	v_mfma_f32_16x16x32_bf16 v[154:157], v[2:5], v[86:89], 0
	v_mfma_f32_16x16x32_bf16 v[162:165], v[2:5], v[112:115], 0
	v_mfma_f32_16x16x32_bf16 v[2:5], v[2:5], v[124:127], 0
	v_mfma_f32_16x16x32_bf16 v[136:139], v[6:9], v[56:59], v[136:139]
	v_mfma_f32_16x16x32_bf16 v[140:143], v[10:13], v[34:37], 0
	v_mfma_f32_16x16x32_bf16 v[154:157], v[6:9], v[100:103], v[154:157]
	v_mfma_f32_16x16x32_bf16 v[158:161], v[10:13], v[86:89], 0
	v_mfma_f32_16x16x32_bf16 v[162:165], v[6:9], v[120:123], v[162:165]
	v_mfma_f32_16x16x32_bf16 v[166:169], v[10:13], v[112:115], 0
	v_mfma_f32_16x16x32_bf16 v[2:5], v[6:9], v[128:131], v[2:5]
	v_mfma_f32_16x16x32_bf16 v[6:9], v[10:13], v[124:127], 0
	v_mfma_f32_16x16x32_bf16 v[140:143], v[14:17], v[56:59], v[140:143]
	v_mfma_f32_16x16x32_bf16 v[158:161], v[14:17], v[100:103], v[158:161]
	v_mfma_f32_16x16x32_bf16 v[166:169], v[14:17], v[120:123], v[166:169]
	v_mfma_f32_16x16x32_bf16 v[170:173], v[14:17], v[128:131], v[6:9]
	v_mfma_f32_16x16x32_bf16 v[6:9], v[18:21], v[34:37], 0
	v_mfma_f32_16x16x32_bf16 v[174:177], v[22:25], v[56:59], v[6:9]
	v_mfma_f32_16x16x32_bf16 v[6:9], v[26:29], v[34:37], 0
	v_mfma_f32_16x16x32_bf16 v[178:181], v[30:33], v[56:59], v[6:9]
	v_mfma_f32_16x16x32_bf16 v[6:9], v[18:21], v[86:89], 0
	v_mfma_f32_16x16x32_bf16 v[182:185], v[22:25], v[100:103], v[6:9]
	v_mfma_f32_16x16x32_bf16 v[6:9], v[26:29], v[86:89], 0
	v_mfma_f32_16x16x32_bf16 v[186:189], v[30:33], v[100:103], v[6:9]
	v_mfma_f32_16x16x32_bf16 v[6:9], v[18:21], v[112:115], 0
	v_mfma_f32_16x16x32_bf16 v[190:193], v[22:25], v[120:123], v[6:9]
	v_mfma_f32_16x16x32_bf16 v[6:9], v[26:29], v[112:115], 0
	v_mfma_f32_16x16x32_bf16 v[212:215], v[30:33], v[120:123], v[6:9]
	v_mfma_f32_16x16x32_bf16 v[6:9], v[18:21], v[124:127], 0
	v_mfma_f32_16x16x32_bf16 v[20:23], v[22:25], v[128:131], v[6:9]
	v_mfma_f32_16x16x32_bf16 v[6:9], v[26:29], v[124:127], 0
	v_mfma_f32_16x16x32_bf16 v[216:219], v[30:33], v[128:131], v[6:9]
	s_setprio 0
	s_barrier
	s_nop 4
	ds_read_b128 v[6:9], v152
	ds_read_b128 v[24:27], v152 offset:1024
	ds_read_b128 v[228:231], v152 offset:2048
	ds_read_b128 v[232:235], v152 offset:3072
	ds_read_b128 v[236:239], v153
	ds_read_b128 v[240:243], v153 offset:1024
	ds_read_b128 v[244:247], v153 offset:2048
	ds_read_b128 v[150:153], v153 offset:3072
	s_or_b32 s9, s68, 0x40100
	s_mov_b32 m0, s37
	ds_read_b128 v[10:13], v149 offset:32768
	ds_read_b128 v[14:17], v149 offset:33792
	ds_read_b128 v[32:35], v149 offset:34816
	ds_read_b128 v[194:197], v149 offset:35840
	ds_read_b128 v[208:211], v149 offset:36864
	ds_read_b128 v[200:203], v149 offset:37888
	ds_read_b128 v[204:207], v149 offset:38912
	ds_read_b128 v[220:223], v149 offset:39936
	buffer_load_dwordx4 v144, s[0:3], s9 offen lds
	s_mov_b32 m0, s38
	s_nop 0
	buffer_load_dwordx4 v146, s[0:3], s9 offen lds
	s_waitcnt vmcnt(8)
	s_waitcnt lgkmcnt(0)
	s_setprio 1
	s_barrier
	v_mfma_f32_16x16x32_bf16 v[28:31], v[6:9], v[10:13], v[66:69]
	v_mfma_f32_16x16x32_bf16 v[120:123], v[24:27], v[14:17], v[28:31]
	v_mfma_f32_16x16x32_bf16 v[28:31], v[228:231], v[10:13], v[70:73]
	v_mfma_f32_16x16x32_bf16 v[112:115], v[232:235], v[14:17], v[28:31]
	v_mfma_f32_16x16x32_bf16 v[28:31], v[6:9], v[32:35], v[74:77]
	v_mfma_f32_16x16x32_bf16 v[100:103], v[24:27], v[194:197], v[28:31]
	v_mfma_f32_16x16x32_bf16 v[28:31], v[228:231], v[32:35], v[78:81]
	v_mfma_f32_16x16x32_bf16 v[88:91], v[232:235], v[194:197], v[28:31]
	v_mfma_f32_16x16x32_bf16 v[28:31], v[6:9], v[208:211], v[82:85]
	v_mfma_f32_16x16x32_bf16 v[68:71], v[24:27], v[200:203], v[28:31]
	v_mfma_f32_16x16x32_bf16 v[28:31], v[228:231], v[208:211], v[92:95]
	v_mfma_f32_16x16x32_bf16 v[56:59], v[232:235], v[200:203], v[28:31]
	v_mfma_f32_16x16x32_bf16 v[28:31], v[6:9], v[204:207], v[96:99]
	v_mfma_f32_16x16x32_bf16 v[36:39], v[24:27], v[220:223], v[28:31]
	v_mfma_f32_16x16x32_bf16 v[28:31], v[228:231], v[204:207], v[104:107]
	v_mfma_f32_16x16x32_bf16 v[28:31], v[232:235], v[220:223], v[28:31]
	v_mfma_f32_16x16x32_bf16 v[64:67], v[236:239], v[10:13], v[108:111]
	v_mfma_f32_16x16x32_bf16 v[10:13], v[244:247], v[10:13], v[116:119]
	v_mfma_f32_16x16x32_bf16 v[124:127], v[150:153], v[14:17], v[10:13]
	v_mfma_f32_16x16x32_bf16 v[10:13], v[236:239], v[32:35], v[132:135]
	v_mfma_f32_16x16x32_bf16 v[116:119], v[240:243], v[194:197], v[10:13]
	v_mfma_f32_16x16x32_bf16 v[10:13], v[244:247], v[32:35], v[40:43]
	v_mfma_f32_16x16x32_bf16 v[108:111], v[150:153], v[194:197], v[10:13]
	v_mfma_f32_16x16x32_bf16 v[10:13], v[236:239], v[208:211], v[44:47]
	v_mfma_f32_16x16x32_bf16 v[92:95], v[240:243], v[200:203], v[10:13]
	v_mfma_f32_16x16x32_bf16 v[10:13], v[244:247], v[208:211], v[48:51]
	v_mfma_f32_16x16x32_bf16 v[80:83], v[150:153], v[200:203], v[10:13]
	v_mfma_f32_16x16x32_bf16 v[10:13], v[236:239], v[204:207], v[52:55]
	v_mfma_f32_16x16x32_bf16 v[128:131], v[240:243], v[14:17], v[64:67]
	v_mfma_f32_16x16x32_bf16 v[64:67], v[240:243], v[220:223], v[10:13]
	v_mfma_f32_16x16x32_bf16 v[10:13], v[244:247], v[204:207], v[60:63]
	v_mfma_f32_16x16x32_bf16 v[48:51], v[150:153], v[220:223], v[10:13]
	s_setprio 0
	s_barrier
	s_mov_b32 m0, s39
	s_or_b32 s9, s69, 0x180
	ds_read_b128 v[44:47], v149 offset:49152
	ds_read_b128 v[52:55], v149 offset:50176
	ds_read_b128 v[76:79], v149 offset:51200
	ds_read_b128 v[132:135], v149 offset:52224
	ds_read_b128 v[194:197], v149 offset:53248
	ds_read_b128 v[200:203], v149 offset:54272
	ds_read_b128 v[204:207], v149 offset:55296
	ds_read_b128 v[208:211], v149 offset:56320
	buffer_load_dwordx4 v145, s[4:7], s9 offen lds
	s_mov_b32 m0, s40
	s_nop 0
	buffer_load_dwordx4 v147, s[4:7], s9 offen lds
	s_or_b32 s9, s69, 0x40180
	s_mov_b32 m0, s43
	s_nop 0
	buffer_load_dwordx4 v145, s[4:7], s9 offen lds
	s_mov_b32 m0, s42
	s_nop 0
	buffer_load_dwordx4 v147, s[4:7], s9 offen lds
	s_mov_b32 m0, s41
	s_nop 0
	buffer_load_dwordx4 v144, s[0:3], s8 offen lds
	s_mov_b32 m0, s33
	s_nop 0
	buffer_load_dwordx4 v146, s[0:3], s8 offen lds
	s_waitcnt vmcnt(8)
	s_waitcnt lgkmcnt(0)
	s_setprio 1
	s_barrier
	v_mfma_f32_16x16x32_bf16 v[10:13], v[6:9], v[44:47], v[136:139]
	v_mfma_f32_16x16x32_bf16 v[72:75], v[24:27], v[52:55], v[10:13]
	v_mfma_f32_16x16x32_bf16 v[10:13], v[228:231], v[44:47], v[140:143]
	v_mfma_f32_16x16x32_bf16 v[60:63], v[232:235], v[52:55], v[10:13]
	v_mfma_f32_16x16x32_bf16 v[10:13], v[6:9], v[76:79], v[154:157]
	v_mfma_f32_16x16x32_bf16 v[40:43], v[24:27], v[132:135], v[10:13]
	v_mfma_f32_16x16x32_bf16 v[10:13], v[228:231], v[76:79], v[158:161]
	v_mfma_f32_16x16x32_bf16 v[32:35], v[232:235], v[132:135], v[10:13]
	v_mfma_f32_16x16x32_bf16 v[10:13], v[6:9], v[194:197], v[162:165]
	v_mfma_f32_16x16x32_bf16 v[16:19], v[24:27], v[200:203], v[10:13]
	v_mfma_f32_16x16x32_bf16 v[10:13], v[228:231], v[194:197], v[166:169]
	v_mfma_f32_16x16x32_bf16 v[2:5], v[6:9], v[204:207], v[2:5]
	v_mfma_f32_16x16x32_bf16 v[12:15], v[232:235], v[200:203], v[10:13]
	v_mfma_f32_16x16x32_bf16 v[8:11], v[24:27], v[208:211], v[2:5]
	v_mfma_f32_16x16x32_bf16 v[2:5], v[228:231], v[204:207], v[170:173]
	v_mfma_f32_16x16x32_bf16 v[4:7], v[232:235], v[208:211], v[2:5]
	v_mfma_f32_16x16x32_bf16 v[24:27], v[236:239], v[44:47], v[174:177]
	v_mfma_f32_16x16x32_bf16 v[96:99], v[240:243], v[52:55], v[24:27]
	v_mfma_f32_16x16x32_bf16 v[24:27], v[244:247], v[44:47], v[178:181]
	v_mfma_f32_16x16x32_bf16 v[104:107], v[150:153], v[52:55], v[24:27]
	v_mfma_f32_16x16x32_bf16 v[24:27], v[236:239], v[76:79], v[182:185]
	v_mfma_f32_16x16x32_bf16 v[84:87], v[240:243], v[132:135], v[24:27]
	v_mfma_f32_16x16x32_bf16 v[24:27], v[244:247], v[76:79], v[186:189]
	v_mfma_f32_16x16x32_bf16 v[76:79], v[150:153], v[132:135], v[24:27]
	v_mfma_f32_16x16x32_bf16 v[24:27], v[236:239], v[194:197], v[190:193]
	v_mfma_f32_16x16x32_bf16 v[52:55], v[240:243], v[200:203], v[24:27]
	v_mfma_f32_16x16x32_bf16 v[24:27], v[244:247], v[194:197], v[212:215]
	v_mfma_f32_16x16x32_bf16 v[20:23], v[236:239], v[204:207], v[20:23]
	v_mfma_f32_16x16x32_bf16 v[44:47], v[150:153], v[200:203], v[24:27]
	v_mfma_f32_16x16x32_bf16 v[24:27], v[240:243], v[208:211], v[20:23]
	v_mfma_f32_16x16x32_bf16 v[20:23], v[244:247], v[204:207], v[216:219]
	v_mfma_f32_16x16x32_bf16 v[20:23], v[150:153], v[208:211], v[20:23]
	s_setprio 0
	s_barrier
	s_mov_b64 s[8:9], 0
	v_mov_b64_e32 v[234:235], v[198:199]
	v_mov_b64_e32 v[236:237], v[226:227]
	v_mov_b32_e32 v198, v0
	v_mov_b32_e32 v226, v225
	v_mov_b64_e32 v[244:245], 0x100
	v_mov_b64_e32 v[246:247], 0xff

; #define PG8_WAIT_V(n) asm volatile("s_waitcnt vmcnt(" #n ")" ::: "memory")
; template <class Epi, bool ALIGN_EPI, bool SP2, class Hook>
; __device__ __forceinline__ void gemm_phase(LAS unsigned char* lds, const Gemm g, const StaticOrder& S, const Epi& E, Acc& acc, const bool fresh, const Hook& H, const int wave_id) {
;     ...
;         for (int t = t0; t < nt; t += 2) {
;             const bool last = (t == nt - 2);
;             const Src a1 = cA + (size_t)(t + 1) * kstep;
;             const Src a2 = last ? nA : cA + (size_t)(t + 2) * kstep, b2 = last ? nB : cB + (size_t)(t + 2) * kstep;
;             const Src a3 = a2 + kstep, b3 = b2 + kstep;
;             if (last && has_next) H(nxt);
;             if constexpr (SP2) {
;             PG8_TRIP_SP2(PG8_WAIT_V(8));
.LBB0_391:
	v_add_u32_e32 v150, 0x10000, v148
	v_add_u32_e32 v151, 0x14000, v148
	ds_read_b128 v[132:135], v150
	ds_read_b128 v[136:139], v150 offset:1024
	ds_read_b128 v[140:143], v150 offset:2048
	ds_read_b128 v[152:155], v150 offset:3072
	ds_read_b128 v[156:159], v151
	ds_read_b128 v[160:163], v151 offset:1024
	ds_read_b128 v[164:167], v151 offset:2048
	ds_read_b128 v[168:171], v151 offset:3072
	s_add_i32 s12, s56, 0xfffc0080
	s_cmp_eq_u32 s29, 12
	s_cselect_b32 s60, s68, s12
	s_cselect_b32 s13, s5, s77
	s_cselect_b32 s12, s4, s76
	s_cselect_b32 s15, s7, s55
	s_cselect_b32 s14, s6, s54
	s_cselect_b32 s58, s69, s57
	s_cselect_b32 s16, s0, s8
	s_cselect_b32 s17, s1, s9
	s_cselect_b32 s18, s2, s10
	s_cselect_b32 s19, s3, s11
	s_or_b32 s59, s60, 0x80
	s_mov_b32 m0, s45
	ds_read_b128 v[172:175], v149
	ds_read_b128 v[176:179], v149 offset:1024
	ds_read_b128 v[180:183], v149 offset:2048
	ds_read_b128 v[184:187], v149 offset:3072
	ds_read_b128 v[188:191], v149 offset:4096
	ds_read_b128 v[212:215], v149 offset:5120
	ds_read_b128 v[216:219], v149 offset:6144
	ds_read_b128 v[228:231], v149 offset:7168
	buffer_load_dwordx4 v144, s[8:11], s56 offen lds
	s_mov_b32 m0, s46
	s_nop 0
	buffer_load_dwordx4 v146, s[8:11], s56 offen lds
	s_waitcnt vmcnt(8)
	s_waitcnt lgkmcnt(0)
	s_setprio 1
	s_barrier
	v_mfma_f32_16x16x32_bf16 v[120:123], v[132:135], v[172:175], v[120:123]
	v_mfma_f32_16x16x32_bf16 v[112:115], v[140:143], v[172:175], v[112:115]
	v_mfma_f32_16x16x32_bf16 v[100:103], v[132:135], v[180:183], v[100:103]
	v_mfma_f32_16x16x32_bf16 v[88:91], v[140:143], v[180:183], v[88:91]
	v_mfma_f32_16x16x32_bf16 v[68:71], v[132:135], v[188:191], v[68:71]
	v_mfma_f32_16x16x32_bf16 v[56:59], v[140:143], v[188:191], v[56:59]
	v_mfma_f32_16x16x32_bf16 v[36:39], v[132:135], v[216:219], v[36:39]
	v_mfma_f32_16x16x32_bf16 v[28:31], v[140:143], v[216:219], v[28:31]
	v_mfma_f32_16x16x32_bf16 v[120:123], v[136:139], v[176:179], v[120:123]
	v_mfma_f32_16x16x32_bf16 v[112:115], v[152:155], v[176:179], v[112:115]
	v_mfma_f32_16x16x32_bf16 v[100:103], v[136:139], v[184:187], v[100:103]
	v_mfma_f32_16x16x32_bf16 v[88:91], v[152:155], v[184:187], v[88:91]
	v_mfma_f32_16x16x32_bf16 v[68:71], v[136:139], v[212:215], v[68:71]
	v_mfma_f32_16x16x32_bf16 v[56:59], v[152:155], v[212:215], v[56:59]
	v_mfma_f32_16x16x32_bf16 v[36:39], v[136:139], v[228:231], v[36:39]
	v_mfma_f32_16x16x32_bf16 v[28:31], v[152:155], v[228:231], v[28:31]
	v_mfma_f32_16x16x32_bf16 v[128:131], v[156:159], v[172:175], v[128:131]
	v_mfma_f32_16x16x32_bf16 v[124:127], v[164:167], v[172:175], v[124:127]
	v_mfma_f32_16x16x32_bf16 v[116:119], v[156:159], v[180:183], v[116:119]
	v_mfma_f32_16x16x32_bf16 v[108:111], v[164:167], v[180:183], v[108:111]
	v_mfma_f32_16x16x32_bf16 v[92:95], v[156:159], v[188:191], v[92:95]
	v_mfma_f32_16x16x32_bf16 v[80:83], v[164:167], v[188:191], v[80:83]
	v_mfma_f32_16x16x32_bf16 v[64:67], v[156:159], v[216:219], v[64:67]
	v_mfma_f32_16x16x32_bf16 v[48:51], v[164:167], v[216:219], v[48:51]
	v_mfma_f32_16x16x32_bf16 v[128:131], v[160:163], v[176:179], v[128:131]
	v_mfma_f32_16x16x32_bf16 v[124:127], v[168:171], v[176:179], v[124:127]
	v_mfma_f32_16x16x32_bf16 v[116:119], v[160:163], v[184:187], v[116:119]
	v_mfma_f32_16x16x32_bf16 v[108:111], v[168:171], v[184:187], v[108:111]
	v_mfma_f32_16x16x32_bf16 v[92:95], v[160:163], v[212:215], v[92:95]
	v_mfma_f32_16x16x32_bf16 v[80:83], v[168:171], v[212:215], v[80:83]
	v_mfma_f32_16x16x32_bf16 v[64:67], v[160:163], v[228:231], v[64:67]
	v_mfma_f32_16x16x32_bf16 v[48:51], v[168:171], v[228:231], v[48:51]
	s_setprio 0
	s_barrier
	s_mov_b32 m0, s92
	ds_read_b128 v[172:175], v149 offset:16384
	ds_read_b128 v[176:179], v149 offset:17408
	ds_read_b128 v[180:183], v149 offset:18432
	ds_read_b128 v[184:187], v149 offset:19456
	ds_read_b128 v[188:191], v149 offset:20480
	ds_read_b128 v[212:215], v149 offset:21504
	ds_read_b128 v[216:219], v149 offset:22528
	ds_read_b128 v[228:231], v149 offset:23552
	buffer_load_dwordx4 v145, s[12:15], s58 offen lds
	s_mov_b32 m0, s93
	s_add_i32 s61, s58, 0x40000
	buffer_load_dwordx4 v147, s[12:15], s58 offen lds
	s_mov_b32 m0, s94
	s_nop 0
	buffer_load_dwordx4 v145, s[12:15], s61 offen lds
	s_mov_b32 m0, s95
	s_nop 0
	buffer_load_dwordx4 v147, s[12:15], s61 offen lds
	s_mov_b32 m0, s44
	s_nop 0
	buffer_load_dwordx4 v144, s[16:19], s60 offen lds
	s_mov_b32 m0, s36
	s_nop 0
	buffer_load_dwordx4 v146, s[16:19], s60 offen lds
	s_waitcnt vmcnt(8)
	s_waitcnt lgkmcnt(0)
	s_setprio 1
	s_barrier
	v_mfma_f32_16x16x32_bf16 v[72:75], v[132:135], v[172:175], v[72:75]
	v_mfma_f32_16x16x32_bf16 v[60:63], v[140:143], v[172:175], v[60:63]
	v_mfma_f32_16x16x32_bf16 v[40:43], v[132:135], v[180:183], v[40:43]
	v_mfma_f32_16x16x32_bf16 v[32:35], v[140:143], v[180:183], v[32:35]
	v_mfma_f32_16x16x32_bf16 v[16:19], v[132:135], v[188:191], v[16:19]
	v_mfma_f32_16x16x32_bf16 v[12:15], v[140:143], v[188:191], v[12:15]
	v_mfma_f32_16x16x32_bf16 v[8:11], v[132:135], v[216:219], v[8:11]
	v_mfma_f32_16x16x32_bf16 v[2:5], v[140:143], v[216:219], v[4:7]
	v_mfma_f32_16x16x32_bf16 v[72:75], v[136:139], v[176:179], v[72:75]
	v_mfma_f32_16x16x32_bf16 v[60:63], v[152:155], v[176:179], v[60:63]
	v_mfma_f32_16x16x32_bf16 v[40:43], v[136:139], v[184:187], v[40:43]
	v_mfma_f32_16x16x32_bf16 v[32:35], v[152:155], v[184:187], v[32:35]
	v_mfma_f32_16x16x32_bf16 v[16:19], v[136:139], v[212:215], v[16:19]
	v_mfma_f32_16x16x32_bf16 v[12:15], v[152:155], v[212:215], v[12:15]
	v_mfma_f32_16x16x32_bf16 v[8:11], v[136:139], v[228:231], v[8:11]
	v_mfma_f32_16x16x32_bf16 v[2:5], v[152:155], v[228:231], v[2:5]
	v_mfma_f32_16x16x32_bf16 v[96:99], v[156:159], v[172:175], v[96:99]
	v_mfma_f32_16x16x32_bf16 v[104:107], v[164:167], v[172:175], v[104:107]
	v_mfma_f32_16x16x32_bf16 v[84:87], v[156:159], v[180:183], v[84:87]
	v_mfma_f32_16x16x32_bf16 v[76:79], v[164:167], v[180:183], v[76:79]
	v_mfma_f32_16x16x32_bf16 v[52:55], v[156:159], v[188:191], v[52:55]
	v_mfma_f32_16x16x32_bf16 v[44:47], v[164:167], v[188:191], v[44:47]
	v_mfma_f32_16x16x32_bf16 v[24:27], v[156:159], v[216:219], v[24:27]
	v_mfma_f32_16x16x32_bf16 v[20:23], v[164:167], v[216:219], v[20:23]
	v_mfma_f32_16x16x32_bf16 v[96:99], v[160:163], v[176:179], v[96:99]
	v_mfma_f32_16x16x32_bf16 v[104:107], v[168:171], v[176:179], v[104:107]
	v_mfma_f32_16x16x32_bf16 v[84:87], v[160:163], v[184:187], v[84:87]
	v_mfma_f32_16x16x32_bf16 v[76:79], v[168:171], v[184:187], v[76:79]
	v_mfma_f32_16x16x32_bf16 v[52:55], v[160:163], v[212:215], v[52:55]
	v_mfma_f32_16x16x32_bf16 v[44:47], v[168:171], v[212:215], v[44:47]
	v_mfma_f32_16x16x32_bf16 v[24:27], v[160:163], v[228:231], v[24:27]
	v_mfma_f32_16x16x32_bf16 v[20:23], v[168:171], v[228:231], v[20:23]
	s_setprio 0
	s_barrier
; #define PG8_WAIT_V(n) asm volatile("s_waitcnt vmcnt(" #n ")" ::: "memory")
; template <class Epi, bool ALIGN_EPI, bool SP2, class Hook>
; __device__ __forceinline__ void gemm_phase(LAS unsigned char* lds, const Gemm g, const StaticOrder& S, const Epi& E, Acc& acc, const bool fresh, const Hook& H, const int wave_id) {
;     ...
;         for (int t = t0; t < nt; t += 2) {
;             const bool last = (t == nt - 2);
;             const Src a1 = cA + (size_t)(t + 1) * kstep;
;             const Src a2 = last ? nA : cA + (size_t)(t + 2) * kstep, b2 = last ? nB : cB + (size_t)(t + 2) * kstep;
;             const Src a3 = a2 + kstep, b3 = b2 + kstep;
;             if (last && has_next) H(nxt);
;             if constexpr (SP2) {
;             PG8_TRIP_SP2(PG8_WAIT_V(8));
	v_add_u32_e32 v152, 0x18000, v148
	v_add_u32_e32 v153, 0x1c000, v148
	ds_read_b128 v[132:135], v152
	ds_read_b128 v[136:139], v152 offset:1024
	ds_read_b128 v[140:143], v152 offset:2048
	ds_read_b128 v[154:157], v152 offset:3072
	ds_read_b128 v[158:161], v153
	ds_read_b128 v[162:165], v153 offset:1024
	ds_read_b128 v[166:169], v153 offset:2048
	ds_read_b128 v[170:173], v153 offset:3072
	s_add_i32 s60, s60, 0x40000
	s_mov_b32 m0, s37
	ds_read_b128 v[174:177], v149 offset:32768
	ds_read_b128 v[178:181], v149 offset:33792
	ds_read_b128 v[182:185], v149 offset:34816
	ds_read_b128 v[186:189], v149 offset:35840
	ds_read_b128 v[190:193], v149 offset:36864
	ds_read_b128 v[212:215], v149 offset:37888
	ds_read_b128 v[216:219], v149 offset:38912
	ds_read_b128 v[228:231], v149 offset:39936
	buffer_load_dwordx4 v144, s[16:19], s60 offen lds
	s_mov_b32 m0, s38
	s_nop 0
	buffer_load_dwordx4 v146, s[16:19], s60 offen lds
	s_waitcnt vmcnt(8)
	s_waitcnt lgkmcnt(0)
	s_setprio 1
	s_barrier
	v_mfma_f32_16x16x32_bf16 v[120:123], v[132:135], v[174:177], v[120:123]
	v_mfma_f32_16x16x32_bf16 v[112:115], v[140:143], v[174:177], v[112:115]
	v_mfma_f32_16x16x32_bf16 v[100:103], v[132:135], v[182:185], v[100:103]
	v_mfma_f32_16x16x32_bf16 v[88:91], v[140:143], v[182:185], v[88:91]
	v_mfma_f32_16x16x32_bf16 v[68:71], v[132:135], v[190:193], v[68:71]
	v_mfma_f32_16x16x32_bf16 v[56:59], v[140:143], v[190:193], v[56:59]
	v_mfma_f32_16x16x32_bf16 v[36:39], v[132:135], v[216:219], v[36:39]
	v_mfma_f32_16x16x32_bf16 v[28:31], v[140:143], v[216:219], v[28:31]
	v_mfma_f32_16x16x32_bf16 v[120:123], v[136:139], v[178:181], v[120:123]
	v_mfma_f32_16x16x32_bf16 v[112:115], v[154:157], v[178:181], v[112:115]
	v_mfma_f32_16x16x32_bf16 v[100:103], v[136:139], v[186:189], v[100:103]
	v_mfma_f32_16x16x32_bf16 v[88:91], v[154:157], v[186:189], v[88:91]
	v_mfma_f32_16x16x32_bf16 v[68:71], v[136:139], v[212:215], v[68:71]
	v_mfma_f32_16x16x32_bf16 v[56:59], v[154:157], v[212:215], v[56:59]
	v_mfma_f32_16x16x32_bf16 v[36:39], v[136:139], v[228:231], v[36:39]
	v_mfma_f32_16x16x32_bf16 v[28:31], v[154:157], v[228:231], v[28:31]
	v_mfma_f32_16x16x32_bf16 v[128:131], v[158:161], v[174:177], v[128:131]
	v_mfma_f32_16x16x32_bf16 v[124:127], v[166:169], v[174:177], v[124:127]
	v_mfma_f32_16x16x32_bf16 v[116:119], v[158:161], v[182:185], v[116:119]
	v_mfma_f32_16x16x32_bf16 v[108:111], v[166:169], v[182:185], v[108:111]
	v_mfma_f32_16x16x32_bf16 v[92:95], v[158:161], v[190:193], v[92:95]
	v_mfma_f32_16x16x32_bf16 v[80:83], v[166:169], v[190:193], v[80:83]
	v_mfma_f32_16x16x32_bf16 v[64:67], v[158:161], v[216:219], v[64:67]
	v_mfma_f32_16x16x32_bf16 v[48:51], v[166:169], v[216:219], v[48:51]
	v_mfma_f32_16x16x32_bf16 v[128:131], v[162:165], v[178:181], v[128:131]
	v_mfma_f32_16x16x32_bf16 v[124:127], v[170:173], v[178:181], v[124:127]
	v_mfma_f32_16x16x32_bf16 v[116:119], v[162:165], v[186:189], v[116:119]
	v_mfma_f32_16x16x32_bf16 v[108:111], v[170:173], v[186:189], v[108:111]
	v_mfma_f32_16x16x32_bf16 v[92:95], v[162:165], v[212:215], v[92:95]
	v_mfma_f32_16x16x32_bf16 v[80:83], v[170:173], v[212:215], v[80:83]
	v_mfma_f32_16x16x32_bf16 v[64:67], v[162:165], v[228:231], v[64:67]
	v_mfma_f32_16x16x32_bf16 v[48:51], v[170:173], v[228:231], v[48:51]
	s_setprio 0
	s_barrier
	s_mov_b32 m0, s39
	s_or_b32 s60, s58, 0x80
	ds_read_b128 v[174:177], v149 offset:49152
	ds_read_b128 v[178:181], v149 offset:50176
	ds_read_b128 v[182:185], v149 offset:51200
	ds_read_b128 v[186:189], v149 offset:52224
	ds_read_b128 v[190:193], v149 offset:53248
	ds_read_b128 v[212:215], v149 offset:54272
	ds_read_b128 v[216:219], v149 offset:55296
	ds_read_b128 v[228:231], v149 offset:56320
	buffer_load_dwordx4 v145, s[12:15], s60 offen lds
	s_mov_b32 m0, s40
	s_add_i32 s58, s58, 0x40080
	buffer_load_dwordx4 v147, s[12:15], s60 offen lds
	s_mov_b32 m0, s43
	s_nop 0
	buffer_load_dwordx4 v145, s[12:15], s58 offen lds
	s_mov_b32 m0, s42
	s_nop 0
	buffer_load_dwordx4 v147, s[12:15], s58 offen lds
	s_mov_b32 m0, s41
	s_nop 0
	buffer_load_dwordx4 v144, s[16:19], s59 offen lds
	s_mov_b32 m0, s33
	s_nop 0
	buffer_load_dwordx4 v146, s[16:19], s59 offen lds
	s_waitcnt vmcnt(8)
	s_waitcnt lgkmcnt(0)
	s_setprio 1
	s_barrier
	v_mfma_f32_16x16x32_bf16 v[72:75], v[132:135], v[174:177], v[72:75]
	v_mfma_f32_16x16x32_bf16 v[60:63], v[140:143], v[174:177], v[60:63]
	v_mfma_f32_16x16x32_bf16 v[40:43], v[132:135], v[182:185], v[40:43]
	v_mfma_f32_16x16x32_bf16 v[32:35], v[140:143], v[182:185], v[32:35]
	v_mfma_f32_16x16x32_bf16 v[16:19], v[132:135], v[190:193], v[16:19]
	v_mfma_f32_16x16x32_bf16 v[12:15], v[140:143], v[190:193], v[12:15]
	v_mfma_f32_16x16x32_bf16 v[6:9], v[132:135], v[216:219], v[8:11]
	v_mfma_f32_16x16x32_bf16 v[2:5], v[140:143], v[216:219], v[2:5]
	v_mfma_f32_16x16x32_bf16 v[72:75], v[136:139], v[178:181], v[72:75]
	v_mfma_f32_16x16x32_bf16 v[60:63], v[154:157], v[178:181], v[60:63]
	v_mfma_f32_16x16x32_bf16 v[40:43], v[136:139], v[186:189], v[40:43]
	v_mfma_f32_16x16x32_bf16 v[32:35], v[154:157], v[186:189], v[32:35]
	v_mfma_f32_16x16x32_bf16 v[16:19], v[136:139], v[212:215], v[16:19]
	v_mfma_f32_16x16x32_bf16 v[12:15], v[154:157], v[212:215], v[12:15]
	v_mfma_f32_16x16x32_bf16 v[8:11], v[136:139], v[228:231], v[6:9]
	v_mfma_f32_16x16x32_bf16 v[4:7], v[154:157], v[228:231], v[2:5]
	v_mfma_f32_16x16x32_bf16 v[96:99], v[158:161], v[174:177], v[96:99]
	v_mfma_f32_16x16x32_bf16 v[104:107], v[166:169], v[174:177], v[104:107]
	v_mfma_f32_16x16x32_bf16 v[84:87], v[158:161], v[182:185], v[84:87]
	v_mfma_f32_16x16x32_bf16 v[76:79], v[166:169], v[182:185], v[76:79]
	v_mfma_f32_16x16x32_bf16 v[52:55], v[158:161], v[190:193], v[52:55]
	v_mfma_f32_16x16x32_bf16 v[44:47], v[166:169], v[190:193], v[44:47]
	v_mfma_f32_16x16x32_bf16 v[24:27], v[158:161], v[216:219], v[24:27]
	v_mfma_f32_16x16x32_bf16 v[20:23], v[166:169], v[216:219], v[20:23]
	v_mfma_f32_16x16x32_bf16 v[96:99], v[162:165], v[178:181], v[96:99]
	v_mfma_f32_16x16x32_bf16 v[104:107], v[170:173], v[178:181], v[104:107]
	v_mfma_f32_16x16x32_bf16 v[84:87], v[162:165], v[186:189], v[84:87]
	v_mfma_f32_16x16x32_bf16 v[76:79], v[170:173], v[186:189], v[76:79]
	v_mfma_f32_16x16x32_bf16 v[52:55], v[162:165], v[212:215], v[52:55]
	v_mfma_f32_16x16x32_bf16 v[44:47], v[170:173], v[212:215], v[44:47]
	v_mfma_f32_16x16x32_bf16 v[24:27], v[162:165], v[228:231], v[24:27]
	v_mfma_f32_16x16x32_bf16 v[20:23], v[170:173], v[228:231], v[20:23]
	s_setprio 0
	s_barrier
	s_add_i32 s29, s29, 2
	s_addk_i32 s56, 0x100
	s_addk_i32 s57, 0x100
	s_cmp_gt_u32 s29, 13
	s_cbranch_scc0 .LBB0_391
	v_readlane_b32 s8, v251, 45
	v_readlane_b32 s9, v251, 46
	s_and_b64 vcc, exec, s[8:9]
	s_cbranch_vccz .LBB0_394
	s_barrier

; #define PG8_WAIT_V(n) asm volatile("s_waitcnt vmcnt(" #n ")" ::: "memory")
; template <class Epi, bool ALIGN_EPI, bool SP2, class Hook>
; __device__ __forceinline__ void gemm_phase(LAS unsigned char* lds, const Gemm g, const StaticOrder& S, const Epi& E, Acc& acc, const bool fresh, const Hook& H, const int wave_id) {
;     ...
;         for (int t = t0; t < nt; t += 2) {
;             const bool last = (t == nt - 2);
;             const Src a1 = cA + (size_t)(t + 1) * kstep;
;             const Src a2 = last ? nA : cA + (size_t)(t + 2) * kstep, b2 = last ? nB : cB + (size_t)(t + 2) * kstep;
;             const Src a3 = a2 + kstep, b3 = b2 + kstep;
;             if (last && has_next) H(nxt);
;             if constexpr (SP2) {
;             PG8_TRIP_SP2(PG8_WAIT_V(8));
.LBB0_702:
	v_add_u32_e32 v70, 0x10000, v216
	v_add_u32_e32 v118, 0x14000, v216
	ds_read_b128 v[34:37], v70
	ds_read_b128 v[46:49], v70 offset:1024
	ds_read_b128 v[58:61], v70 offset:2048
	ds_read_b128 v[70:73], v70 offset:3072
	ds_read_b128 v[82:85], v118
	ds_read_b128 v[94:97], v118 offset:1024
	ds_read_b128 v[106:109], v118 offset:2048
	ds_read_b128 v[118:121], v118 offset:3072
	s_add_i32 s12, s55, 0xfffe0080
	s_cmp_eq_u32 s57, 4
	s_cselect_b32 s60, s53, s12
	s_cselect_b32 s13, s29, s77
	s_cselect_b32 s12, s28, s76
	s_cselect_b32 s15, s31, s35
	s_cselect_b32 s14, s30, s34
	s_cselect_b32 s58, s54, s56
	s_cselect_b32 s16, s2, s8
	s_cselect_b32 s17, s3, s9
	s_cselect_b32 s18, s26, s10
	s_cselect_b32 s19, s27, s11
	s_or_b32 s59, s60, 0x80
	s_mov_b32 m0, s45
	s_waitcnt vmcnt(14)
	ds_read_b128 v[130:133], v217
	ds_read_b128 v[142:145], v217 offset:1024
	ds_read_b128 v[154:157], v217 offset:2048
	ds_read_b128 v[166:169], v217 offset:3072
	ds_read_b128 v[174:177], v217 offset:4096
	ds_read_b128 v[182:185], v217 offset:5120
	ds_read_b128 v[186:189], v217 offset:6144
	ds_read_b128 v[190:193], v217 offset:7168
	buffer_load_dwordx4 v0, s[8:11], s55 offen lds
	s_mov_b32 m0, s46
	s_nop 0
	buffer_load_dwordx4 v214, s[8:11], s55 offen lds
	s_waitcnt vmcnt(8)
	s_waitcnt lgkmcnt(0)
	s_setprio 1
	s_barrier
	v_mfma_f32_16x16x32_bf16 v[178:181], v[34:37], v[130:133], v[178:181]
	v_mfma_f32_16x16x32_bf16 v[170:173], v[58:61], v[130:133], v[170:173]
	v_mfma_f32_16x16x32_bf16 v[150:153], v[34:37], v[154:157], v[150:153]
	v_mfma_f32_16x16x32_bf16 v[146:149], v[58:61], v[154:157], v[146:149]
	v_mfma_f32_16x16x32_bf16 v[126:129], v[34:37], v[174:177], v[126:129]
	v_mfma_f32_16x16x32_bf16 v[122:125], v[58:61], v[174:177], v[122:125]
	v_mfma_f32_16x16x32_bf16 v[102:105], v[34:37], v[186:189], v[102:105]
	v_mfma_f32_16x16x32_bf16 v[98:101], v[58:61], v[186:189], v[98:101]
	v_mfma_f32_16x16x32_bf16 v[178:181], v[46:49], v[142:145], v[178:181]
	v_mfma_f32_16x16x32_bf16 v[170:173], v[70:73], v[142:145], v[170:173]
	v_mfma_f32_16x16x32_bf16 v[150:153], v[46:49], v[166:169], v[150:153]
	v_mfma_f32_16x16x32_bf16 v[146:149], v[70:73], v[166:169], v[146:149]
	v_mfma_f32_16x16x32_bf16 v[126:129], v[46:49], v[182:185], v[126:129]
	v_mfma_f32_16x16x32_bf16 v[122:125], v[70:73], v[182:185], v[122:125]
	v_mfma_f32_16x16x32_bf16 v[102:105], v[46:49], v[190:193], v[102:105]
	v_mfma_f32_16x16x32_bf16 v[98:101], v[70:73], v[190:193], v[98:101]
	v_mfma_f32_16x16x32_bf16 v[162:165], v[82:85], v[130:133], v[162:165]
	v_mfma_f32_16x16x32_bf16 v[138:141], v[82:85], v[154:157], v[138:141]
	v_mfma_f32_16x16x32_bf16 v[134:137], v[106:109], v[154:157], v[134:137]
	v_mfma_f32_16x16x32_bf16 v[114:117], v[82:85], v[174:177], v[114:117]
	v_mfma_f32_16x16x32_bf16 v[110:113], v[106:109], v[174:177], v[110:113]
	v_mfma_f32_16x16x32_bf16 v[90:93], v[82:85], v[186:189], v[90:93]
	v_mfma_f32_16x16x32_bf16 v[86:89], v[106:109], v[186:189], v[86:89]
	v_mfma_f32_16x16x32_bf16 v[162:165], v[94:97], v[142:145], v[162:165]
	v_mfma_f32_16x16x32_bf16 v[130:133], v[106:109], v[130:133], v[158:161]
	v_mfma_f32_16x16x32_bf16 v[138:141], v[94:97], v[166:169], v[138:141]
	v_mfma_f32_16x16x32_bf16 v[134:137], v[118:121], v[166:169], v[134:137]
	v_mfma_f32_16x16x32_bf16 v[114:117], v[94:97], v[182:185], v[114:117]
	v_mfma_f32_16x16x32_bf16 v[110:113], v[118:121], v[182:185], v[110:113]
	v_mfma_f32_16x16x32_bf16 v[90:93], v[94:97], v[190:193], v[90:93]
	v_mfma_f32_16x16x32_bf16 v[86:89], v[118:121], v[190:193], v[86:89]
	v_mfma_f32_16x16x32_bf16 v[130:133], v[118:121], v[142:145], v[130:133]
	s_setprio 0
	s_barrier
	s_mov_b32 m0, s92
	ds_read_b128 v[142:145], v217 offset:16384
	ds_read_b128 v[154:157], v217 offset:17408
	ds_read_b128 v[158:161], v217 offset:18432
	ds_read_b128 v[166:169], v217 offset:19456
	ds_read_b128 v[174:177], v217 offset:20480
	ds_read_b128 v[182:185], v217 offset:21504
	ds_read_b128 v[186:189], v217 offset:22528
	ds_read_b128 v[190:193], v217 offset:23552
	buffer_load_dwordx4 v199, s[12:15], s58 offen lds
	s_mov_b32 m0, s93
	s_add_i32 s61, s58, 0x20000
	buffer_load_dwordx4 v215, s[12:15], s58 offen lds
	s_mov_b32 m0, s94
	s_nop 0
	buffer_load_dwordx4 v199, s[12:15], s61 offen lds
	s_mov_b32 m0, s95
	s_nop 0
	buffer_load_dwordx4 v215, s[12:15], s61 offen lds
	s_mov_b32 m0, s44
	s_nop 0
	buffer_load_dwordx4 v0, s[16:19], s60 offen lds
	s_mov_b32 m0, s36
	s_nop 0
	buffer_load_dwordx4 v214, s[16:19], s60 offen lds
	s_waitcnt vmcnt(8)
	s_waitcnt lgkmcnt(0)
	s_setprio 1
	s_barrier
	v_mfma_f32_16x16x32_bf16 v[78:81], v[34:37], v[142:145], v[78:81]
	v_mfma_f32_16x16x32_bf16 v[74:77], v[58:61], v[142:145], v[74:77]
	v_mfma_f32_16x16x32_bf16 v[54:57], v[34:37], v[158:161], v[54:57]
	v_mfma_f32_16x16x32_bf16 v[50:53], v[58:61], v[158:161], v[50:53]
	v_mfma_f32_16x16x32_bf16 v[30:33], v[34:37], v[174:177], v[30:33]
	v_mfma_f32_16x16x32_bf16 v[26:29], v[58:61], v[174:177], v[26:29]
	v_mfma_f32_16x16x32_bf16 v[14:17], v[34:37], v[186:189], v[14:17]
	v_mfma_f32_16x16x32_bf16 v[10:13], v[58:61], v[186:189], v[10:13]
	v_mfma_f32_16x16x32_bf16 v[78:81], v[46:49], v[154:157], v[78:81]
	v_mfma_f32_16x16x32_bf16 v[74:77], v[70:73], v[154:157], v[74:77]
	v_mfma_f32_16x16x32_bf16 v[54:57], v[46:49], v[166:169], v[54:57]
	v_mfma_f32_16x16x32_bf16 v[50:53], v[70:73], v[166:169], v[50:53]
	v_mfma_f32_16x16x32_bf16 v[30:33], v[46:49], v[182:185], v[30:33]
	v_mfma_f32_16x16x32_bf16 v[26:29], v[70:73], v[182:185], v[26:29]
	v_mfma_f32_16x16x32_bf16 v[14:17], v[46:49], v[190:193], v[14:17]
	v_mfma_f32_16x16x32_bf16 v[10:13], v[70:73], v[190:193], v[10:13]
	v_mfma_f32_16x16x32_bf16 v[42:45], v[82:85], v[158:161], v[42:45]
	v_mfma_f32_16x16x32_bf16 v[38:41], v[106:109], v[158:161], v[38:41]
	v_mfma_f32_16x16x32_bf16 v[22:25], v[82:85], v[174:177], v[22:25]
	v_mfma_f32_16x16x32_bf16 v[18:21], v[106:109], v[174:177], v[18:21]
	v_mfma_f32_16x16x32_bf16 v[6:9], v[82:85], v[186:189], v[6:9]
	v_mfma_f32_16x16x32_bf16 v[2:5], v[106:109], v[186:189], v[2:5]
	v_mfma_f32_16x16x32_bf16 v[34:37], v[82:85], v[142:145], v[66:69]
	v_mfma_f32_16x16x32_bf16 v[46:49], v[106:109], v[142:145], v[62:65]
	v_mfma_f32_16x16x32_bf16 v[42:45], v[94:97], v[166:169], v[42:45]
	v_mfma_f32_16x16x32_bf16 v[38:41], v[118:121], v[166:169], v[38:41]
	v_mfma_f32_16x16x32_bf16 v[22:25], v[94:97], v[182:185], v[22:25]
	v_mfma_f32_16x16x32_bf16 v[18:21], v[118:121], v[182:185], v[18:21]
	v_mfma_f32_16x16x32_bf16 v[6:9], v[94:97], v[190:193], v[6:9]
	v_mfma_f32_16x16x32_bf16 v[2:5], v[118:121], v[190:193], v[2:5]
	v_mfma_f32_16x16x32_bf16 v[34:37], v[94:97], v[154:157], v[34:37]
	v_mfma_f32_16x16x32_bf16 v[46:49], v[118:121], v[154:157], v[46:49]
	s_setprio 0
	s_barrier
; #define PG8_WAIT_V(n) asm volatile("s_waitcnt vmcnt(" #n ")" ::: "memory")
; template <class Epi, bool ALIGN_EPI, bool SP2, class Hook>
; __device__ __forceinline__ void gemm_phase(LAS unsigned char* lds, const Gemm g, const StaticOrder& S, const Epi& E, Acc& acc, const bool fresh, const Hook& H, const int wave_id) {
;     ...
;         for (int t = t0; t < nt; t += 2) {
;             const bool last = (t == nt - 2);
;             const Src a1 = cA + (size_t)(t + 1) * kstep;
;             const Src a2 = last ? nA : cA + (size_t)(t + 2) * kstep, b2 = last ? nB : cB + (size_t)(t + 2) * kstep;
;             const Src a3 = a2 + kstep, b3 = b2 + kstep;
;             if (last && has_next) H(nxt);
;             if constexpr (SP2) {
;             PG8_TRIP_SP2(PG8_WAIT_V(8));
	v_add_u32_e32 v70, 0x18000, v216
	v_add_u32_e32 v118, 0x1c000, v216
	ds_read_b128 v[58:61], v70
	ds_read_b128 v[62:65], v70 offset:1024
	ds_read_b128 v[66:69], v70 offset:2048
	ds_read_b128 v[70:73], v70 offset:3072
	ds_read_b128 v[82:85], v118
	ds_read_b128 v[94:97], v118 offset:1024
	ds_read_b128 v[106:109], v118 offset:2048
	ds_read_b128 v[118:121], v118 offset:3072
	s_add_i32 s60, s60, 0x20000
	s_mov_b32 m0, s37
	ds_read_b128 v[142:145], v217 offset:32768
	ds_read_b128 v[154:157], v217 offset:33792
	ds_read_b128 v[166:169], v217 offset:34816
	ds_read_b128 v[174:177], v217 offset:35840
	ds_read_b128 v[182:185], v217 offset:36864
	ds_read_b128 v[186:189], v217 offset:37888
	ds_read_b128 v[190:193], v217 offset:38912
	ds_read_b128 v[194:197], v217 offset:39936
	buffer_load_dwordx4 v0, s[16:19], s60 offen lds
	s_mov_b32 m0, s38
	s_nop 0
	buffer_load_dwordx4 v214, s[16:19], s60 offen lds
	s_waitcnt vmcnt(8)
	s_waitcnt lgkmcnt(0)
	s_setprio 1
	s_barrier
	v_mfma_f32_16x16x32_bf16 v[158:161], v[58:61], v[142:145], v[178:181]
	v_mfma_f32_16x16x32_bf16 v[178:181], v[62:65], v[154:157], v[158:161]
	v_mfma_f32_16x16x32_bf16 v[158:161], v[66:69], v[142:145], v[170:173]
	v_mfma_f32_16x16x32_bf16 v[150:153], v[58:61], v[166:169], v[150:153]
	v_mfma_f32_16x16x32_bf16 v[146:149], v[66:69], v[166:169], v[146:149]
	v_mfma_f32_16x16x32_bf16 v[126:129], v[58:61], v[182:185], v[126:129]
	v_mfma_f32_16x16x32_bf16 v[122:125], v[66:69], v[182:185], v[122:125]
	v_mfma_f32_16x16x32_bf16 v[102:105], v[58:61], v[190:193], v[102:105]
	v_mfma_f32_16x16x32_bf16 v[98:101], v[66:69], v[190:193], v[98:101]
	v_mfma_f32_16x16x32_bf16 v[170:173], v[70:73], v[154:157], v[158:161]
	v_mfma_f32_16x16x32_bf16 v[150:153], v[62:65], v[174:177], v[150:153]
	v_mfma_f32_16x16x32_bf16 v[146:149], v[70:73], v[174:177], v[146:149]
	v_mfma_f32_16x16x32_bf16 v[126:129], v[62:65], v[186:189], v[126:129]
	v_mfma_f32_16x16x32_bf16 v[122:125], v[70:73], v[186:189], v[122:125]
	v_mfma_f32_16x16x32_bf16 v[102:105], v[62:65], v[194:197], v[102:105]
	v_mfma_f32_16x16x32_bf16 v[98:101], v[70:73], v[194:197], v[98:101]
	v_mfma_f32_16x16x32_bf16 v[158:161], v[82:85], v[142:145], v[162:165]
	v_mfma_f32_16x16x32_bf16 v[130:133], v[106:109], v[142:145], v[130:133]
	v_mfma_f32_16x16x32_bf16 v[162:165], v[94:97], v[154:157], v[158:161]
	v_mfma_f32_16x16x32_bf16 v[158:161], v[118:121], v[154:157], v[130:133]
	v_mfma_f32_16x16x32_bf16 v[130:133], v[82:85], v[166:169], v[138:141]
	v_mfma_f32_16x16x32_bf16 v[138:141], v[94:97], v[174:177], v[130:133]
	v_mfma_f32_16x16x32_bf16 v[130:133], v[106:109], v[166:169], v[134:137]
	v_mfma_f32_16x16x32_bf16 v[114:117], v[82:85], v[182:185], v[114:117]
	v_mfma_f32_16x16x32_bf16 v[110:113], v[106:109], v[182:185], v[110:113]
	v_mfma_f32_16x16x32_bf16 v[90:93], v[82:85], v[190:193], v[90:93]
	v_mfma_f32_16x16x32_bf16 v[86:89], v[106:109], v[190:193], v[86:89]
	v_mfma_f32_16x16x32_bf16 v[134:137], v[118:121], v[174:177], v[130:133]
	v_mfma_f32_16x16x32_bf16 v[114:117], v[94:97], v[186:189], v[114:117]
	v_mfma_f32_16x16x32_bf16 v[110:113], v[118:121], v[186:189], v[110:113]
	v_mfma_f32_16x16x32_bf16 v[90:93], v[94:97], v[194:197], v[90:93]
	v_mfma_f32_16x16x32_bf16 v[86:89], v[118:121], v[194:197], v[86:89]
	s_setprio 0
	s_barrier
	s_mov_b32 m0, s39
	s_or_b32 s60, s58, 0x80
	ds_read_b128 v[130:133], v217 offset:49152
	ds_read_b128 v[142:145], v217 offset:50176
	ds_read_b128 v[154:157], v217 offset:51200
	ds_read_b128 v[166:169], v217 offset:52224
	ds_read_b128 v[174:177], v217 offset:53248
	ds_read_b128 v[182:185], v217 offset:54272
	ds_read_b128 v[186:189], v217 offset:55296
	ds_read_b128 v[190:193], v217 offset:56320
	buffer_load_dwordx4 v199, s[12:15], s60 offen lds
	s_mov_b32 m0, s40
	s_add_i32 s58, s58, 0x20080
	buffer_load_dwordx4 v215, s[12:15], s60 offen lds
	s_mov_b32 m0, s43
	s_nop 0
	buffer_load_dwordx4 v199, s[12:15], s58 offen lds
	s_mov_b32 m0, s42
	s_nop 0
	buffer_load_dwordx4 v215, s[12:15], s58 offen lds
	s_mov_b32 m0, s41
	s_nop 0
	buffer_load_dwordx4 v0, s[16:19], s59 offen lds
	s_mov_b32 m0, s33
	s_nop 0
	buffer_load_dwordx4 v214, s[16:19], s59 offen lds
	s_waitcnt vmcnt(8)
	s_waitcnt lgkmcnt(0)
	s_setprio 1
	s_barrier
	v_mfma_f32_16x16x32_bf16 v[78:81], v[58:61], v[130:133], v[78:81]
	v_mfma_f32_16x16x32_bf16 v[74:77], v[66:69], v[130:133], v[74:77]
	v_mfma_f32_16x16x32_bf16 v[54:57], v[58:61], v[154:157], v[54:57]
	v_mfma_f32_16x16x32_bf16 v[50:53], v[66:69], v[154:157], v[50:53]
	v_mfma_f32_16x16x32_bf16 v[30:33], v[58:61], v[174:177], v[30:33]
	v_mfma_f32_16x16x32_bf16 v[26:29], v[66:69], v[174:177], v[26:29]
	v_mfma_f32_16x16x32_bf16 v[14:17], v[58:61], v[186:189], v[14:17]
	v_mfma_f32_16x16x32_bf16 v[10:13], v[66:69], v[186:189], v[10:13]
	v_mfma_f32_16x16x32_bf16 v[78:81], v[62:65], v[142:145], v[78:81]
	v_mfma_f32_16x16x32_bf16 v[74:77], v[70:73], v[142:145], v[74:77]
	v_mfma_f32_16x16x32_bf16 v[54:57], v[62:65], v[166:169], v[54:57]
	v_mfma_f32_16x16x32_bf16 v[50:53], v[70:73], v[166:169], v[50:53]
	v_mfma_f32_16x16x32_bf16 v[30:33], v[62:65], v[182:185], v[30:33]
	v_mfma_f32_16x16x32_bf16 v[26:29], v[70:73], v[182:185], v[26:29]
	v_mfma_f32_16x16x32_bf16 v[14:17], v[62:65], v[190:193], v[14:17]
	v_mfma_f32_16x16x32_bf16 v[10:13], v[70:73], v[190:193], v[10:13]
	v_mfma_f32_16x16x32_bf16 v[34:37], v[82:85], v[130:133], v[34:37]
	v_mfma_f32_16x16x32_bf16 v[66:69], v[94:97], v[142:145], v[34:37]
	v_mfma_f32_16x16x32_bf16 v[34:37], v[106:109], v[130:133], v[46:49]
	v_mfma_f32_16x16x32_bf16 v[62:65], v[118:121], v[142:145], v[34:37]
	v_mfma_f32_16x16x32_bf16 v[34:37], v[82:85], v[154:157], v[42:45]
	v_mfma_f32_16x16x32_bf16 v[42:45], v[94:97], v[166:169], v[34:37]
	v_mfma_f32_16x16x32_bf16 v[34:37], v[106:109], v[154:157], v[38:41]
	v_mfma_f32_16x16x32_bf16 v[22:25], v[82:85], v[174:177], v[22:25]
	v_mfma_f32_16x16x32_bf16 v[18:21], v[106:109], v[174:177], v[18:21]
	v_mfma_f32_16x16x32_bf16 v[6:9], v[82:85], v[186:189], v[6:9]
	v_mfma_f32_16x16x32_bf16 v[2:5], v[106:109], v[186:189], v[2:5]
	v_mfma_f32_16x16x32_bf16 v[38:41], v[118:121], v[166:169], v[34:37]
	v_mfma_f32_16x16x32_bf16 v[22:25], v[94:97], v[182:185], v[22:25]
	v_mfma_f32_16x16x32_bf16 v[18:21], v[118:121], v[182:185], v[18:21]
	v_mfma_f32_16x16x32_bf16 v[6:9], v[94:97], v[190:193], v[6:9]
	v_mfma_f32_16x16x32_bf16 v[2:5], v[118:121], v[190:193], v[2:5]
	s_setprio 0
	s_barrier
	s_add_i32 s57, s57, 2
	s_addk_i32 s55, 0x100
	s_addk_i32 s56, 0x100
	s_cmp_gt_u32 s57, 5
	s_cbranch_scc0 .LBB0_702
	v_readlane_b32 s8, v251, 45
	v_readlane_b32 s9, v251, 46
	s_and_b64 vcc, exec, s[8:9]
	s_cbranch_vccz .LBB0_705
	s_barrier

; #define PG8_WAIT_V(n) asm volatile("s_waitcnt vmcnt(" #n ")" ::: "memory")
; template <class Epi, bool ALIGN_EPI, bool SP2, class Hook>
; __device__ __forceinline__ void gemm_phase(LAS unsigned char* lds, const Gemm g, const StaticOrder& S, const Epi& E, Acc& acc, const bool fresh, const Hook& H, const int wave_id) {
;     ...
;         for (int t = t0; t < nt; t += 2) {
;             const bool last = (t == nt - 2);
;             const Src a1 = cA + (size_t)(t + 1) * kstep;
;             const Src a2 = last ? nA : cA + (size_t)(t + 2) * kstep, b2 = last ? nB : cB + (size_t)(t + 2) * kstep;
;             const Src a3 = a2 + kstep, b3 = b2 + kstep;
;             if (last && has_next) H(nxt);
;             if constexpr (SP2) {
;             PG8_TRIP_SP2(PG8_WAIT_V(8));
.LBB0_779:
	v_add_u32_e32 v0, 0x10000, v230
	s_waitcnt vmcnt(0)
	ds_read_b128 v[130:133], v0
	ds_read_b128 v[134:137], v0 offset:1024
	ds_read_b128 v[138:141], v0 offset:2048
	ds_read_b128 v[142:145], v0 offset:3072
	v_add_u32_e32 v0, 0x14000, v230
	ds_read_b128 v[146:149], v0
	ds_read_b128 v[150:153], v0 offset:1024
	ds_read_b128 v[154:157], v0 offset:2048
	ds_read_b128 v[158:161], v0 offset:3072
	s_add_i32 s12, s2, 0xfffe0080
	s_cmp_eq_u32 s63, 4
	s_cselect_b32 s66, s60, s12
	s_cselect_b32 s13, s53, s77
	s_cselect_b32 s12, s52, s76
	s_cselect_b32 s15, s55, s7
	s_cselect_b32 s14, s54, s6
	s_cselect_b32 s64, s61, s3
	s_cselect_b32 s16, s34, s8
	s_cselect_b32 s17, s35, s9
	s_cselect_b32 s18, s50, s10
	s_cselect_b32 s19, s51, s11
	s_or_b32 s65, s66, 0x80
	s_mov_b32 m0, s45
	ds_read_b128 v[162:165], v231
	ds_read_b128 v[166:169], v231 offset:1024
	ds_read_b128 v[170:173], v231 offset:2048
	ds_read_b128 v[174:177], v231 offset:3072
	ds_read_b128 v[178:181], v231 offset:4096
	ds_read_b128 v[182:185], v231 offset:5120
	ds_read_b128 v[186:189], v231 offset:6144
	ds_read_b128 v[190:193], v231 offset:7168
	buffer_load_dwordx4 v199, s[8:11], s2 offen lds
	s_mov_b32 m0, s46
	s_nop 0
	buffer_load_dwordx4 v228, s[8:11], s2 offen lds
	s_waitcnt vmcnt(8)
	s_waitcnt lgkmcnt(0)
	s_setprio 1
	s_barrier
	v_mfma_f32_16x16x32_bf16 v[126:129], v[130:133], v[162:165], v[126:129]
	v_mfma_f32_16x16x32_bf16 v[122:125], v[138:141], v[162:165], v[122:125]
	v_mfma_f32_16x16x32_bf16 v[118:121], v[130:133], v[170:173], v[118:121]
	v_mfma_f32_16x16x32_bf16 v[114:117], v[138:141], v[170:173], v[114:117]
	v_mfma_f32_16x16x32_bf16 v[110:113], v[130:133], v[178:181], v[110:113]
	v_mfma_f32_16x16x32_bf16 v[106:109], v[138:141], v[178:181], v[106:109]
	v_mfma_f32_16x16x32_bf16 v[102:105], v[130:133], v[186:189], v[102:105]
	v_mfma_f32_16x16x32_bf16 v[98:101], v[138:141], v[186:189], v[98:101]
	v_mfma_f32_16x16x32_bf16 v[126:129], v[134:137], v[166:169], v[126:129]
	v_mfma_f32_16x16x32_bf16 v[122:125], v[142:145], v[166:169], v[122:125]
	v_mfma_f32_16x16x32_bf16 v[118:121], v[134:137], v[174:177], v[118:121]
	v_mfma_f32_16x16x32_bf16 v[114:117], v[142:145], v[174:177], v[114:117]
	v_mfma_f32_16x16x32_bf16 v[110:113], v[134:137], v[182:185], v[110:113]
	v_mfma_f32_16x16x32_bf16 v[106:109], v[142:145], v[182:185], v[106:109]
	v_mfma_f32_16x16x32_bf16 v[102:105], v[134:137], v[190:193], v[102:105]
	v_mfma_f32_16x16x32_bf16 v[98:101], v[142:145], v[190:193], v[98:101]
	v_mfma_f32_16x16x32_bf16 v[94:97], v[146:149], v[162:165], v[94:97]
	v_mfma_f32_16x16x32_bf16 v[90:93], v[154:157], v[162:165], v[90:93]
	v_mfma_f32_16x16x32_bf16 v[86:89], v[146:149], v[170:173], v[86:89]
	v_mfma_f32_16x16x32_bf16 v[82:85], v[154:157], v[170:173], v[82:85]
	v_mfma_f32_16x16x32_bf16 v[78:81], v[146:149], v[178:181], v[78:81]
	v_mfma_f32_16x16x32_bf16 v[74:77], v[154:157], v[178:181], v[74:77]
	v_mfma_f32_16x16x32_bf16 v[70:73], v[146:149], v[186:189], v[70:73]
	v_mfma_f32_16x16x32_bf16 v[66:69], v[154:157], v[186:189], v[66:69]
	v_mfma_f32_16x16x32_bf16 v[94:97], v[150:153], v[166:169], v[94:97]
	v_mfma_f32_16x16x32_bf16 v[90:93], v[158:161], v[166:169], v[90:93]
	v_mfma_f32_16x16x32_bf16 v[86:89], v[150:153], v[174:177], v[86:89]
	v_mfma_f32_16x16x32_bf16 v[82:85], v[158:161], v[174:177], v[82:85]
	v_mfma_f32_16x16x32_bf16 v[78:81], v[150:153], v[182:185], v[78:81]
	v_mfma_f32_16x16x32_bf16 v[74:77], v[158:161], v[182:185], v[74:77]
	v_mfma_f32_16x16x32_bf16 v[70:73], v[150:153], v[190:193], v[70:73]
	v_mfma_f32_16x16x32_bf16 v[66:69], v[158:161], v[190:193], v[66:69]
	s_setprio 0
	s_barrier
	s_mov_b32 m0, s92
	ds_read_b128 v[162:165], v231 offset:16384
	ds_read_b128 v[166:169], v231 offset:17408
	ds_read_b128 v[170:173], v231 offset:18432
	ds_read_b128 v[174:177], v231 offset:19456
	ds_read_b128 v[178:181], v231 offset:20480
	ds_read_b128 v[182:185], v231 offset:21504
	ds_read_b128 v[186:189], v231 offset:22528
	ds_read_b128 v[190:193], v231 offset:23552
	buffer_load_dwordx4 v227, s[12:15], s64 offen lds
	s_mov_b32 m0, s93
	s_add_i32 s67, s64, 0x20000
	buffer_load_dwordx4 v229, s[12:15], s64 offen lds
	s_mov_b32 m0, s94
	s_nop 0
	buffer_load_dwordx4 v227, s[12:15], s67 offen lds
	s_mov_b32 m0, s95
	s_nop 0
	buffer_load_dwordx4 v229, s[12:15], s67 offen lds
	s_mov_b32 m0, s44
	s_nop 0
	buffer_load_dwordx4 v199, s[16:19], s66 offen lds
	s_mov_b32 m0, s36
	s_nop 0
	buffer_load_dwordx4 v228, s[16:19], s66 offen lds
	s_waitcnt vmcnt(8)
	s_waitcnt lgkmcnt(0)
	s_setprio 1
	s_barrier
	v_mfma_f32_16x16x32_bf16 v[62:65], v[130:133], v[162:165], v[62:65]
	v_mfma_f32_16x16x32_bf16 v[58:61], v[138:141], v[162:165], v[58:61]
	v_mfma_f32_16x16x32_bf16 v[54:57], v[130:133], v[170:173], v[54:57]
	v_mfma_f32_16x16x32_bf16 v[50:53], v[138:141], v[170:173], v[50:53]
	v_mfma_f32_16x16x32_bf16 v[46:49], v[130:133], v[178:181], v[46:49]
	v_mfma_f32_16x16x32_bf16 v[42:45], v[138:141], v[178:181], v[42:45]
	v_mfma_f32_16x16x32_bf16 v[38:41], v[130:133], v[186:189], v[38:41]
	v_mfma_f32_16x16x32_bf16 v[34:37], v[138:141], v[186:189], v[34:37]
	v_mfma_f32_16x16x32_bf16 v[62:65], v[134:137], v[166:169], v[62:65]
	v_mfma_f32_16x16x32_bf16 v[58:61], v[142:145], v[166:169], v[58:61]
	v_mfma_f32_16x16x32_bf16 v[54:57], v[134:137], v[174:177], v[54:57]
	v_mfma_f32_16x16x32_bf16 v[50:53], v[142:145], v[174:177], v[50:53]
	v_mfma_f32_16x16x32_bf16 v[46:49], v[134:137], v[182:185], v[46:49]
	v_mfma_f32_16x16x32_bf16 v[42:45], v[142:145], v[182:185], v[42:45]
	v_mfma_f32_16x16x32_bf16 v[38:41], v[134:137], v[190:193], v[38:41]
	v_mfma_f32_16x16x32_bf16 v[34:37], v[142:145], v[190:193], v[34:37]
	v_mfma_f32_16x16x32_bf16 v[30:33], v[146:149], v[162:165], v[30:33]
	v_mfma_f32_16x16x32_bf16 v[26:29], v[154:157], v[162:165], v[26:29]
	v_mfma_f32_16x16x32_bf16 v[22:25], v[146:149], v[170:173], v[22:25]
	v_mfma_f32_16x16x32_bf16 v[18:21], v[154:157], v[170:173], v[18:21]
	v_mfma_f32_16x16x32_bf16 v[14:17], v[146:149], v[178:181], v[14:17]
	v_mfma_f32_16x16x32_bf16 v[10:13], v[154:157], v[178:181], v[10:13]
	v_mfma_f32_16x16x32_bf16 v[6:9], v[146:149], v[186:189], v[6:9]
	v_mfma_f32_16x16x32_bf16 v[2:5], v[154:157], v[186:189], v[2:5]
	v_mfma_f32_16x16x32_bf16 v[30:33], v[150:153], v[166:169], v[30:33]
	v_mfma_f32_16x16x32_bf16 v[26:29], v[158:161], v[166:169], v[26:29]
	v_mfma_f32_16x16x32_bf16 v[22:25], v[150:153], v[174:177], v[22:25]
	v_mfma_f32_16x16x32_bf16 v[18:21], v[158:161], v[174:177], v[18:21]
	v_mfma_f32_16x16x32_bf16 v[14:17], v[150:153], v[182:185], v[14:17]
	v_mfma_f32_16x16x32_bf16 v[10:13], v[158:161], v[182:185], v[10:13]
	v_mfma_f32_16x16x32_bf16 v[6:9], v[150:153], v[190:193], v[6:9]
	v_mfma_f32_16x16x32_bf16 v[2:5], v[158:161], v[190:193], v[2:5]
	s_setprio 0
	s_barrier
; #define PG8_STAGE(bufoff, gbase, voff) do { const Src _g = (gbase); _Pragma("unroll") for (int _i = 0; _i < 2; ++_i) \
;         __builtin_amdgcn_raw_ptr_buffer_load_lds(_g.r, (LAS unsigned*)(lds + (bufoff) + ldsw + _i * 8192), 16, (voff)[_i], _g.o, 0, 0); } while (0)
; #define PG8_WAIT_V(n) asm volatile("s_waitcnt vmcnt(" #n ")" ::: "memory")
; template <class Epi, bool ALIGN_EPI, bool SP2, class Hook>
; __device__ __forceinline__ void gemm_phase(LAS unsigned char* lds, const Gemm g, const StaticOrder& S, const Epi& E, Acc& acc, const bool fresh, const Hook& H, const int wave_id) {
;     ...
;         for (int t = t0; t < nt; t += 2) {
;             const bool last = (t == nt - 2);
;             const Src a1 = cA + (size_t)(t + 1) * kstep;
;             const Src a2 = last ? nA : cA + (size_t)(t + 2) * kstep, b2 = last ? nB : cB + (size_t)(t + 2) * kstep;
;             const Src a3 = a2 + kstep, b3 = b2 + kstep;
;             if (last && has_next) H(nxt);
;             if constexpr (SP2) {
;             PG8_TRIP_SP2(PG8_WAIT_V(8));
;             } else {
;             PG8_LDB(B0, 0, 0); PG8_SCHED; PG8_LDA(At, 0, 0); PG8_STAGE(PG8_SA(1, 1), a1 + hstepA, voffA);
;             PG8_WAIT_L(8); PG8_BAR; PG8_WAIT_L(0); PG8_MMA(0, 0, At, B0); PG8_BAR; PG8_SCHED;
;             PG8_LDB(B1, 0, 1); PG8_STAGE(PG8_SB(0, 0), b2, voffB);
;             PG8_BAR; PG8_WAIT_L(0); PG8_MMA(0, 1, At, B1); PG8_BAR;
;             PG8_LDA(At, 0, 1); PG8_STAGE(PG8_SA(0, 0), a2, voffA);
;             PG8_BAR; PG8_WAIT_L(0); PG8_MMA(1, 0, At, B0); PG8_BAR; PG8_SCHED;
;             PG8_STAGE(PG8_SB(0, 1), b2 + hstep, voffB);
;             PG8_WAIT_V(6); PG8_BAR; PG8_MMA(1, 1, At, B1); PG8_BAR;
;             PG8_LDB(B0, 1, 0); PG8_SCHED; PG8_LDA(At, 1, 0); PG8_STAGE(PG8_SA(0, 1), a2 + hstepA, voffA);
;             PG8_WAIT_L(8); PG8_BAR; PG8_WAIT_L(0); PG8_MMA(0, 0, At, B0); PG8_BAR; PG8_SCHED;
;             PG8_LDB(B1, 1, 1); PG8_STAGE(PG8_SB(1, 0), b3, voffB);
;             PG8_BAR; PG8_WAIT_L(0); PG8_MMA(0, 1, At, B1); PG8_BAR;
;             PG8_LDA(At, 1, 1); PG8_STAGE(PG8_SA(1, 0), a3, voffA);
;             PG8_BAR; PG8_WAIT_L(0); PG8_MMA(1, 0, At, B0); PG8_BAR; PG8_SCHED;
;             PG8_STAGE(PG8_SB(1, 1), b3 + hstep, voffB);
;             PG8_WAIT_V(6); PG8_BAR; PG8_MMA(1, 1, At, B1); PG8_BAR;
;             }
;         }
;         if constexpr (ALIGN_EPI) { if (wr == 0) PG8_BAR; }
	v_add_u32_e32 v0, 0x18000, v230
	ds_read_b128 v[130:133], v0
	ds_read_b128 v[134:137], v0 offset:1024
	ds_read_b128 v[138:141], v0 offset:2048
	ds_read_b128 v[142:145], v0 offset:3072
	v_add_u32_e32 v0, 0x1c000, v230
	ds_read_b128 v[146:149], v0
	ds_read_b128 v[150:153], v0 offset:1024
	ds_read_b128 v[154:157], v0 offset:2048
	ds_read_b128 v[158:161], v0 offset:3072
	s_add_i32 s66, s66, 0x20000
	s_mov_b32 m0, s37
	ds_read_b128 v[162:165], v231 offset:32768
	ds_read_b128 v[166:169], v231 offset:33792
	ds_read_b128 v[170:173], v231 offset:34816
	ds_read_b128 v[174:177], v231 offset:35840
	ds_read_b128 v[178:181], v231 offset:36864
	ds_read_b128 v[182:185], v231 offset:37888
	ds_read_b128 v[186:189], v231 offset:38912
	ds_read_b128 v[190:193], v231 offset:39936
	buffer_load_dwordx4 v199, s[16:19], s66 offen lds
	s_mov_b32 m0, s38
	s_nop 0
	buffer_load_dwordx4 v228, s[16:19], s66 offen lds
	s_waitcnt vmcnt(8)
	s_waitcnt lgkmcnt(0)
	s_setprio 1
	s_barrier
	v_mfma_f32_16x16x32_bf16 v[126:129], v[130:133], v[162:165], v[126:129]
	v_mfma_f32_16x16x32_bf16 v[122:125], v[138:141], v[162:165], v[122:125]
	v_mfma_f32_16x16x32_bf16 v[118:121], v[130:133], v[170:173], v[118:121]
	v_mfma_f32_16x16x32_bf16 v[114:117], v[138:141], v[170:173], v[114:117]
	v_mfma_f32_16x16x32_bf16 v[110:113], v[130:133], v[178:181], v[110:113]
	v_mfma_f32_16x16x32_bf16 v[106:109], v[138:141], v[178:181], v[106:109]
	v_mfma_f32_16x16x32_bf16 v[102:105], v[130:133], v[186:189], v[102:105]
	v_mfma_f32_16x16x32_bf16 v[98:101], v[138:141], v[186:189], v[98:101]
	v_mfma_f32_16x16x32_bf16 v[126:129], v[134:137], v[166:169], v[126:129]
	v_mfma_f32_16x16x32_bf16 v[122:125], v[142:145], v[166:169], v[122:125]
	v_mfma_f32_16x16x32_bf16 v[118:121], v[134:137], v[174:177], v[118:121]
	v_mfma_f32_16x16x32_bf16 v[114:117], v[142:145], v[174:177], v[114:117]
	v_mfma_f32_16x16x32_bf16 v[110:113], v[134:137], v[182:185], v[110:113]
	v_mfma_f32_16x16x32_bf16 v[106:109], v[142:145], v[182:185], v[106:109]
	v_mfma_f32_16x16x32_bf16 v[102:105], v[134:137], v[190:193], v[102:105]
	v_mfma_f32_16x16x32_bf16 v[98:101], v[142:145], v[190:193], v[98:101]
	v_mfma_f32_16x16x32_bf16 v[94:97], v[146:149], v[162:165], v[94:97]
	v_mfma_f32_16x16x32_bf16 v[90:93], v[154:157], v[162:165], v[90:93]
	v_mfma_f32_16x16x32_bf16 v[86:89], v[146:149], v[170:173], v[86:89]
	v_mfma_f32_16x16x32_bf16 v[82:85], v[154:157], v[170:173], v[82:85]
	v_mfma_f32_16x16x32_bf16 v[78:81], v[146:149], v[178:181], v[78:81]
	v_mfma_f32_16x16x32_bf16 v[74:77], v[154:157], v[178:181], v[74:77]
	v_mfma_f32_16x16x32_bf16 v[70:73], v[146:149], v[186:189], v[70:73]
	v_mfma_f32_16x16x32_bf16 v[66:69], v[154:157], v[186:189], v[66:69]
	v_mfma_f32_16x16x32_bf16 v[94:97], v[150:153], v[166:169], v[94:97]
	v_mfma_f32_16x16x32_bf16 v[90:93], v[158:161], v[166:169], v[90:93]
	v_mfma_f32_16x16x32_bf16 v[86:89], v[150:153], v[174:177], v[86:89]
	v_mfma_f32_16x16x32_bf16 v[82:85], v[158:161], v[174:177], v[82:85]
	v_mfma_f32_16x16x32_bf16 v[78:81], v[150:153], v[182:185], v[78:81]
	v_mfma_f32_16x16x32_bf16 v[74:77], v[158:161], v[182:185], v[74:77]
	v_mfma_f32_16x16x32_bf16 v[70:73], v[150:153], v[190:193], v[70:73]
	v_mfma_f32_16x16x32_bf16 v[66:69], v[158:161], v[190:193], v[66:69]
	s_setprio 0
	s_barrier
	s_mov_b32 m0, s39
	s_or_b32 s66, s64, 0x80
	ds_read_b128 v[162:165], v231 offset:49152
	ds_read_b128 v[166:169], v231 offset:50176
	ds_read_b128 v[170:173], v231 offset:51200
	ds_read_b128 v[174:177], v231 offset:52224
	ds_read_b128 v[178:181], v231 offset:53248
	ds_read_b128 v[182:185], v231 offset:54272
	ds_read_b128 v[186:189], v231 offset:55296
	ds_read_b128 v[190:193], v231 offset:56320
	buffer_load_dwordx4 v227, s[12:15], s66 offen lds
	s_mov_b32 m0, s40
	s_add_i32 s64, s64, 0x20080
	buffer_load_dwordx4 v229, s[12:15], s66 offen lds
	s_mov_b32 m0, s43
	s_nop 0
	buffer_load_dwordx4 v227, s[12:15], s64 offen lds
	s_mov_b32 m0, s42
	s_nop 0
	buffer_load_dwordx4 v229, s[12:15], s64 offen lds
	s_mov_b32 m0, s41
	s_nop 0
	buffer_load_dwordx4 v199, s[16:19], s65 offen lds
	s_mov_b32 m0, s33
	s_nop 0
	buffer_load_dwordx4 v228, s[16:19], s65 offen lds
	s_waitcnt vmcnt(8)
	s_waitcnt lgkmcnt(0)
	s_setprio 1
	s_barrier
	v_mfma_f32_16x16x32_bf16 v[62:65], v[130:133], v[162:165], v[62:65]
	v_mfma_f32_16x16x32_bf16 v[58:61], v[138:141], v[162:165], v[58:61]
	v_mfma_f32_16x16x32_bf16 v[54:57], v[130:133], v[170:173], v[54:57]
	v_mfma_f32_16x16x32_bf16 v[50:53], v[138:141], v[170:173], v[50:53]
	v_mfma_f32_16x16x32_bf16 v[46:49], v[130:133], v[178:181], v[46:49]
	v_mfma_f32_16x16x32_bf16 v[42:45], v[138:141], v[178:181], v[42:45]
	v_mfma_f32_16x16x32_bf16 v[38:41], v[130:133], v[186:189], v[38:41]
	v_mfma_f32_16x16x32_bf16 v[34:37], v[138:141], v[186:189], v[34:37]
	v_mfma_f32_16x16x32_bf16 v[62:65], v[134:137], v[166:169], v[62:65]
	v_mfma_f32_16x16x32_bf16 v[58:61], v[142:145], v[166:169], v[58:61]
	v_mfma_f32_16x16x32_bf16 v[54:57], v[134:137], v[174:177], v[54:57]
	v_mfma_f32_16x16x32_bf16 v[50:53], v[142:145], v[174:177], v[50:53]
	v_mfma_f32_16x16x32_bf16 v[46:49], v[134:137], v[182:185], v[46:49]
	v_mfma_f32_16x16x32_bf16 v[42:45], v[142:145], v[182:185], v[42:45]
	v_mfma_f32_16x16x32_bf16 v[38:41], v[134:137], v[190:193], v[38:41]
	v_mfma_f32_16x16x32_bf16 v[34:37], v[142:145], v[190:193], v[34:37]
	v_mfma_f32_16x16x32_bf16 v[30:33], v[146:149], v[162:165], v[30:33]
	v_mfma_f32_16x16x32_bf16 v[26:29], v[154:157], v[162:165], v[26:29]
	v_mfma_f32_16x16x32_bf16 v[22:25], v[146:149], v[170:173], v[22:25]
	v_mfma_f32_16x16x32_bf16 v[18:21], v[154:157], v[170:173], v[18:21]
	v_mfma_f32_16x16x32_bf16 v[14:17], v[146:149], v[178:181], v[14:17]
	v_mfma_f32_16x16x32_bf16 v[10:13], v[154:157], v[178:181], v[10:13]
	v_mfma_f32_16x16x32_bf16 v[6:9], v[146:149], v[186:189], v[6:9]
	v_mfma_f32_16x16x32_bf16 v[2:5], v[154:157], v[186:189], v[2:5]
	v_mfma_f32_16x16x32_bf16 v[30:33], v[150:153], v[166:169], v[30:33]
	v_mfma_f32_16x16x32_bf16 v[26:29], v[158:161], v[166:169], v[26:29]
	v_mfma_f32_16x16x32_bf16 v[22:25], v[150:153], v[174:177], v[22:25]
	v_mfma_f32_16x16x32_bf16 v[18:21], v[158:161], v[174:177], v[18:21]
	v_mfma_f32_16x16x32_bf16 v[14:17], v[150:153], v[182:185], v[14:17]
	v_mfma_f32_16x16x32_bf16 v[10:13], v[158:161], v[182:185], v[10:13]
	v_mfma_f32_16x16x32_bf16 v[6:9], v[150:153], v[190:193], v[6:9]
	v_mfma_f32_16x16x32_bf16 v[2:5], v[158:161], v[190:193], v[2:5]
	s_setprio 0
	s_barrier
	s_add_i32 s63, s63, 2
	s_addk_i32 s2, 0x100
	s_addk_i32 s3, 0x100
	s_cmp_gt_u32 s63, 5
	s_cbranch_scc0 .LBB0_779
	v_readlane_b32 s2, v251, 45
	v_readlane_b32 s3, v251, 46
	s_and_b64 vcc, exec, s[2:3]
	s_cbranch_vccz .LBB0_782
	s_barrier

; __device__ __forceinline__ const bf16_t* selA(const Gemm& g, int s) { return sel3(g.A0, g.A1, g.A2, s); }
; __device__ __forceinline__ const bf16_t* selB(const Gemm& g, int s) { return sel3(g.B0, g.B1, g.B2, s); }
; __device__ __forceinline__ Src make_src(const bf16_t* p, size_t off) { Src s_; s_.r = __builtin_amdgcn_make_buffer_rsrc((void*)p, (short)0, 0x7fffffff, 0x00020000); s_.o = (unsigned)off; return s_; }
; #define PG8_WAIT_V(n) asm volatile("s_waitcnt vmcnt(" #n ")" ::: "memory")
; template <class Epi, bool ALIGN_EPI, bool SP2, class Hook>
; __device__ __forceinline__ void gemm_phase(LAS unsigned char* lds, const Gemm g, const StaticOrder& S, const Epi& E, Acc& acc, const bool fresh, const Hook& H, const int wave_id) {
;     ...
;         const bool has_next = S.next(ui + 1, nxt);
;         const Src nA = has_next ? make_src(selA(g, nxt.seg), (size_t)nxt.pm * tstepA) : cA, nB = has_next ? make_src(selB(g, nxt.seg), (size_t)nxt.pn * tstep) : cB;
;         for (int t = t0; t < nt; t += 2) {
;             const bool last = (t == nt - 2);
;             const Src a1 = cA + (size_t)(t + 1) * kstep;
;             const Src a2 = last ? nA : cA + (size_t)(t + 2) * kstep, b2 = last ? nB : cB + (size_t)(t + 2) * kstep;
;             const Src a3 = a2 + kstep, b3 = b2 + kstep;
;             if (last && has_next) H(nxt);
;             if constexpr (SP2) {
;             PG8_TRIP_SP2(PG8_WAIT_V(8));
.LBB0_903:
	v_add_u32_e32 v70, 0x10000, v216
	v_add_u32_e32 v118, 0x14000, v216
	ds_read_b128 v[34:37], v70
	ds_read_b128 v[46:49], v70 offset:1024
	ds_read_b128 v[58:61], v70 offset:2048
	ds_read_b128 v[70:73], v70 offset:3072
	ds_read_b128 v[82:85], v118
	ds_read_b128 v[94:97], v118 offset:1024
	ds_read_b128 v[106:109], v118 offset:2048
	ds_read_b128 v[118:121], v118 offset:3072
	s_add_i32 s12, s55, 0xfffe0080
	s_cmp_eq_u32 s57, 4
	s_cselect_b32 s60, s53, s12
	s_cselect_b32 s13, s29, s77
	s_cselect_b32 s12, s28, s76
	s_cselect_b32 s15, s31, s35
	s_cselect_b32 s14, s30, s34
	s_cselect_b32 s58, s54, s56
	s_cselect_b32 s16, s2, s8
	s_cselect_b32 s17, s3, s9
	s_cselect_b32 s18, s26, s10
	s_cselect_b32 s19, s27, s11
	s_or_b32 s59, s60, 0x80
	s_mov_b32 m0, s45
	ds_read_b128 v[130:133], v217
	ds_read_b128 v[142:145], v217 offset:1024
	ds_read_b128 v[154:157], v217 offset:2048
	ds_read_b128 v[166:169], v217 offset:3072
	ds_read_b128 v[174:177], v217 offset:4096
	ds_read_b128 v[182:185], v217 offset:5120
	ds_read_b128 v[186:189], v217 offset:6144
	ds_read_b128 v[190:193], v217 offset:7168
	buffer_load_dwordx4 v0, s[8:11], s55 offen lds
	s_mov_b32 m0, s46
	s_nop 0
	buffer_load_dwordx4 v214, s[8:11], s55 offen lds
	s_waitcnt vmcnt(8)
	s_waitcnt lgkmcnt(0)
	s_setprio 1
	s_barrier
	v_mfma_f32_16x16x32_bf16 v[178:181], v[34:37], v[130:133], v[178:181]
	v_mfma_f32_16x16x32_bf16 v[170:173], v[58:61], v[130:133], v[170:173]
	v_mfma_f32_16x16x32_bf16 v[150:153], v[34:37], v[154:157], v[150:153]
	v_mfma_f32_16x16x32_bf16 v[146:149], v[58:61], v[154:157], v[146:149]
	v_mfma_f32_16x16x32_bf16 v[126:129], v[34:37], v[174:177], v[126:129]
	v_mfma_f32_16x16x32_bf16 v[122:125], v[58:61], v[174:177], v[122:125]
	v_mfma_f32_16x16x32_bf16 v[102:105], v[34:37], v[186:189], v[102:105]
	v_mfma_f32_16x16x32_bf16 v[98:101], v[58:61], v[186:189], v[98:101]
	v_mfma_f32_16x16x32_bf16 v[178:181], v[46:49], v[142:145], v[178:181]
	v_mfma_f32_16x16x32_bf16 v[170:173], v[70:73], v[142:145], v[170:173]
	v_mfma_f32_16x16x32_bf16 v[150:153], v[46:49], v[166:169], v[150:153]
	v_mfma_f32_16x16x32_bf16 v[146:149], v[70:73], v[166:169], v[146:149]
	v_mfma_f32_16x16x32_bf16 v[126:129], v[46:49], v[182:185], v[126:129]
	v_mfma_f32_16x16x32_bf16 v[122:125], v[70:73], v[182:185], v[122:125]
	v_mfma_f32_16x16x32_bf16 v[102:105], v[46:49], v[190:193], v[102:105]
	v_mfma_f32_16x16x32_bf16 v[98:101], v[70:73], v[190:193], v[98:101]
	v_mfma_f32_16x16x32_bf16 v[162:165], v[82:85], v[130:133], v[162:165]
	v_mfma_f32_16x16x32_bf16 v[138:141], v[82:85], v[154:157], v[138:141]
	v_mfma_f32_16x16x32_bf16 v[134:137], v[106:109], v[154:157], v[134:137]
	v_mfma_f32_16x16x32_bf16 v[114:117], v[82:85], v[174:177], v[114:117]
	v_mfma_f32_16x16x32_bf16 v[110:113], v[106:109], v[174:177], v[110:113]
	v_mfma_f32_16x16x32_bf16 v[90:93], v[82:85], v[186:189], v[90:93]
	v_mfma_f32_16x16x32_bf16 v[86:89], v[106:109], v[186:189], v[86:89]
	v_mfma_f32_16x16x32_bf16 v[162:165], v[94:97], v[142:145], v[162:165]
	v_mfma_f32_16x16x32_bf16 v[130:133], v[106:109], v[130:133], v[158:161]
	v_mfma_f32_16x16x32_bf16 v[138:141], v[94:97], v[166:169], v[138:141]
	v_mfma_f32_16x16x32_bf16 v[134:137], v[118:121], v[166:169], v[134:137]
	v_mfma_f32_16x16x32_bf16 v[114:117], v[94:97], v[182:185], v[114:117]
	v_mfma_f32_16x16x32_bf16 v[110:113], v[118:121], v[182:185], v[110:113]
	v_mfma_f32_16x16x32_bf16 v[90:93], v[94:97], v[190:193], v[90:93]
	v_mfma_f32_16x16x32_bf16 v[86:89], v[118:121], v[190:193], v[86:89]
	v_mfma_f32_16x16x32_bf16 v[130:133], v[118:121], v[142:145], v[130:133]
	s_setprio 0
	s_barrier
	s_mov_b32 m0, s92
	ds_read_b128 v[142:145], v217 offset:16384
	ds_read_b128 v[154:157], v217 offset:17408
	ds_read_b128 v[158:161], v217 offset:18432
	ds_read_b128 v[166:169], v217 offset:19456
	ds_read_b128 v[174:177], v217 offset:20480
	ds_read_b128 v[182:185], v217 offset:21504
	ds_read_b128 v[186:189], v217 offset:22528
	ds_read_b128 v[190:193], v217 offset:23552
	buffer_load_dwordx4 v199, s[12:15], s58 offen lds
	s_mov_b32 m0, s93
	s_add_i32 s61, s58, 0x20000
	buffer_load_dwordx4 v215, s[12:15], s58 offen lds
	s_mov_b32 m0, s94
	s_nop 0
	buffer_load_dwordx4 v199, s[12:15], s61 offen lds
	s_mov_b32 m0, s95
	s_nop 0
	buffer_load_dwordx4 v215, s[12:15], s61 offen lds
	s_mov_b32 m0, s44
	s_nop 0
	buffer_load_dwordx4 v0, s[16:19], s60 offen lds
	s_mov_b32 m0, s36
	s_nop 0
	buffer_load_dwordx4 v214, s[16:19], s60 offen lds
	s_waitcnt vmcnt(8)
	s_waitcnt lgkmcnt(0)
	s_setprio 1
	s_barrier
	v_mfma_f32_16x16x32_bf16 v[78:81], v[34:37], v[142:145], v[78:81]
	v_mfma_f32_16x16x32_bf16 v[74:77], v[58:61], v[142:145], v[74:77]
	v_mfma_f32_16x16x32_bf16 v[54:57], v[34:37], v[158:161], v[54:57]
	v_mfma_f32_16x16x32_bf16 v[50:53], v[58:61], v[158:161], v[50:53]
	v_mfma_f32_16x16x32_bf16 v[30:33], v[34:37], v[174:177], v[30:33]
	v_mfma_f32_16x16x32_bf16 v[26:29], v[58:61], v[174:177], v[26:29]
	v_mfma_f32_16x16x32_bf16 v[14:17], v[34:37], v[186:189], v[14:17]
	v_mfma_f32_16x16x32_bf16 v[10:13], v[58:61], v[186:189], v[10:13]
	v_mfma_f32_16x16x32_bf16 v[78:81], v[46:49], v[154:157], v[78:81]
	v_mfma_f32_16x16x32_bf16 v[74:77], v[70:73], v[154:157], v[74:77]
	v_mfma_f32_16x16x32_bf16 v[54:57], v[46:49], v[166:169], v[54:57]
	v_mfma_f32_16x16x32_bf16 v[50:53], v[70:73], v[166:169], v[50:53]
	v_mfma_f32_16x16x32_bf16 v[30:33], v[46:49], v[182:185], v[30:33]
	v_mfma_f32_16x16x32_bf16 v[26:29], v[70:73], v[182:185], v[26:29]
	v_mfma_f32_16x16x32_bf16 v[14:17], v[46:49], v[190:193], v[14:17]
	v_mfma_f32_16x16x32_bf16 v[10:13], v[70:73], v[190:193], v[10:13]
	v_mfma_f32_16x16x32_bf16 v[42:45], v[82:85], v[158:161], v[42:45]
	v_mfma_f32_16x16x32_bf16 v[38:41], v[106:109], v[158:161], v[38:41]
	v_mfma_f32_16x16x32_bf16 v[22:25], v[82:85], v[174:177], v[22:25]
	v_mfma_f32_16x16x32_bf16 v[18:21], v[106:109], v[174:177], v[18:21]
	v_mfma_f32_16x16x32_bf16 v[6:9], v[82:85], v[186:189], v[6:9]
	v_mfma_f32_16x16x32_bf16 v[2:5], v[106:109], v[186:189], v[2:5]
	v_mfma_f32_16x16x32_bf16 v[34:37], v[82:85], v[142:145], v[66:69]
	v_mfma_f32_16x16x32_bf16 v[46:49], v[106:109], v[142:145], v[62:65]
	v_mfma_f32_16x16x32_bf16 v[42:45], v[94:97], v[166:169], v[42:45]
	v_mfma_f32_16x16x32_bf16 v[38:41], v[118:121], v[166:169], v[38:41]
	v_mfma_f32_16x16x32_bf16 v[22:25], v[94:97], v[182:185], v[22:25]
	v_mfma_f32_16x16x32_bf16 v[18:21], v[118:121], v[182:185], v[18:21]
	v_mfma_f32_16x16x32_bf16 v[6:9], v[94:97], v[190:193], v[6:9]
	v_mfma_f32_16x16x32_bf16 v[2:5], v[118:121], v[190:193], v[2:5]
	v_mfma_f32_16x16x32_bf16 v[34:37], v[94:97], v[154:157], v[34:37]
	v_mfma_f32_16x16x32_bf16 v[46:49], v[118:121], v[154:157], v[46:49]
	s_setprio 0
	s_barrier
; #define PG8_STAGE(bufoff, gbase, voff) do { const Src _g = (gbase); _Pragma("unroll") for (int _i = 0; _i < 2; ++_i) \
;         __builtin_amdgcn_raw_ptr_buffer_load_lds(_g.r, (LAS unsigned*)(lds + (bufoff) + ldsw + _i * 8192), 16, (voff)[_i], _g.o, 0, 0); } while (0)
; #define PG8_WAIT_V(n) asm volatile("s_waitcnt vmcnt(" #n ")" ::: "memory")
; template <class Epi, bool ALIGN_EPI, bool SP2, class Hook>
; __device__ __forceinline__ void gemm_phase(LAS unsigned char* lds, const Gemm g, const StaticOrder& S, const Epi& E, Acc& acc, const bool fresh, const Hook& H, const int wave_id) {
;     ...
;         for (int t = t0; t < nt; t += 2) {
;             const bool last = (t == nt - 2);
;             const Src a1 = cA + (size_t)(t + 1) * kstep;
;             const Src a2 = last ? nA : cA + (size_t)(t + 2) * kstep, b2 = last ? nB : cB + (size_t)(t + 2) * kstep;
;             const Src a3 = a2 + kstep, b3 = b2 + kstep;
;             if (last && has_next) H(nxt);
;             if constexpr (SP2) {
;             PG8_TRIP_SP2(PG8_WAIT_V(8));
;             } else {
;             PG8_LDB(B0, 0, 0); PG8_SCHED; PG8_LDA(At, 0, 0); PG8_STAGE(PG8_SA(1, 1), a1 + hstepA, voffA);
;             PG8_WAIT_L(8); PG8_BAR; PG8_WAIT_L(0); PG8_MMA(0, 0, At, B0); PG8_BAR; PG8_SCHED;
;             PG8_LDB(B1, 0, 1); PG8_STAGE(PG8_SB(0, 0), b2, voffB);
;             PG8_BAR; PG8_WAIT_L(0); PG8_MMA(0, 1, At, B1); PG8_BAR;
;             PG8_LDA(At, 0, 1); PG8_STAGE(PG8_SA(0, 0), a2, voffA);
;             PG8_BAR; PG8_WAIT_L(0); PG8_MMA(1, 0, At, B0); PG8_BAR; PG8_SCHED;
;             PG8_STAGE(PG8_SB(0, 1), b2 + hstep, voffB);
;             PG8_WAIT_V(6); PG8_BAR; PG8_MMA(1, 1, At, B1); PG8_BAR;
;             PG8_LDB(B0, 1, 0); PG8_SCHED; PG8_LDA(At, 1, 0); PG8_STAGE(PG8_SA(0, 1), a2 + hstepA, voffA);
;             PG8_WAIT_L(8); PG8_BAR; PG8_WAIT_L(0); PG8_MMA(0, 0, At, B0); PG8_BAR; PG8_SCHED;
;             PG8_LDB(B1, 1, 1); PG8_STAGE(PG8_SB(1, 0), b3, voffB);
;             PG8_BAR; PG8_WAIT_L(0); PG8_MMA(0, 1, At, B1); PG8_BAR;
;             PG8_LDA(At, 1, 1); PG8_STAGE(PG8_SA(1, 0), a3, voffA);
;             PG8_BAR; PG8_WAIT_L(0); PG8_MMA(1, 0, At, B0); PG8_BAR; PG8_SCHED;
;             PG8_STAGE(PG8_SB(1, 1), b3 + hstep, voffB);
;             PG8_WAIT_V(6); PG8_BAR; PG8_MMA(1, 1, At, B1); PG8_BAR;
;             }
;         }
;         if constexpr (ALIGN_EPI) { if (wr == 0) PG8_BAR; }
	v_add_u32_e32 v70, 0x18000, v216
	v_add_u32_e32 v118, 0x1c000, v216
	ds_read_b128 v[58:61], v70
	ds_read_b128 v[62:65], v70 offset:1024
	ds_read_b128 v[66:69], v70 offset:2048
	ds_read_b128 v[70:73], v70 offset:3072
	ds_read_b128 v[82:85], v118
	ds_read_b128 v[94:97], v118 offset:1024
	ds_read_b128 v[106:109], v118 offset:2048
	ds_read_b128 v[118:121], v118 offset:3072
	s_add_i32 s60, s60, 0x20000
	s_mov_b32 m0, s37
	ds_read_b128 v[142:145], v217 offset:32768
	ds_read_b128 v[154:157], v217 offset:33792
	ds_read_b128 v[166:169], v217 offset:34816
	ds_read_b128 v[174:177], v217 offset:35840
	ds_read_b128 v[182:185], v217 offset:36864
	ds_read_b128 v[186:189], v217 offset:37888
	ds_read_b128 v[190:193], v217 offset:38912
	ds_read_b128 v[194:197], v217 offset:39936
	buffer_load_dwordx4 v0, s[16:19], s60 offen lds
	s_mov_b32 m0, s38
	s_nop 0
	buffer_load_dwordx4 v214, s[16:19], s60 offen lds
	s_waitcnt vmcnt(8)
	s_waitcnt lgkmcnt(0)
	s_setprio 1
	s_barrier
	v_mfma_f32_16x16x32_bf16 v[158:161], v[58:61], v[142:145], v[178:181]
	v_mfma_f32_16x16x32_bf16 v[178:181], v[62:65], v[154:157], v[158:161]
	v_mfma_f32_16x16x32_bf16 v[158:161], v[66:69], v[142:145], v[170:173]
	v_mfma_f32_16x16x32_bf16 v[150:153], v[58:61], v[166:169], v[150:153]
	v_mfma_f32_16x16x32_bf16 v[146:149], v[66:69], v[166:169], v[146:149]
	v_mfma_f32_16x16x32_bf16 v[126:129], v[58:61], v[182:185], v[126:129]
	v_mfma_f32_16x16x32_bf16 v[122:125], v[66:69], v[182:185], v[122:125]
	v_mfma_f32_16x16x32_bf16 v[102:105], v[58:61], v[190:193], v[102:105]
	v_mfma_f32_16x16x32_bf16 v[98:101], v[66:69], v[190:193], v[98:101]
	v_mfma_f32_16x16x32_bf16 v[170:173], v[70:73], v[154:157], v[158:161]
	v_mfma_f32_16x16x32_bf16 v[150:153], v[62:65], v[174:177], v[150:153]
	v_mfma_f32_16x16x32_bf16 v[146:149], v[70:73], v[174:177], v[146:149]
	v_mfma_f32_16x16x32_bf16 v[126:129], v[62:65], v[186:189], v[126:129]
	v_mfma_f32_16x16x32_bf16 v[122:125], v[70:73], v[186:189], v[122:125]
	v_mfma_f32_16x16x32_bf16 v[102:105], v[62:65], v[194:197], v[102:105]
	v_mfma_f32_16x16x32_bf16 v[98:101], v[70:73], v[194:197], v[98:101]
	v_mfma_f32_16x16x32_bf16 v[158:161], v[82:85], v[142:145], v[162:165]
	v_mfma_f32_16x16x32_bf16 v[130:133], v[106:109], v[142:145], v[130:133]
	v_mfma_f32_16x16x32_bf16 v[162:165], v[94:97], v[154:157], v[158:161]
	v_mfma_f32_16x16x32_bf16 v[158:161], v[118:121], v[154:157], v[130:133]
	v_mfma_f32_16x16x32_bf16 v[130:133], v[82:85], v[166:169], v[138:141]
	v_mfma_f32_16x16x32_bf16 v[138:141], v[94:97], v[174:177], v[130:133]
	v_mfma_f32_16x16x32_bf16 v[130:133], v[106:109], v[166:169], v[134:137]
	v_mfma_f32_16x16x32_bf16 v[114:117], v[82:85], v[182:185], v[114:117]
	v_mfma_f32_16x16x32_bf16 v[110:113], v[106:109], v[182:185], v[110:113]
	v_mfma_f32_16x16x32_bf16 v[90:93], v[82:85], v[190:193], v[90:93]
	v_mfma_f32_16x16x32_bf16 v[86:89], v[106:109], v[190:193], v[86:89]
	v_mfma_f32_16x16x32_bf16 v[134:137], v[118:121], v[174:177], v[130:133]
	v_mfma_f32_16x16x32_bf16 v[114:117], v[94:97], v[186:189], v[114:117]
	v_mfma_f32_16x16x32_bf16 v[110:113], v[118:121], v[186:189], v[110:113]
	v_mfma_f32_16x16x32_bf16 v[90:93], v[94:97], v[194:197], v[90:93]
	v_mfma_f32_16x16x32_bf16 v[86:89], v[118:121], v[194:197], v[86:89]
	s_setprio 0
	s_barrier
	s_mov_b32 m0, s39
	s_or_b32 s60, s58, 0x80
	ds_read_b128 v[130:133], v217 offset:49152
	ds_read_b128 v[142:145], v217 offset:50176
	ds_read_b128 v[154:157], v217 offset:51200
	ds_read_b128 v[166:169], v217 offset:52224
	ds_read_b128 v[174:177], v217 offset:53248
	ds_read_b128 v[182:185], v217 offset:54272
	ds_read_b128 v[186:189], v217 offset:55296
	ds_read_b128 v[190:193], v217 offset:56320
	buffer_load_dwordx4 v199, s[12:15], s60 offen lds
	s_mov_b32 m0, s40
	s_add_i32 s58, s58, 0x20080
	buffer_load_dwordx4 v215, s[12:15], s60 offen lds
	s_mov_b32 m0, s43
	s_nop 0
	buffer_load_dwordx4 v199, s[12:15], s58 offen lds
	s_mov_b32 m0, s42
	s_nop 0
	buffer_load_dwordx4 v215, s[12:15], s58 offen lds
	s_mov_b32 m0, s41
	s_nop 0
	buffer_load_dwordx4 v0, s[16:19], s59 offen lds
	s_mov_b32 m0, s33
	s_nop 0
	buffer_load_dwordx4 v214, s[16:19], s59 offen lds
	s_waitcnt vmcnt(8)
	s_waitcnt lgkmcnt(0)
	s_setprio 1
	s_barrier
	v_mfma_f32_16x16x32_bf16 v[78:81], v[58:61], v[130:133], v[78:81]
	v_mfma_f32_16x16x32_bf16 v[74:77], v[66:69], v[130:133], v[74:77]
	v_mfma_f32_16x16x32_bf16 v[54:57], v[58:61], v[154:157], v[54:57]
	v_mfma_f32_16x16x32_bf16 v[50:53], v[66:69], v[154:157], v[50:53]
	v_mfma_f32_16x16x32_bf16 v[30:33], v[58:61], v[174:177], v[30:33]
	v_mfma_f32_16x16x32_bf16 v[26:29], v[66:69], v[174:177], v[26:29]
	v_mfma_f32_16x16x32_bf16 v[14:17], v[58:61], v[186:189], v[14:17]
	v_mfma_f32_16x16x32_bf16 v[10:13], v[66:69], v[186:189], v[10:13]
	v_mfma_f32_16x16x32_bf16 v[78:81], v[62:65], v[142:145], v[78:81]
	v_mfma_f32_16x16x32_bf16 v[74:77], v[70:73], v[142:145], v[74:77]
	v_mfma_f32_16x16x32_bf16 v[54:57], v[62:65], v[166:169], v[54:57]
	v_mfma_f32_16x16x32_bf16 v[50:53], v[70:73], v[166:169], v[50:53]
	v_mfma_f32_16x16x32_bf16 v[30:33], v[62:65], v[182:185], v[30:33]
	v_mfma_f32_16x16x32_bf16 v[26:29], v[70:73], v[182:185], v[26:29]
	v_mfma_f32_16x16x32_bf16 v[14:17], v[62:65], v[190:193], v[14:17]
	v_mfma_f32_16x16x32_bf16 v[10:13], v[70:73], v[190:193], v[10:13]
	v_mfma_f32_16x16x32_bf16 v[34:37], v[82:85], v[130:133], v[34:37]
	v_mfma_f32_16x16x32_bf16 v[66:69], v[94:97], v[142:145], v[34:37]
	v_mfma_f32_16x16x32_bf16 v[34:37], v[106:109], v[130:133], v[46:49]
	v_mfma_f32_16x16x32_bf16 v[62:65], v[118:121], v[142:145], v[34:37]
	v_mfma_f32_16x16x32_bf16 v[34:37], v[82:85], v[154:157], v[42:45]
	v_mfma_f32_16x16x32_bf16 v[42:45], v[94:97], v[166:169], v[34:37]
	v_mfma_f32_16x16x32_bf16 v[34:37], v[106:109], v[154:157], v[38:41]
	v_mfma_f32_16x16x32_bf16 v[22:25], v[82:85], v[174:177], v[22:25]
	v_mfma_f32_16x16x32_bf16 v[18:21], v[106:109], v[174:177], v[18:21]
	v_mfma_f32_16x16x32_bf16 v[6:9], v[82:85], v[186:189], v[6:9]
	v_mfma_f32_16x16x32_bf16 v[2:5], v[106:109], v[186:189], v[2:5]
	v_mfma_f32_16x16x32_bf16 v[38:41], v[118:121], v[166:169], v[34:37]
	v_mfma_f32_16x16x32_bf16 v[22:25], v[94:97], v[182:185], v[22:25]
	v_mfma_f32_16x16x32_bf16 v[18:21], v[118:121], v[182:185], v[18:21]
	v_mfma_f32_16x16x32_bf16 v[6:9], v[94:97], v[190:193], v[6:9]
	v_mfma_f32_16x16x32_bf16 v[2:5], v[118:121], v[190:193], v[2:5]
	s_setprio 0
	s_barrier
	s_add_i32 s57, s57, 2
	s_addk_i32 s55, 0x100
	s_addk_i32 s56, 0x100
	s_cmp_gt_u32 s57, 5
	s_cbranch_scc0 .LBB0_903
	v_readlane_b32 s8, v251, 45
	v_readlane_b32 s9, v251, 46
	s_and_b64 vcc, exec, s[8:9]
	s_cbranch_vccz .LBB0_906
	s_barrier

; __device__ __forceinline__ const bf16_t* selA(const Gemm& g, int s) { return sel3(g.A0, g.A1, g.A2, s); }
; __device__ __forceinline__ const bf16_t* selB(const Gemm& g, int s) { return sel3(g.B0, g.B1, g.B2, s); }
; __device__ __forceinline__ Src make_src(const bf16_t* p, size_t off) { Src s_; s_.r = __builtin_amdgcn_make_buffer_rsrc((void*)p, (short)0, 0x7fffffff, 0x00020000); s_.o = (unsigned)off; return s_; }
; #define PG8_WAIT_V(n) asm volatile("s_waitcnt vmcnt(" #n ")" ::: "memory")
; template <class Epi, bool ALIGN_EPI, bool SP2, class Hook>
; __device__ __forceinline__ void gemm_phase(LAS unsigned char* lds, const Gemm g, const StaticOrder& S, const Epi& E, Acc& acc, const bool fresh, const Hook& H, const int wave_id) {
;     ...
;         const bool has_next = S.next(ui + 1, nxt);
;         const Src nA = has_next ? make_src(selA(g, nxt.seg), (size_t)nxt.pm * tstepA) : cA, nB = has_next ? make_src(selB(g, nxt.seg), (size_t)nxt.pn * tstep) : cB;
;         for (int t = t0; t < nt; t += 2) {
;             const bool last = (t == nt - 2);
;             const Src a1 = cA + (size_t)(t + 1) * kstep;
;             const Src a2 = last ? nA : cA + (size_t)(t + 2) * kstep, b2 = last ? nB : cB + (size_t)(t + 2) * kstep;
;             const Src a3 = a2 + kstep, b3 = b2 + kstep;
;             if (last && has_next) H(nxt);
;             if constexpr (SP2) {
;             PG8_TRIP_SP2(PG8_WAIT_V(8));
.LBB0_1029:
.LBB0_1030:
	v_add_u32_e32 v0, 0x10000, v230
	s_waitcnt vmcnt(0)
	ds_read_b128 v[130:133], v0
	ds_read_b128 v[134:137], v0 offset:1024
	ds_read_b128 v[138:141], v0 offset:2048
	ds_read_b128 v[142:145], v0 offset:3072
	v_add_u32_e32 v0, 0x14000, v230
	ds_read_b128 v[146:149], v0
	ds_read_b128 v[150:153], v0 offset:1024
	ds_read_b128 v[154:157], v0 offset:2048
	ds_read_b128 v[158:161], v0 offset:3072
	s_lshl_b32 s55, s20, 7
	s_add_i32 s18, s73, s55
	s_and_b64 s[12:13], s[16:17], exec
	s_cselect_b32 s13, s31, s9
	s_cselect_b32 s12, s30, s8
	s_cselect_b32 s15, s35, s11
	s_cselect_b32 s14, s34, s10
	s_cselect_b32 s56, s68, s18
	s_add_i32 s21, s74, s55
	s_and_b64 s[16:17], s[16:17], exec
	s_cselect_b32 s54, s69, s21
	s_cselect_b32 s17, s51, s77
	s_cselect_b32 s16, s50, s76
	s_cselect_b32 s19, s53, s7
	s_cselect_b32 s18, s52, s6
	s_or_b32 s21, s56, 0x80
	s_or_b32 s57, s54, 0x80
	s_add_i32 s55, s55, s75
	s_mov_b32 m0, s45
	ds_read_b128 v[162:165], v231
	ds_read_b128 v[166:169], v231 offset:1024
	ds_read_b128 v[170:173], v231 offset:2048
	ds_read_b128 v[174:177], v231 offset:3072
	ds_read_b128 v[178:181], v231 offset:4096
	ds_read_b128 v[182:185], v231 offset:5120
	ds_read_b128 v[186:189], v231 offset:6144
	ds_read_b128 v[190:193], v231 offset:7168
	buffer_load_dwordx4 v199, s[8:11], s55 offen lds
	s_mov_b32 m0, s46
	s_nop 0
	buffer_load_dwordx4 v228, s[8:11], s55 offen lds
	s_waitcnt vmcnt(8)
	s_waitcnt lgkmcnt(0)
	s_setprio 1
	s_barrier
	v_mfma_f32_16x16x32_bf16 v[126:129], v[130:133], v[162:165], v[126:129]
	v_mfma_f32_16x16x32_bf16 v[122:125], v[138:141], v[162:165], v[122:125]
	v_mfma_f32_16x16x32_bf16 v[118:121], v[130:133], v[170:173], v[118:121]
	v_mfma_f32_16x16x32_bf16 v[114:117], v[138:141], v[170:173], v[114:117]
	v_mfma_f32_16x16x32_bf16 v[110:113], v[130:133], v[178:181], v[110:113]
	v_mfma_f32_16x16x32_bf16 v[106:109], v[138:141], v[178:181], v[106:109]
	v_mfma_f32_16x16x32_bf16 v[102:105], v[130:133], v[186:189], v[102:105]
	v_mfma_f32_16x16x32_bf16 v[98:101], v[138:141], v[186:189], v[98:101]
	v_mfma_f32_16x16x32_bf16 v[126:129], v[134:137], v[166:169], v[126:129]
	v_mfma_f32_16x16x32_bf16 v[122:125], v[142:145], v[166:169], v[122:125]
	v_mfma_f32_16x16x32_bf16 v[118:121], v[134:137], v[174:177], v[118:121]
	v_mfma_f32_16x16x32_bf16 v[114:117], v[142:145], v[174:177], v[114:117]
	v_mfma_f32_16x16x32_bf16 v[110:113], v[134:137], v[182:185], v[110:113]
	v_mfma_f32_16x16x32_bf16 v[106:109], v[142:145], v[182:185], v[106:109]
	v_mfma_f32_16x16x32_bf16 v[102:105], v[134:137], v[190:193], v[102:105]
	v_mfma_f32_16x16x32_bf16 v[98:101], v[142:145], v[190:193], v[98:101]
	v_mfma_f32_16x16x32_bf16 v[94:97], v[146:149], v[162:165], v[94:97]
	v_mfma_f32_16x16x32_bf16 v[90:93], v[154:157], v[162:165], v[90:93]
	v_mfma_f32_16x16x32_bf16 v[86:89], v[146:149], v[170:173], v[86:89]
	v_mfma_f32_16x16x32_bf16 v[82:85], v[154:157], v[170:173], v[82:85]
	v_mfma_f32_16x16x32_bf16 v[78:81], v[146:149], v[178:181], v[78:81]
	v_mfma_f32_16x16x32_bf16 v[74:77], v[154:157], v[178:181], v[74:77]
	v_mfma_f32_16x16x32_bf16 v[70:73], v[146:149], v[186:189], v[70:73]
	v_mfma_f32_16x16x32_bf16 v[66:69], v[154:157], v[186:189], v[66:69]
	v_mfma_f32_16x16x32_bf16 v[94:97], v[150:153], v[166:169], v[94:97]
	v_mfma_f32_16x16x32_bf16 v[90:93], v[158:161], v[166:169], v[90:93]
	v_mfma_f32_16x16x32_bf16 v[86:89], v[150:153], v[174:177], v[86:89]
	v_mfma_f32_16x16x32_bf16 v[82:85], v[158:161], v[174:177], v[82:85]
	v_mfma_f32_16x16x32_bf16 v[78:81], v[150:153], v[182:185], v[78:81]
	v_mfma_f32_16x16x32_bf16 v[74:77], v[158:161], v[182:185], v[74:77]
	v_mfma_f32_16x16x32_bf16 v[70:73], v[150:153], v[190:193], v[70:73]
	v_mfma_f32_16x16x32_bf16 v[66:69], v[158:161], v[190:193], v[66:69]
	s_setprio 0
	s_barrier
	s_mov_b32 m0, s92
	ds_read_b128 v[162:165], v231 offset:16384
	ds_read_b128 v[166:169], v231 offset:17408
	ds_read_b128 v[170:173], v231 offset:18432
	ds_read_b128 v[174:177], v231 offset:19456
	ds_read_b128 v[178:181], v231 offset:20480
	ds_read_b128 v[182:185], v231 offset:21504
	ds_read_b128 v[186:189], v231 offset:22528
	ds_read_b128 v[190:193], v231 offset:23552
	buffer_load_dwordx4 v227, s[16:19], s54 offen lds
	s_mov_b32 m0, s93
	s_add_i32 s55, s54, 0x20000
	buffer_load_dwordx4 v229, s[16:19], s54 offen lds
	s_mov_b32 m0, s94
	s_nop 0
	buffer_load_dwordx4 v227, s[16:19], s55 offen lds
	s_mov_b32 m0, s95
	s_nop 0
	buffer_load_dwordx4 v229, s[16:19], s55 offen lds
	s_mov_b32 m0, s44
	s_nop 0
	buffer_load_dwordx4 v199, s[12:15], s56 offen lds
	s_mov_b32 m0, s36
	s_nop 0
	buffer_load_dwordx4 v228, s[12:15], s56 offen lds
	s_waitcnt vmcnt(8)
	s_waitcnt lgkmcnt(0)
	s_setprio 1
	s_barrier
	v_mfma_f32_16x16x32_bf16 v[62:65], v[130:133], v[162:165], v[62:65]
	v_mfma_f32_16x16x32_bf16 v[58:61], v[138:141], v[162:165], v[58:61]
	v_mfma_f32_16x16x32_bf16 v[54:57], v[130:133], v[170:173], v[54:57]
	v_mfma_f32_16x16x32_bf16 v[50:53], v[138:141], v[170:173], v[50:53]
	v_mfma_f32_16x16x32_bf16 v[46:49], v[130:133], v[178:181], v[46:49]
	v_mfma_f32_16x16x32_bf16 v[42:45], v[138:141], v[178:181], v[42:45]
	v_mfma_f32_16x16x32_bf16 v[38:41], v[130:133], v[186:189], v[38:41]
	v_mfma_f32_16x16x32_bf16 v[34:37], v[138:141], v[186:189], v[34:37]
	v_mfma_f32_16x16x32_bf16 v[62:65], v[134:137], v[166:169], v[62:65]
	v_mfma_f32_16x16x32_bf16 v[58:61], v[142:145], v[166:169], v[58:61]
	v_mfma_f32_16x16x32_bf16 v[54:57], v[134:137], v[174:177], v[54:57]
	v_mfma_f32_16x16x32_bf16 v[50:53], v[142:145], v[174:177], v[50:53]
	v_mfma_f32_16x16x32_bf16 v[46:49], v[134:137], v[182:185], v[46:49]
	v_mfma_f32_16x16x32_bf16 v[42:45], v[142:145], v[182:185], v[42:45]
	v_mfma_f32_16x16x32_bf16 v[38:41], v[134:137], v[190:193], v[38:41]
	v_mfma_f32_16x16x32_bf16 v[34:37], v[142:145], v[190:193], v[34:37]
	v_mfma_f32_16x16x32_bf16 v[30:33], v[146:149], v[162:165], v[30:33]
	v_mfma_f32_16x16x32_bf16 v[26:29], v[154:157], v[162:165], v[26:29]
	v_mfma_f32_16x16x32_bf16 v[22:25], v[146:149], v[170:173], v[22:25]
	v_mfma_f32_16x16x32_bf16 v[18:21], v[154:157], v[170:173], v[18:21]
	v_mfma_f32_16x16x32_bf16 v[14:17], v[146:149], v[178:181], v[14:17]
	v_mfma_f32_16x16x32_bf16 v[10:13], v[154:157], v[178:181], v[10:13]
	v_mfma_f32_16x16x32_bf16 v[6:9], v[146:149], v[186:189], v[6:9]
	v_mfma_f32_16x16x32_bf16 v[2:5], v[154:157], v[186:189], v[2:5]
	v_mfma_f32_16x16x32_bf16 v[30:33], v[150:153], v[166:169], v[30:33]
	v_mfma_f32_16x16x32_bf16 v[26:29], v[158:161], v[166:169], v[26:29]
	v_mfma_f32_16x16x32_bf16 v[22:25], v[150:153], v[174:177], v[22:25]
	v_mfma_f32_16x16x32_bf16 v[18:21], v[158:161], v[174:177], v[18:21]
	v_mfma_f32_16x16x32_bf16 v[14:17], v[150:153], v[182:185], v[14:17]
	v_mfma_f32_16x16x32_bf16 v[10:13], v[158:161], v[182:185], v[10:13]
	v_mfma_f32_16x16x32_bf16 v[6:9], v[150:153], v[190:193], v[6:9]
	v_mfma_f32_16x16x32_bf16 v[2:5], v[158:161], v[190:193], v[2:5]
	s_setprio 0
	s_barrier
	v_add_u32_e32 v0, 0x18000, v230
	ds_read_b128 v[130:133], v0
	ds_read_b128 v[134:137], v0 offset:1024
	ds_read_b128 v[138:141], v0 offset:2048
	ds_read_b128 v[142:145], v0 offset:3072
	v_add_u32_e32 v0, 0x1c000, v230
	ds_read_b128 v[146:149], v0
	ds_read_b128 v[150:153], v0 offset:1024
	ds_read_b128 v[154:157], v0 offset:2048
	ds_read_b128 v[158:161], v0 offset:3072
	s_add_i32 s56, s56, 0x20000
	s_mov_b32 m0, s37
	ds_read_b128 v[162:165], v231 offset:32768
	ds_read_b128 v[166:169], v231 offset:33792
	ds_read_b128 v[170:173], v231 offset:34816
	ds_read_b128 v[174:177], v231 offset:35840
	ds_read_b128 v[178:181], v231 offset:36864
	ds_read_b128 v[182:185], v231 offset:37888
	ds_read_b128 v[186:189], v231 offset:38912
	ds_read_b128 v[190:193], v231 offset:39936
	buffer_load_dwordx4 v199, s[12:15], s56 offen lds
	s_mov_b32 m0, s38
	s_nop 0
	buffer_load_dwordx4 v228, s[12:15], s56 offen lds
	s_waitcnt vmcnt(8)
	s_waitcnt lgkmcnt(0)
	s_setprio 1
	s_barrier
	v_mfma_f32_16x16x32_bf16 v[126:129], v[130:133], v[162:165], v[126:129]
	v_mfma_f32_16x16x32_bf16 v[122:125], v[138:141], v[162:165], v[122:125]
	v_mfma_f32_16x16x32_bf16 v[118:121], v[130:133], v[170:173], v[118:121]
	v_mfma_f32_16x16x32_bf16 v[114:117], v[138:141], v[170:173], v[114:117]
	v_mfma_f32_16x16x32_bf16 v[110:113], v[130:133], v[178:181], v[110:113]
	v_mfma_f32_16x16x32_bf16 v[106:109], v[138:141], v[178:181], v[106:109]
	v_mfma_f32_16x16x32_bf16 v[102:105], v[130:133], v[186:189], v[102:105]
	v_mfma_f32_16x16x32_bf16 v[98:101], v[138:141], v[186:189], v[98:101]
	v_mfma_f32_16x16x32_bf16 v[126:129], v[134:137], v[166:169], v[126:129]
	v_mfma_f32_16x16x32_bf16 v[122:125], v[142:145], v[166:169], v[122:125]
	v_mfma_f32_16x16x32_bf16 v[118:121], v[134:137], v[174:177], v[118:121]
	v_mfma_f32_16x16x32_bf16 v[114:117], v[142:145], v[174:177], v[114:117]
	v_mfma_f32_16x16x32_bf16 v[110:113], v[134:137], v[182:185], v[110:113]
	v_mfma_f32_16x16x32_bf16 v[106:109], v[142:145], v[182:185], v[106:109]
	v_mfma_f32_16x16x32_bf16 v[102:105], v[134:137], v[190:193], v[102:105]
	v_mfma_f32_16x16x32_bf16 v[98:101], v[142:145], v[190:193], v[98:101]
	v_mfma_f32_16x16x32_bf16 v[94:97], v[146:149], v[162:165], v[94:97]
	v_mfma_f32_16x16x32_bf16 v[90:93], v[154:157], v[162:165], v[90:93]
	v_mfma_f32_16x16x32_bf16 v[86:89], v[146:149], v[170:173], v[86:89]
	v_mfma_f32_16x16x32_bf16 v[82:85], v[154:157], v[170:173], v[82:85]
	v_mfma_f32_16x16x32_bf16 v[78:81], v[146:149], v[178:181], v[78:81]
	v_mfma_f32_16x16x32_bf16 v[74:77], v[154:157], v[178:181], v[74:77]
	v_mfma_f32_16x16x32_bf16 v[70:73], v[146:149], v[186:189], v[70:73]
	v_mfma_f32_16x16x32_bf16 v[66:69], v[154:157], v[186:189], v[66:69]
	v_mfma_f32_16x16x32_bf16 v[94:97], v[150:153], v[166:169], v[94:97]
	v_mfma_f32_16x16x32_bf16 v[90:93], v[158:161], v[166:169], v[90:93]
	v_mfma_f32_16x16x32_bf16 v[86:89], v[150:153], v[174:177], v[86:89]
	v_mfma_f32_16x16x32_bf16 v[82:85], v[158:161], v[174:177], v[82:85]
	v_mfma_f32_16x16x32_bf16 v[78:81], v[150:153], v[182:185], v[78:81]
	v_mfma_f32_16x16x32_bf16 v[74:77], v[158:161], v[182:185], v[74:77]
	v_mfma_f32_16x16x32_bf16 v[70:73], v[150:153], v[190:193], v[70:73]
	v_mfma_f32_16x16x32_bf16 v[66:69], v[158:161], v[190:193], v[66:69]
	s_setprio 0
	s_barrier
; #define PG8_WAIT_V(n) asm volatile("s_waitcnt vmcnt(" #n ")" ::: "memory")
; template <class Epi, bool ALIGN_EPI, bool SP2, class Hook>
; __device__ __forceinline__ void gemm_phase(LAS unsigned char* lds, const Gemm g, const StaticOrder& S, const Epi& E, Acc& acc, const bool fresh, const Hook& H, const int wave_id) {
;     ...
;         for (int t = t0; t < nt; t += 2) {
;             const bool last = (t == nt - 2);
;             const Src a1 = cA + (size_t)(t + 1) * kstep;
;             const Src a2 = last ? nA : cA + (size_t)(t + 2) * kstep, b2 = last ? nB : cB + (size_t)(t + 2) * kstep;
;             const Src a3 = a2 + kstep, b3 = b2 + kstep;
;             if (last && has_next) H(nxt);
;             if constexpr (SP2) {
;             PG8_TRIP_SP2(PG8_WAIT_V(8));
	s_mov_b32 m0, s39
	ds_read_b128 v[162:165], v231 offset:49152
	ds_read_b128 v[166:169], v231 offset:50176
	ds_read_b128 v[170:173], v231 offset:51200
	ds_read_b128 v[174:177], v231 offset:52224
	ds_read_b128 v[178:181], v231 offset:53248
	ds_read_b128 v[182:185], v231 offset:54272
	ds_read_b128 v[186:189], v231 offset:55296
	ds_read_b128 v[190:193], v231 offset:56320
	buffer_load_dwordx4 v227, s[16:19], s57 offen lds
	s_mov_b32 m0, s40
	s_add_i32 s54, s54, 0x20080
	buffer_load_dwordx4 v229, s[16:19], s57 offen lds
	s_mov_b32 m0, s43
	s_nop 0
	buffer_load_dwordx4 v227, s[16:19], s54 offen lds
	s_mov_b32 m0, s42
	s_nop 0
	buffer_load_dwordx4 v229, s[16:19], s54 offen lds
	s_mov_b32 m0, s41
	s_nop 0
	buffer_load_dwordx4 v199, s[12:15], s21 offen lds
	s_mov_b32 m0, s33
	s_nop 0
	buffer_load_dwordx4 v228, s[12:15], s21 offen lds
	s_waitcnt vmcnt(8)
	s_waitcnt lgkmcnt(0)
	s_setprio 1
	s_barrier
	v_mfma_f32_16x16x32_bf16 v[62:65], v[130:133], v[162:165], v[62:65]
	v_mfma_f32_16x16x32_bf16 v[58:61], v[138:141], v[162:165], v[58:61]
	v_mfma_f32_16x16x32_bf16 v[54:57], v[130:133], v[170:173], v[54:57]
	v_mfma_f32_16x16x32_bf16 v[50:53], v[138:141], v[170:173], v[50:53]
	v_mfma_f32_16x16x32_bf16 v[46:49], v[130:133], v[178:181], v[46:49]
	v_mfma_f32_16x16x32_bf16 v[42:45], v[138:141], v[178:181], v[42:45]
	v_mfma_f32_16x16x32_bf16 v[38:41], v[130:133], v[186:189], v[38:41]
	v_mfma_f32_16x16x32_bf16 v[34:37], v[138:141], v[186:189], v[34:37]
	v_mfma_f32_16x16x32_bf16 v[62:65], v[134:137], v[166:169], v[62:65]
	v_mfma_f32_16x16x32_bf16 v[58:61], v[142:145], v[166:169], v[58:61]
	v_mfma_f32_16x16x32_bf16 v[54:57], v[134:137], v[174:177], v[54:57]
	v_mfma_f32_16x16x32_bf16 v[50:53], v[142:145], v[174:177], v[50:53]
	v_mfma_f32_16x16x32_bf16 v[46:49], v[134:137], v[182:185], v[46:49]
	v_mfma_f32_16x16x32_bf16 v[42:45], v[142:145], v[182:185], v[42:45]
	v_mfma_f32_16x16x32_bf16 v[38:41], v[134:137], v[190:193], v[38:41]
	v_mfma_f32_16x16x32_bf16 v[34:37], v[142:145], v[190:193], v[34:37]
	v_mfma_f32_16x16x32_bf16 v[30:33], v[146:149], v[162:165], v[30:33]
	v_mfma_f32_16x16x32_bf16 v[26:29], v[154:157], v[162:165], v[26:29]
	v_mfma_f32_16x16x32_bf16 v[22:25], v[146:149], v[170:173], v[22:25]
	v_mfma_f32_16x16x32_bf16 v[18:21], v[154:157], v[170:173], v[18:21]
	v_mfma_f32_16x16x32_bf16 v[14:17], v[146:149], v[178:181], v[14:17]
	v_mfma_f32_16x16x32_bf16 v[10:13], v[154:157], v[178:181], v[10:13]
	v_mfma_f32_16x16x32_bf16 v[6:9], v[146:149], v[186:189], v[6:9]
	v_mfma_f32_16x16x32_bf16 v[2:5], v[154:157], v[186:189], v[2:5]
	v_mfma_f32_16x16x32_bf16 v[30:33], v[150:153], v[166:169], v[30:33]
	v_mfma_f32_16x16x32_bf16 v[26:29], v[158:161], v[166:169], v[26:29]
	v_mfma_f32_16x16x32_bf16 v[22:25], v[150:153], v[174:177], v[22:25]
	v_mfma_f32_16x16x32_bf16 v[18:21], v[158:161], v[174:177], v[18:21]
	v_mfma_f32_16x16x32_bf16 v[14:17], v[150:153], v[182:185], v[14:17]
	v_mfma_f32_16x16x32_bf16 v[10:13], v[158:161], v[182:185], v[10:13]
	v_mfma_f32_16x16x32_bf16 v[6:9], v[150:153], v[190:193], v[6:9]
	v_mfma_f32_16x16x32_bf16 v[2:5], v[158:161], v[190:193], v[2:5]
	s_setprio 0
	s_barrier
	s_add_i32 s12, s20, 2
	s_cmp_gt_u32 s20, 5
	s_cbranch_scc1 .LBB0_1032
	s_mov_b32 s20, s12
	s_branch .LBB0_951

; __device__ __forceinline__ const bf16_t* selA(const Gemm& g, int s) { return sel3(g.A0, g.A1, g.A2, s); }
; __device__ __forceinline__ const bf16_t* selB(const Gemm& g, int s) { return sel3(g.B0, g.B1, g.B2, s); }
; __device__ __forceinline__ Src make_src(const bf16_t* p, size_t off) { Src s_; s_.r = __builtin_amdgcn_make_buffer_rsrc((void*)p, (short)0, 0x7fffffff, 0x00020000); s_.o = (unsigned)off; return s_; }
; #define PG8_WAIT_V(n) asm volatile("s_waitcnt vmcnt(" #n ")" ::: "memory")
; template <class Epi, bool ALIGN_EPI, bool SP2, class Hook>
; __device__ __forceinline__ void gemm_phase(LAS unsigned char* lds, const Gemm g, const StaticOrder& S, const Epi& E, Acc& acc, const bool fresh, const Hook& H, const int wave_id) {
;     ...
;         const bool has_next = S.next(ui + 1, nxt);
;         const Src nA = has_next ? make_src(selA(g, nxt.seg), (size_t)nxt.pm * tstepA) : cA, nB = has_next ? make_src(selB(g, nxt.seg), (size_t)nxt.pn * tstep) : cB;
;         for (int t = t0; t < nt; t += 2) {
;             const bool last = (t == nt - 2);
;             const Src a1 = cA + (size_t)(t + 1) * kstep;
;             const Src a2 = last ? nA : cA + (size_t)(t + 2) * kstep, b2 = last ? nB : cB + (size_t)(t + 2) * kstep;
;             const Src a3 = a2 + kstep, b3 = b2 + kstep;
;             if (last && has_next) H(nxt);
;             if constexpr (SP2) {
;             PG8_TRIP_SP2(PG8_WAIT_V(8));
.LBB0_1235:
	v_add_u32_e32 v142, 0x10000, v161
	v_add_u32_e32 v163, 0x14000, v161
	ds_read_b128 v[130:133], v142
	ds_read_b128 v[134:137], v142 offset:1024
	ds_read_b128 v[138:141], v142 offset:2048
	ds_read_b128 v[142:145], v142 offset:3072
	ds_read_b128 v[146:149], v163
	ds_read_b128 v[150:153], v163 offset:1024
	ds_read_b128 v[154:157], v163 offset:2048
	ds_read_b128 v[164:167], v163 offset:3072
	s_add_i32 s16, s2, 0xfffc0080
	s_cmp_eq_u32 s59, 12
	s_cselect_b32 s62, s55, s16
	s_cselect_b32 s17, s31, s9
	s_cselect_b32 s16, s30, s8
	s_cselect_b32 s19, s35, s51
	s_cselect_b32 s18, s34, s50
	s_cselect_b32 s60, s56, s3
	s_cselect_b32 s20, s26, s12
	s_cselect_b32 s21, s27, s13
	s_cselect_b32 s22, s28, s14
	s_cselect_b32 s23, s29, s15
	s_or_b32 s61, s62, 0x80
	s_mov_b32 m0, s45
	ds_read_b128 v[168:171], v162
	ds_read_b128 v[172:175], v162 offset:1024
	ds_read_b128 v[176:179], v162 offset:2048
	ds_read_b128 v[180:183], v162 offset:3072
	ds_read_b128 v[184:187], v162 offset:4096
	ds_read_b128 v[188:191], v162 offset:5120
	ds_read_b128 v[192:195], v162 offset:6144
	ds_read_b128 v[200:203], v162 offset:7168
	buffer_load_dwordx4 v0, s[12:15], s2 offen lds
	s_mov_b32 m0, s46
	s_nop 0
	buffer_load_dwordx4 v159, s[12:15], s2 offen lds
	s_waitcnt vmcnt(8)
	s_waitcnt lgkmcnt(0)
	s_setprio 1
	s_barrier
	v_mfma_f32_16x16x32_bf16 v[126:129], v[130:133], v[168:171], v[126:129]
	v_mfma_f32_16x16x32_bf16 v[122:125], v[138:141], v[168:171], v[122:125]
	v_mfma_f32_16x16x32_bf16 v[110:113], v[130:133], v[176:179], v[110:113]
	v_mfma_f32_16x16x32_bf16 v[106:109], v[138:141], v[176:179], v[106:109]
	v_mfma_f32_16x16x32_bf16 v[94:97], v[130:133], v[184:187], v[94:97]
	v_mfma_f32_16x16x32_bf16 v[90:93], v[138:141], v[184:187], v[90:93]
	v_mfma_f32_16x16x32_bf16 v[78:81], v[130:133], v[192:195], v[78:81]
	v_mfma_f32_16x16x32_bf16 v[74:77], v[138:141], v[192:195], v[74:77]
	v_mfma_f32_16x16x32_bf16 v[126:129], v[134:137], v[172:175], v[126:129]
	v_mfma_f32_16x16x32_bf16 v[122:125], v[142:145], v[172:175], v[122:125]
	v_mfma_f32_16x16x32_bf16 v[110:113], v[134:137], v[180:183], v[110:113]
	v_mfma_f32_16x16x32_bf16 v[106:109], v[142:145], v[180:183], v[106:109]
	v_mfma_f32_16x16x32_bf16 v[94:97], v[134:137], v[188:191], v[94:97]
	v_mfma_f32_16x16x32_bf16 v[90:93], v[142:145], v[188:191], v[90:93]
	v_mfma_f32_16x16x32_bf16 v[78:81], v[134:137], v[200:203], v[78:81]
	v_mfma_f32_16x16x32_bf16 v[74:77], v[142:145], v[200:203], v[74:77]
	v_mfma_f32_16x16x32_bf16 v[118:121], v[146:149], v[168:171], v[118:121]
	v_mfma_f32_16x16x32_bf16 v[114:117], v[154:157], v[168:171], v[114:117]
	v_mfma_f32_16x16x32_bf16 v[102:105], v[146:149], v[176:179], v[102:105]
	v_mfma_f32_16x16x32_bf16 v[98:101], v[154:157], v[176:179], v[98:101]
	v_mfma_f32_16x16x32_bf16 v[86:89], v[146:149], v[184:187], v[86:89]
	v_mfma_f32_16x16x32_bf16 v[82:85], v[154:157], v[184:187], v[82:85]
	v_mfma_f32_16x16x32_bf16 v[70:73], v[146:149], v[192:195], v[70:73]
	v_mfma_f32_16x16x32_bf16 v[66:69], v[154:157], v[192:195], v[66:69]
	v_mfma_f32_16x16x32_bf16 v[118:121], v[150:153], v[172:175], v[118:121]
	v_mfma_f32_16x16x32_bf16 v[114:117], v[164:167], v[172:175], v[114:117]
	v_mfma_f32_16x16x32_bf16 v[102:105], v[150:153], v[180:183], v[102:105]
	v_mfma_f32_16x16x32_bf16 v[98:101], v[164:167], v[180:183], v[98:101]
	v_mfma_f32_16x16x32_bf16 v[86:89], v[150:153], v[188:191], v[86:89]
	v_mfma_f32_16x16x32_bf16 v[82:85], v[164:167], v[188:191], v[82:85]
	v_mfma_f32_16x16x32_bf16 v[70:73], v[150:153], v[200:203], v[70:73]
	v_mfma_f32_16x16x32_bf16 v[66:69], v[164:167], v[200:203], v[66:69]
	s_setprio 0
	s_barrier
	s_mov_b32 m0, s92
	ds_read_b128 v[168:171], v162 offset:16384
	ds_read_b128 v[172:175], v162 offset:17408
	ds_read_b128 v[176:179], v162 offset:18432
	ds_read_b128 v[180:183], v162 offset:19456
	ds_read_b128 v[184:187], v162 offset:20480
	ds_read_b128 v[188:191], v162 offset:21504
	ds_read_b128 v[192:195], v162 offset:22528
	ds_read_b128 v[200:203], v162 offset:23552
	buffer_load_dwordx4 v158, s[16:19], s60 offen lds
	s_mov_b32 m0, s93
	s_add_i32 s63, s60, 0x40000
	buffer_load_dwordx4 v160, s[16:19], s60 offen lds
	s_mov_b32 m0, s94
	s_nop 0
	buffer_load_dwordx4 v158, s[16:19], s63 offen lds
	s_mov_b32 m0, s95
	s_nop 0
	buffer_load_dwordx4 v160, s[16:19], s63 offen lds
	s_mov_b32 m0, s44
	s_nop 0
	buffer_load_dwordx4 v0, s[20:23], s62 offen lds
	s_mov_b32 m0, s36
	s_nop 0
	buffer_load_dwordx4 v159, s[20:23], s62 offen lds
	s_waitcnt vmcnt(8)
	s_waitcnt lgkmcnt(0)
	s_setprio 1
	s_barrier
	v_mfma_f32_16x16x32_bf16 v[62:65], v[130:133], v[168:171], v[62:65]
	v_mfma_f32_16x16x32_bf16 v[58:61], v[138:141], v[168:171], v[58:61]
	v_mfma_f32_16x16x32_bf16 v[46:49], v[130:133], v[176:179], v[46:49]
	v_mfma_f32_16x16x32_bf16 v[42:45], v[138:141], v[176:179], v[42:45]
	v_mfma_f32_16x16x32_bf16 v[30:33], v[130:133], v[184:187], v[30:33]
	v_mfma_f32_16x16x32_bf16 v[26:29], v[138:141], v[184:187], v[26:29]
	v_mfma_f32_16x16x32_bf16 v[14:17], v[130:133], v[192:195], v[14:17]
	v_mfma_f32_16x16x32_bf16 v[10:13], v[138:141], v[192:195], v[10:13]
	v_mfma_f32_16x16x32_bf16 v[62:65], v[134:137], v[172:175], v[62:65]
	v_mfma_f32_16x16x32_bf16 v[58:61], v[142:145], v[172:175], v[58:61]
	v_mfma_f32_16x16x32_bf16 v[46:49], v[134:137], v[180:183], v[46:49]
	v_mfma_f32_16x16x32_bf16 v[42:45], v[142:145], v[180:183], v[42:45]
	v_mfma_f32_16x16x32_bf16 v[30:33], v[134:137], v[188:191], v[30:33]
	v_mfma_f32_16x16x32_bf16 v[26:29], v[142:145], v[188:191], v[26:29]
	v_mfma_f32_16x16x32_bf16 v[14:17], v[134:137], v[200:203], v[14:17]
	v_mfma_f32_16x16x32_bf16 v[10:13], v[142:145], v[200:203], v[10:13]
	v_mfma_f32_16x16x32_bf16 v[54:57], v[146:149], v[168:171], v[54:57]
	v_mfma_f32_16x16x32_bf16 v[50:53], v[154:157], v[168:171], v[50:53]
	v_mfma_f32_16x16x32_bf16 v[38:41], v[146:149], v[176:179], v[38:41]
	v_mfma_f32_16x16x32_bf16 v[34:37], v[154:157], v[176:179], v[34:37]
	v_mfma_f32_16x16x32_bf16 v[22:25], v[146:149], v[184:187], v[22:25]
	v_mfma_f32_16x16x32_bf16 v[18:21], v[154:157], v[184:187], v[18:21]
	v_mfma_f32_16x16x32_bf16 v[6:9], v[146:149], v[192:195], v[6:9]
	v_mfma_f32_16x16x32_bf16 v[2:5], v[154:157], v[192:195], v[2:5]
	v_mfma_f32_16x16x32_bf16 v[54:57], v[150:153], v[172:175], v[54:57]
	v_mfma_f32_16x16x32_bf16 v[50:53], v[164:167], v[172:175], v[50:53]
	v_mfma_f32_16x16x32_bf16 v[38:41], v[150:153], v[180:183], v[38:41]
	v_mfma_f32_16x16x32_bf16 v[34:37], v[164:167], v[180:183], v[34:37]
	v_mfma_f32_16x16x32_bf16 v[22:25], v[150:153], v[188:191], v[22:25]
	v_mfma_f32_16x16x32_bf16 v[18:21], v[164:167], v[188:191], v[18:21]
	v_mfma_f32_16x16x32_bf16 v[6:9], v[150:153], v[200:203], v[6:9]
	v_mfma_f32_16x16x32_bf16 v[2:5], v[164:167], v[200:203], v[2:5]
	s_setprio 0
	s_barrier
; #define PG8_STAGE(bufoff, gbase, voff) do { const Src _g = (gbase); _Pragma("unroll") for (int _i = 0; _i < 2; ++_i) \
;         __builtin_amdgcn_raw_ptr_buffer_load_lds(_g.r, (LAS unsigned*)(lds + (bufoff) + ldsw + _i * 8192), 16, (voff)[_i], _g.o, 0, 0); } while (0)
; #define PG8_WAIT_V(n) asm volatile("s_waitcnt vmcnt(" #n ")" ::: "memory")
; template <class Epi, bool ALIGN_EPI, bool SP2, class Hook>
; __device__ __forceinline__ void gemm_phase(LAS unsigned char* lds, const Gemm g, const StaticOrder& S, const Epi& E, Acc& acc, const bool fresh, const Hook& H, const int wave_id) {
;     ...
;         for (int t = t0; t < nt; t += 2) {
;             const bool last = (t == nt - 2);
;             const Src a1 = cA + (size_t)(t + 1) * kstep;
;             const Src a2 = last ? nA : cA + (size_t)(t + 2) * kstep, b2 = last ? nB : cB + (size_t)(t + 2) * kstep;
;             const Src a3 = a2 + kstep, b3 = b2 + kstep;
;             if (last && has_next) H(nxt);
;             if constexpr (SP2) {
;             PG8_TRIP_SP2(PG8_WAIT_V(8));
;             } else {
;             PG8_LDB(B0, 0, 0); PG8_SCHED; PG8_LDA(At, 0, 0); PG8_STAGE(PG8_SA(1, 1), a1 + hstepA, voffA);
;             PG8_WAIT_L(8); PG8_BAR; PG8_WAIT_L(0); PG8_MMA(0, 0, At, B0); PG8_BAR; PG8_SCHED;
;             PG8_LDB(B1, 0, 1); PG8_STAGE(PG8_SB(0, 0), b2, voffB);
;             PG8_BAR; PG8_WAIT_L(0); PG8_MMA(0, 1, At, B1); PG8_BAR;
;             PG8_LDA(At, 0, 1); PG8_STAGE(PG8_SA(0, 0), a2, voffA);
;             PG8_BAR; PG8_WAIT_L(0); PG8_MMA(1, 0, At, B0); PG8_BAR; PG8_SCHED;
;             PG8_STAGE(PG8_SB(0, 1), b2 + hstep, voffB);
;             PG8_WAIT_V(6); PG8_BAR; PG8_MMA(1, 1, At, B1); PG8_BAR;
;             PG8_LDB(B0, 1, 0); PG8_SCHED; PG8_LDA(At, 1, 0); PG8_STAGE(PG8_SA(0, 1), a2 + hstepA, voffA);
;             PG8_WAIT_L(8); PG8_BAR; PG8_WAIT_L(0); PG8_MMA(0, 0, At, B0); PG8_BAR; PG8_SCHED;
;             PG8_LDB(B1, 1, 1); PG8_STAGE(PG8_SB(1, 0), b3, voffB);
;             PG8_BAR; PG8_WAIT_L(0); PG8_MMA(0, 1, At, B1); PG8_BAR;
;             PG8_LDA(At, 1, 1); PG8_STAGE(PG8_SA(1, 0), a3, voffA);
;             PG8_BAR; PG8_WAIT_L(0); PG8_MMA(1, 0, At, B0); PG8_BAR; PG8_SCHED;
;             PG8_STAGE(PG8_SB(1, 1), b3 + hstep, voffB);
;             PG8_WAIT_V(6); PG8_BAR; PG8_MMA(1, 1, At, B1); PG8_BAR;
;             }
;         }
;         if constexpr (ALIGN_EPI) { if (wr == 0) PG8_BAR; }
	v_add_u32_e32 v142, 0x18000, v161
	v_add_u32_e32 v163, 0x1c000, v161
	ds_read_b128 v[130:133], v142
	ds_read_b128 v[134:137], v142 offset:1024
	ds_read_b128 v[138:141], v142 offset:2048
	ds_read_b128 v[142:145], v142 offset:3072
	ds_read_b128 v[146:149], v163
	ds_read_b128 v[150:153], v163 offset:1024
	ds_read_b128 v[154:157], v163 offset:2048
	ds_read_b128 v[164:167], v163 offset:3072
	s_add_i32 s62, s62, 0x40000
	s_mov_b32 m0, s37
	ds_read_b128 v[168:171], v162 offset:32768
	ds_read_b128 v[172:175], v162 offset:33792
	ds_read_b128 v[176:179], v162 offset:34816
	ds_read_b128 v[180:183], v162 offset:35840
	ds_read_b128 v[184:187], v162 offset:36864
	ds_read_b128 v[188:191], v162 offset:37888
	ds_read_b128 v[192:195], v162 offset:38912
	ds_read_b128 v[200:203], v162 offset:39936
	buffer_load_dwordx4 v0, s[20:23], s62 offen lds
	s_mov_b32 m0, s38
	s_nop 0
	buffer_load_dwordx4 v159, s[20:23], s62 offen lds
	s_waitcnt vmcnt(8)
	s_waitcnt lgkmcnt(0)
	s_setprio 1
	s_barrier
	v_mfma_f32_16x16x32_bf16 v[126:129], v[130:133], v[168:171], v[126:129]
	v_mfma_f32_16x16x32_bf16 v[122:125], v[138:141], v[168:171], v[122:125]
	v_mfma_f32_16x16x32_bf16 v[110:113], v[130:133], v[176:179], v[110:113]
	v_mfma_f32_16x16x32_bf16 v[106:109], v[138:141], v[176:179], v[106:109]
	v_mfma_f32_16x16x32_bf16 v[94:97], v[130:133], v[184:187], v[94:97]
	v_mfma_f32_16x16x32_bf16 v[90:93], v[138:141], v[184:187], v[90:93]
	v_mfma_f32_16x16x32_bf16 v[78:81], v[130:133], v[192:195], v[78:81]
	v_mfma_f32_16x16x32_bf16 v[74:77], v[138:141], v[192:195], v[74:77]
	v_mfma_f32_16x16x32_bf16 v[126:129], v[134:137], v[172:175], v[126:129]
	v_mfma_f32_16x16x32_bf16 v[122:125], v[142:145], v[172:175], v[122:125]
	v_mfma_f32_16x16x32_bf16 v[110:113], v[134:137], v[180:183], v[110:113]
	v_mfma_f32_16x16x32_bf16 v[106:109], v[142:145], v[180:183], v[106:109]
	v_mfma_f32_16x16x32_bf16 v[94:97], v[134:137], v[188:191], v[94:97]
	v_mfma_f32_16x16x32_bf16 v[90:93], v[142:145], v[188:191], v[90:93]
	v_mfma_f32_16x16x32_bf16 v[78:81], v[134:137], v[200:203], v[78:81]
	v_mfma_f32_16x16x32_bf16 v[74:77], v[142:145], v[200:203], v[74:77]
	v_mfma_f32_16x16x32_bf16 v[118:121], v[146:149], v[168:171], v[118:121]
	v_mfma_f32_16x16x32_bf16 v[114:117], v[154:157], v[168:171], v[114:117]
	v_mfma_f32_16x16x32_bf16 v[102:105], v[146:149], v[176:179], v[102:105]
	v_mfma_f32_16x16x32_bf16 v[98:101], v[154:157], v[176:179], v[98:101]
	v_mfma_f32_16x16x32_bf16 v[86:89], v[146:149], v[184:187], v[86:89]
	v_mfma_f32_16x16x32_bf16 v[82:85], v[154:157], v[184:187], v[82:85]
	v_mfma_f32_16x16x32_bf16 v[70:73], v[146:149], v[192:195], v[70:73]
	v_mfma_f32_16x16x32_bf16 v[66:69], v[154:157], v[192:195], v[66:69]
	v_mfma_f32_16x16x32_bf16 v[118:121], v[150:153], v[172:175], v[118:121]
	v_mfma_f32_16x16x32_bf16 v[114:117], v[164:167], v[172:175], v[114:117]
	v_mfma_f32_16x16x32_bf16 v[102:105], v[150:153], v[180:183], v[102:105]
	v_mfma_f32_16x16x32_bf16 v[98:101], v[164:167], v[180:183], v[98:101]
	v_mfma_f32_16x16x32_bf16 v[86:89], v[150:153], v[188:191], v[86:89]
	v_mfma_f32_16x16x32_bf16 v[82:85], v[164:167], v[188:191], v[82:85]
	v_mfma_f32_16x16x32_bf16 v[70:73], v[150:153], v[200:203], v[70:73]
	v_mfma_f32_16x16x32_bf16 v[66:69], v[164:167], v[200:203], v[66:69]
	s_setprio 0
	s_barrier
	s_mov_b32 m0, s39
	s_or_b32 s62, s60, 0x80
	ds_read_b128 v[168:171], v162 offset:49152
	ds_read_b128 v[172:175], v162 offset:50176
	ds_read_b128 v[176:179], v162 offset:51200
	ds_read_b128 v[180:183], v162 offset:52224
	ds_read_b128 v[184:187], v162 offset:53248
	ds_read_b128 v[188:191], v162 offset:54272
	ds_read_b128 v[192:195], v162 offset:55296
	ds_read_b128 v[200:203], v162 offset:56320
	buffer_load_dwordx4 v158, s[16:19], s62 offen lds
	s_mov_b32 m0, s40
	s_add_i32 s60, s60, 0x40080
	buffer_load_dwordx4 v160, s[16:19], s62 offen lds
	s_mov_b32 m0, s43
	s_nop 0
	buffer_load_dwordx4 v158, s[16:19], s60 offen lds
	s_mov_b32 m0, s42
	s_nop 0
	buffer_load_dwordx4 v160, s[16:19], s60 offen lds
	s_mov_b32 m0, s41
	s_nop 0
	buffer_load_dwordx4 v0, s[20:23], s61 offen lds
	s_mov_b32 m0, s33
	s_nop 0
	buffer_load_dwordx4 v159, s[20:23], s61 offen lds
	s_waitcnt vmcnt(8)
	s_waitcnt lgkmcnt(0)
	s_setprio 1
	s_barrier
	v_mfma_f32_16x16x32_bf16 v[62:65], v[130:133], v[168:171], v[62:65]
	v_mfma_f32_16x16x32_bf16 v[58:61], v[138:141], v[168:171], v[58:61]
	v_mfma_f32_16x16x32_bf16 v[46:49], v[130:133], v[176:179], v[46:49]
	v_mfma_f32_16x16x32_bf16 v[42:45], v[138:141], v[176:179], v[42:45]
	v_mfma_f32_16x16x32_bf16 v[30:33], v[130:133], v[184:187], v[30:33]
	v_mfma_f32_16x16x32_bf16 v[26:29], v[138:141], v[184:187], v[26:29]
	v_mfma_f32_16x16x32_bf16 v[14:17], v[130:133], v[192:195], v[14:17]
	v_mfma_f32_16x16x32_bf16 v[10:13], v[138:141], v[192:195], v[10:13]
	v_mfma_f32_16x16x32_bf16 v[62:65], v[134:137], v[172:175], v[62:65]
	v_mfma_f32_16x16x32_bf16 v[58:61], v[142:145], v[172:175], v[58:61]
	v_mfma_f32_16x16x32_bf16 v[46:49], v[134:137], v[180:183], v[46:49]
	v_mfma_f32_16x16x32_bf16 v[42:45], v[142:145], v[180:183], v[42:45]
	v_mfma_f32_16x16x32_bf16 v[30:33], v[134:137], v[188:191], v[30:33]
	v_mfma_f32_16x16x32_bf16 v[26:29], v[142:145], v[188:191], v[26:29]
	v_mfma_f32_16x16x32_bf16 v[14:17], v[134:137], v[200:203], v[14:17]
	v_mfma_f32_16x16x32_bf16 v[10:13], v[142:145], v[200:203], v[10:13]
	v_mfma_f32_16x16x32_bf16 v[54:57], v[146:149], v[168:171], v[54:57]
	v_mfma_f32_16x16x32_bf16 v[50:53], v[154:157], v[168:171], v[50:53]
	v_mfma_f32_16x16x32_bf16 v[38:41], v[146:149], v[176:179], v[38:41]
	v_mfma_f32_16x16x32_bf16 v[34:37], v[154:157], v[176:179], v[34:37]
	v_mfma_f32_16x16x32_bf16 v[22:25], v[146:149], v[184:187], v[22:25]
	v_mfma_f32_16x16x32_bf16 v[18:21], v[154:157], v[184:187], v[18:21]
	v_mfma_f32_16x16x32_bf16 v[6:9], v[146:149], v[192:195], v[6:9]
	v_mfma_f32_16x16x32_bf16 v[2:5], v[154:157], v[192:195], v[2:5]
	v_mfma_f32_16x16x32_bf16 v[54:57], v[150:153], v[172:175], v[54:57]
	v_mfma_f32_16x16x32_bf16 v[50:53], v[164:167], v[172:175], v[50:53]
	v_mfma_f32_16x16x32_bf16 v[38:41], v[150:153], v[180:183], v[38:41]
	v_mfma_f32_16x16x32_bf16 v[34:37], v[164:167], v[180:183], v[34:37]
	v_mfma_f32_16x16x32_bf16 v[22:25], v[150:153], v[188:191], v[22:25]
	v_mfma_f32_16x16x32_bf16 v[18:21], v[164:167], v[188:191], v[18:21]
	v_mfma_f32_16x16x32_bf16 v[6:9], v[150:153], v[200:203], v[6:9]
	v_mfma_f32_16x16x32_bf16 v[2:5], v[164:167], v[200:203], v[2:5]
	s_setprio 0
	s_barrier
	s_add_i32 s59, s59, 2
	s_addk_i32 s2, 0x100
	s_addk_i32 s3, 0x100
	s_cmp_gt_u32 s59, 13
	s_cbranch_scc0 .LBB0_1235
	v_readlane_b32 s2, v251, 45
	v_readlane_b32 s3, v251, 46
	s_and_b64 vcc, exec, s[2:3]
	s_cbranch_vccz .LBB0_1238
	s_barrier

; #define PG8_WAIT_V(n) asm volatile("s_waitcnt vmcnt(" #n ")" ::: "memory")
; #define PG8_BAR __builtin_amdgcn_s_barrier()
; template <class Epi, bool ALIGN_EPI, bool SP2, class Hook>
; __device__ __forceinline__ void gemm_phase(LAS unsigned char* lds, const Gemm g, const StaticOrder& S, const Epi& E, Acc& acc, const bool fresh, const Hook& H, const int wave_id) {
;     ...
;         if (reset) {
; #pragma unroll
;             for (int a = 0; a < 2; ++a)
; #pragma unroll
;                 for (int b = 0; b < 2; ++b)
; #pragma unroll
;                     for (int m = 0; m < 4; ++m)
; #pragma unroll
;                         for (int n = 0; n < 2; ++n) acc[a][b][m][n] = (f32x4){0.f, 0.f, 0.f, 0.f};
;         }
;         cur = nxt; cA = nA; cB = nB; ++ui;
;         if constexpr (ALIGN_EPI) { if (wr == 1) PG8_BAR; }
;         if constexpr (SP2 && Epi::NSTORE > 0) {
;             const Src a1 = cA + kstep, a2 = cA + 2 * kstep, b2 = cB + 2 * kstep, a3 = a2 + kstep, b3 = b2 + kstep;
;             if constexpr (Epi::NSTORE == 16) PG8_TRIP_SP2(PG8_WAIT_V(24)); else PG8_TRIP_SP2(PG8_WAIT_V(16));
;             t0 = 2;
;         }
.LBB0_1452:
	ds_read_b128 v[2:5], v138
	ds_read_b128 v[6:9], v138 offset:1024
	ds_read_b128 v[10:13], v138 offset:2048
	ds_read_b128 v[14:17], v138 offset:3072
	ds_read_b128 v[18:21], v139
	ds_read_b128 v[22:25], v139 offset:1024
	ds_read_b128 v[26:29], v139 offset:2048
	ds_read_b128 v[30:33], v139 offset:3072
	s_or_b32 s3, s50, 0x100
	s_or_b32 s2, s50, 0x180
	s_or_b32 s12, s51, 0x100
	s_or_b32 s13, s50, 0x40080
	s_mov_b32 m0, s45
	ds_read_b128 v[34:37], v137
	ds_read_b128 v[38:41], v137 offset:1024
	ds_read_b128 v[42:45], v137 offset:2048
	ds_read_b128 v[46:49], v137 offset:3072
	ds_read_b128 v[50:53], v137 offset:4096
	ds_read_b128 v[54:57], v137 offset:5120
	ds_read_b128 v[58:61], v137 offset:6144
	ds_read_b128 v[62:65], v137 offset:7168
	buffer_load_dwordx4 v132, s[4:7], s13 offen lds
	s_mov_b32 m0, s46
	s_nop 0
	buffer_load_dwordx4 v134, s[4:7], s13 offen lds
	s_waitcnt vmcnt(16)
	s_waitcnt lgkmcnt(0)
	s_setprio 1
	s_barrier
	v_mfma_f32_16x16x32_bf16 v[90:93], v[2:5], v[58:61], 0
	v_mfma_f32_16x16x32_bf16 v[66:69], v[2:5], v[34:37], 0
	v_mfma_f32_16x16x32_bf16 v[70:73], v[10:13], v[34:37], 0
	v_mfma_f32_16x16x32_bf16 v[74:77], v[2:5], v[42:45], 0
	v_mfma_f32_16x16x32_bf16 v[78:81], v[10:13], v[42:45], 0
	v_mfma_f32_16x16x32_bf16 v[82:85], v[2:5], v[50:53], 0
	v_mfma_f32_16x16x32_bf16 v[86:89], v[10:13], v[50:53], 0
	v_mfma_f32_16x16x32_bf16 v[96:99], v[6:9], v[62:65], v[90:93]
	v_mfma_f32_16x16x32_bf16 v[90:93], v[10:13], v[58:61], 0
	v_mfma_f32_16x16x32_bf16 v[66:69], v[6:9], v[38:41], v[66:69]
	v_mfma_f32_16x16x32_bf16 v[70:73], v[14:17], v[38:41], v[70:73]
	v_mfma_f32_16x16x32_bf16 v[74:77], v[6:9], v[46:49], v[74:77]
	v_mfma_f32_16x16x32_bf16 v[78:81], v[14:17], v[46:49], v[78:81]
	v_mfma_f32_16x16x32_bf16 v[82:85], v[6:9], v[54:57], v[82:85]
	v_mfma_f32_16x16x32_bf16 v[86:89], v[14:17], v[54:57], v[86:89]
	v_mfma_f32_16x16x32_bf16 v[104:107], v[14:17], v[62:65], v[90:93]
	v_mfma_f32_16x16x32_bf16 v[90:93], v[18:21], v[34:37], 0
	v_mfma_f32_16x16x32_bf16 v[34:37], v[26:29], v[34:37], 0
	v_mfma_f32_16x16x32_bf16 v[112:115], v[22:25], v[38:41], v[90:93]
	v_mfma_f32_16x16x32_bf16 v[34:37], v[30:33], v[38:41], v[34:37]
	v_mfma_f32_16x16x32_bf16 v[38:41], v[18:21], v[42:45], 0
	v_mfma_f32_16x16x32_bf16 v[42:45], v[26:29], v[42:45], 0
	v_mfma_f32_16x16x32_bf16 v[38:41], v[22:25], v[46:49], v[38:41]
	v_mfma_f32_16x16x32_bf16 v[42:45], v[30:33], v[46:49], v[42:45]
	v_mfma_f32_16x16x32_bf16 v[46:49], v[18:21], v[50:53], 0
	v_mfma_f32_16x16x32_bf16 v[50:53], v[26:29], v[50:53], 0
	v_mfma_f32_16x16x32_bf16 v[46:49], v[22:25], v[54:57], v[46:49]
	v_mfma_f32_16x16x32_bf16 v[50:53], v[30:33], v[54:57], v[50:53]
	v_mfma_f32_16x16x32_bf16 v[54:57], v[18:21], v[58:61], 0
	v_mfma_f32_16x16x32_bf16 v[58:61], v[26:29], v[58:61], 0
	v_mfma_f32_16x16x32_bf16 v[54:57], v[22:25], v[62:65], v[54:57]
	v_mfma_f32_16x16x32_bf16 v[58:61], v[30:33], v[62:65], v[58:61]
	s_setprio 0
	s_barrier
	s_mov_b32 m0, s92
	ds_read_b128 v[62:65], v137 offset:16384
	ds_read_b128 v[90:93], v137 offset:17408
	ds_read_b128 v[100:103], v137 offset:18432
	ds_read_b128 v[108:111], v137 offset:19456
	ds_read_b128 v[116:119], v137 offset:20480
	ds_read_b128 v[120:123], v137 offset:21504
	ds_read_b128 v[124:127], v137 offset:22528
	ds_read_b128 v[128:131], v137 offset:23552
	buffer_load_dwordx4 v133, s[8:11], s12 offen lds
	s_mov_b32 m0, s93
	s_nop 0
	buffer_load_dwordx4 v135, s[8:11], s12 offen lds
	s_or_b32 s12, s51, 0x40100
	s_mov_b32 m0, s94
	s_nop 0
	buffer_load_dwordx4 v133, s[8:11], s12 offen lds
	s_mov_b32 m0, s95
	s_nop 0
	buffer_load_dwordx4 v135, s[8:11], s12 offen lds
	s_mov_b32 m0, s44
	s_nop 0
	buffer_load_dwordx4 v132, s[4:7], s3 offen lds
	s_mov_b32 m0, s36
	s_nop 0
	buffer_load_dwordx4 v134, s[4:7], s3 offen lds
	s_waitcnt vmcnt(16)
	s_waitcnt lgkmcnt(0)
	s_setprio 1
	s_barrier
	v_mfma_f32_16x16x32_bf16 v[142:145], v[2:5], v[62:65], 0
	v_mfma_f32_16x16x32_bf16 v[150:153], v[2:5], v[100:103], 0
	v_mfma_f32_16x16x32_bf16 v[158:161], v[2:5], v[116:119], 0
	v_mfma_f32_16x16x32_bf16 v[2:5], v[2:5], v[124:127], 0
	v_mfma_f32_16x16x32_bf16 v[142:145], v[6:9], v[90:93], v[142:145]
	v_mfma_f32_16x16x32_bf16 v[150:153], v[6:9], v[108:111], v[150:153]
	v_mfma_f32_16x16x32_bf16 v[158:161], v[6:9], v[120:123], v[158:161]
	v_mfma_f32_16x16x32_bf16 v[2:5], v[6:9], v[128:131], v[2:5]
	v_mfma_f32_16x16x32_bf16 v[6:9], v[10:13], v[124:127], 0
	v_mfma_f32_16x16x32_bf16 v[146:149], v[10:13], v[62:65], 0
	v_mfma_f32_16x16x32_bf16 v[154:157], v[10:13], v[100:103], 0
	v_mfma_f32_16x16x32_bf16 v[162:165], v[10:13], v[116:119], 0
	v_mfma_f32_16x16x32_bf16 v[6:9], v[14:17], v[128:131], v[6:9]
	v_mfma_f32_16x16x32_bf16 v[146:149], v[14:17], v[90:93], v[146:149]
	v_mfma_f32_16x16x32_bf16 v[154:157], v[14:17], v[108:111], v[154:157]
	v_mfma_f32_16x16x32_bf16 v[162:165], v[14:17], v[120:123], v[162:165]
	v_mfma_f32_16x16x32_bf16 v[10:13], v[18:21], v[62:65], 0
	v_mfma_f32_16x16x32_bf16 v[166:169], v[22:25], v[90:93], v[10:13]
	v_mfma_f32_16x16x32_bf16 v[10:13], v[26:29], v[62:65], 0
	v_mfma_f32_16x16x32_bf16 v[170:173], v[30:33], v[90:93], v[10:13]
	v_mfma_f32_16x16x32_bf16 v[10:13], v[18:21], v[100:103], 0
	v_mfma_f32_16x16x32_bf16 v[174:177], v[22:25], v[108:111], v[10:13]
	v_mfma_f32_16x16x32_bf16 v[10:13], v[26:29], v[100:103], 0
	v_mfma_f32_16x16x32_bf16 v[178:181], v[30:33], v[108:111], v[10:13]
	v_mfma_f32_16x16x32_bf16 v[10:13], v[18:21], v[116:119], 0
	v_mfma_f32_16x16x32_bf16 v[182:185], v[22:25], v[120:123], v[10:13]
	v_mfma_f32_16x16x32_bf16 v[10:13], v[26:29], v[116:119], 0
	v_mfma_f32_16x16x32_bf16 v[186:189], v[30:33], v[120:123], v[10:13]
	v_mfma_f32_16x16x32_bf16 v[10:13], v[18:21], v[124:127], 0
	v_mfma_f32_16x16x32_bf16 v[16:19], v[22:25], v[128:131], v[10:13]
	v_mfma_f32_16x16x32_bf16 v[10:13], v[26:29], v[124:127], 0
	v_mfma_f32_16x16x32_bf16 v[190:193], v[30:33], v[128:131], v[10:13]
	s_setprio 0
	s_barrier
; #define PG8_WAIT_V(n) asm volatile("s_waitcnt vmcnt(" #n ")" ::: "memory")
; #define PG8_BAR __builtin_amdgcn_s_barrier()
; template <class Epi, bool ALIGN_EPI, bool SP2, class Hook>
; __device__ __forceinline__ void gemm_phase(LAS unsigned char* lds, const Gemm g, const StaticOrder& S, const Epi& E, Acc& acc, const bool fresh, const Hook& H, const int wave_id) {
;     ...
;         cur = nxt; cA = nA; cB = nB; ++ui;
;         if constexpr (ALIGN_EPI) { if (wr == 1) PG8_BAR; }
;         if constexpr (SP2 && Epi::NSTORE > 0) {
;             const Src a1 = cA + kstep, a2 = cA + 2 * kstep, b2 = cB + 2 * kstep, a3 = a2 + kstep, b3 = b2 + kstep;
;             if constexpr (Epi::NSTORE == 16) PG8_TRIP_SP2(PG8_WAIT_V(24)); else PG8_TRIP_SP2(PG8_WAIT_V(16));
;             t0 = 2;
;         }
	s_nop 4
	ds_read_b128 v[10:13], v140
	ds_read_b128 v[24:27], v140 offset:1024
	ds_read_b128 v[194:197], v140 offset:2048
	ds_read_b128 v[200:203], v140 offset:3072
	ds_read_b128 v[204:207], v141
	ds_read_b128 v[208:211], v141 offset:1024
	ds_read_b128 v[212:215], v141 offset:2048
	ds_read_b128 v[138:141], v141 offset:3072
	s_or_b32 s3, s50, 0x40100
	s_mov_b32 m0, s37
	ds_read_b128 v[20:23], v137 offset:32768
	ds_read_b128 v[28:31], v137 offset:33792
	ds_read_b128 v[216:219], v137 offset:34816
	ds_read_b128 v[220:223], v137 offset:35840
	ds_read_b128 v[228:231], v137 offset:36864
	ds_read_b128 v[232:235], v137 offset:37888
	ds_read_b128 v[236:239], v137 offset:38912
	ds_read_b128 v[240:243], v137 offset:39936
	buffer_load_dwordx4 v132, s[4:7], s3 offen lds
	s_mov_b32 m0, s38
	s_nop 0
	buffer_load_dwordx4 v134, s[4:7], s3 offen lds
	s_waitcnt vmcnt(8)
	s_waitcnt lgkmcnt(0)
	s_setprio 1
	s_barrier
	v_mfma_f32_16x16x32_bf16 v[62:65], v[10:13], v[20:23], v[66:69]
	v_mfma_f32_16x16x32_bf16 v[124:127], v[24:27], v[28:31], v[62:65]
	v_mfma_f32_16x16x32_bf16 v[62:65], v[194:197], v[20:23], v[70:73]
	v_mfma_f32_16x16x32_bf16 v[116:119], v[200:203], v[28:31], v[62:65]
	v_mfma_f32_16x16x32_bf16 v[62:65], v[10:13], v[216:219], v[74:77]
	v_mfma_f32_16x16x32_bf16 v[108:111], v[24:27], v[220:223], v[62:65]
	v_mfma_f32_16x16x32_bf16 v[62:65], v[194:197], v[216:219], v[78:81]
	v_mfma_f32_16x16x32_bf16 v[100:103], v[200:203], v[220:223], v[62:65]
	v_mfma_f32_16x16x32_bf16 v[62:65], v[10:13], v[228:231], v[82:85]
	v_mfma_f32_16x16x32_bf16 v[92:95], v[24:27], v[232:235], v[62:65]
	v_mfma_f32_16x16x32_bf16 v[62:65], v[194:197], v[228:231], v[86:89]
	v_mfma_f32_16x16x32_bf16 v[84:87], v[200:203], v[232:235], v[62:65]
	v_mfma_f32_16x16x32_bf16 v[62:65], v[10:13], v[236:239], v[96:99]
	v_mfma_f32_16x16x32_bf16 v[76:79], v[24:27], v[240:243], v[62:65]
	v_mfma_f32_16x16x32_bf16 v[62:65], v[194:197], v[236:239], v[104:107]
	v_mfma_f32_16x16x32_bf16 v[64:67], v[200:203], v[240:243], v[62:65]
	v_mfma_f32_16x16x32_bf16 v[68:71], v[204:207], v[20:23], v[112:115]
	v_mfma_f32_16x16x32_bf16 v[20:23], v[212:215], v[20:23], v[34:37]
	v_mfma_f32_16x16x32_bf16 v[120:123], v[138:141], v[28:31], v[20:23]
	v_mfma_f32_16x16x32_bf16 v[20:23], v[204:207], v[216:219], v[38:41]
	v_mfma_f32_16x16x32_bf16 v[112:115], v[208:211], v[220:223], v[20:23]
	v_mfma_f32_16x16x32_bf16 v[20:23], v[212:215], v[216:219], v[42:45]
	v_mfma_f32_16x16x32_bf16 v[104:107], v[138:141], v[220:223], v[20:23]
	v_mfma_f32_16x16x32_bf16 v[20:23], v[204:207], v[228:231], v[46:49]
	v_mfma_f32_16x16x32_bf16 v[96:99], v[208:211], v[232:235], v[20:23]
	v_mfma_f32_16x16x32_bf16 v[20:23], v[212:215], v[228:231], v[50:53]
	v_mfma_f32_16x16x32_bf16 v[88:91], v[138:141], v[232:235], v[20:23]
	v_mfma_f32_16x16x32_bf16 v[20:23], v[204:207], v[236:239], v[54:57]
	v_mfma_f32_16x16x32_bf16 v[80:83], v[208:211], v[240:243], v[20:23]
	v_mfma_f32_16x16x32_bf16 v[20:23], v[212:215], v[236:239], v[58:61]
	v_mfma_f32_16x16x32_bf16 v[128:131], v[208:211], v[28:31], v[68:71]
	v_mfma_f32_16x16x32_bf16 v[68:71], v[138:141], v[240:243], v[20:23]
	s_setprio 0
	s_barrier
	s_mov_b32 m0, s39
	s_or_b32 s3, s51, 0x180
	ds_read_b128 v[32:35], v137 offset:49152
	ds_read_b128 v[40:43], v137 offset:50176
	ds_read_b128 v[216:219], v137 offset:51200
	ds_read_b128 v[220:223], v137 offset:52224
	ds_read_b128 v[228:231], v137 offset:53248
	ds_read_b128 v[232:235], v137 offset:54272
	ds_read_b128 v[236:239], v137 offset:55296
	ds_read_b128 v[240:243], v137 offset:56320
	buffer_load_dwordx4 v133, s[8:11], s3 offen lds
	s_mov_b32 m0, s40
	s_nop 0
	buffer_load_dwordx4 v135, s[8:11], s3 offen lds
	s_or_b32 s3, s51, 0x40180
	s_mov_b32 m0, s43
	s_nop 0
	buffer_load_dwordx4 v133, s[8:11], s3 offen lds
	s_mov_b32 m0, s42
	s_nop 0
	buffer_load_dwordx4 v135, s[8:11], s3 offen lds
	s_mov_b32 m0, s41
	s_nop 0
	buffer_load_dwordx4 v132, s[4:7], s2 offen lds
	s_mov_b32 m0, s33
	s_nop 0
	buffer_load_dwordx4 v134, s[4:7], s2 offen lds
	s_waitcnt vmcnt(8)
	s_waitcnt lgkmcnt(0)
	s_setprio 1
	s_barrier
	v_mfma_f32_16x16x32_bf16 v[20:23], v[10:13], v[32:35], v[142:145]
	v_mfma_f32_16x16x32_bf16 v[60:63], v[24:27], v[40:43], v[20:23]
	v_mfma_f32_16x16x32_bf16 v[20:23], v[194:197], v[32:35], v[146:149]
	v_mfma_f32_16x16x32_bf16 v[52:55], v[200:203], v[40:43], v[20:23]
	v_mfma_f32_16x16x32_bf16 v[20:23], v[10:13], v[216:219], v[150:153]
	v_mfma_f32_16x16x32_bf16 v[44:47], v[24:27], v[220:223], v[20:23]
	v_mfma_f32_16x16x32_bf16 v[20:23], v[194:197], v[216:219], v[154:157]
	v_mfma_f32_16x16x32_bf16 v[36:39], v[200:203], v[220:223], v[20:23]
	v_mfma_f32_16x16x32_bf16 v[20:23], v[10:13], v[228:231], v[158:161]
	v_mfma_f32_16x16x32_bf16 v[2:5], v[10:13], v[236:239], v[2:5]
	v_mfma_f32_16x16x32_bf16 v[28:31], v[24:27], v[232:235], v[20:23]
	v_mfma_f32_16x16x32_bf16 v[20:23], v[194:197], v[228:231], v[162:165]
	v_mfma_f32_16x16x32_bf16 v[12:15], v[24:27], v[240:243], v[2:5]
	v_mfma_f32_16x16x32_bf16 v[2:5], v[194:197], v[236:239], v[6:9]
	v_mfma_f32_16x16x32_bf16 v[20:23], v[200:203], v[232:235], v[20:23]
	v_mfma_f32_16x16x32_bf16 v[4:7], v[200:203], v[240:243], v[2:5]
	v_mfma_f32_16x16x32_bf16 v[8:11], v[204:207], v[32:35], v[166:169]
	v_mfma_f32_16x16x32_bf16 v[72:75], v[208:211], v[40:43], v[8:11]
	v_mfma_f32_16x16x32_bf16 v[8:11], v[212:215], v[32:35], v[170:173]
	v_mfma_f32_16x16x32_bf16 v[56:59], v[138:141], v[40:43], v[8:11]
	v_mfma_f32_16x16x32_bf16 v[8:11], v[204:207], v[216:219], v[174:177]
	v_mfma_f32_16x16x32_bf16 v[48:51], v[208:211], v[220:223], v[8:11]
	v_mfma_f32_16x16x32_bf16 v[8:11], v[212:215], v[216:219], v[178:181]
	v_mfma_f32_16x16x32_bf16 v[40:43], v[138:141], v[220:223], v[8:11]
	v_mfma_f32_16x16x32_bf16 v[8:11], v[204:207], v[228:231], v[182:185]
	v_mfma_f32_16x16x32_bf16 v[32:35], v[208:211], v[232:235], v[8:11]
	v_mfma_f32_16x16x32_bf16 v[8:11], v[212:215], v[228:231], v[186:189]
	v_mfma_f32_16x16x32_bf16 v[24:27], v[138:141], v[232:235], v[8:11]
	v_mfma_f32_16x16x32_bf16 v[8:11], v[204:207], v[236:239], v[16:19]
	v_mfma_f32_16x16x32_bf16 v[16:19], v[208:211], v[240:243], v[8:11]
	v_mfma_f32_16x16x32_bf16 v[8:11], v[212:215], v[236:239], v[190:193]
	v_mfma_f32_16x16x32_bf16 v[8:11], v[138:141], v[240:243], v[8:11]
	s_setprio 0
	s_barrier
	s_mov_b64 s[2:3], 0
	v_mov_b64_e32 v[234:235], v[226:227]
	v_mov_b32_e32 v226, v0
	v_mov_b64_e32 v[236:237], v[198:199]
	v_mov_b32_e32 v198, v225

; __device__ __forceinline__ const bf16_t* selA(const Gemm& g, int s) { return sel3(g.A0, g.A1, g.A2, s); }
; __device__ __forceinline__ const bf16_t* selB(const Gemm& g, int s) { return sel3(g.B0, g.B1, g.B2, s); }
; __device__ __forceinline__ Src make_src(const bf16_t* p, size_t off) { Src s_; s_.r = __builtin_amdgcn_make_buffer_rsrc((void*)p, (short)0, 0x7fffffff, 0x00020000); s_.o = (unsigned)off; return s_; }
; #define PG8_WAIT_V(n) asm volatile("s_waitcnt vmcnt(" #n ")" ::: "memory")
; template <class Epi, bool ALIGN_EPI, bool SP2, class Hook>
; __device__ __forceinline__ void gemm_phase(LAS unsigned char* lds, const Gemm g, const StaticOrder& S, const Epi& E, Acc& acc, const bool fresh, const Hook& H, const int wave_id) {
;     ...
;         const bool has_next = S.next(ui + 1, nxt);
;         const Src nA = has_next ? make_src(selA(g, nxt.seg), (size_t)nxt.pm * tstepA) : cA, nB = has_next ? make_src(selB(g, nxt.seg), (size_t)nxt.pn * tstep) : cB;
;         for (int t = t0; t < nt; t += 2) {
;             const bool last = (t == nt - 2);
;             const Src a1 = cA + (size_t)(t + 1) * kstep;
;             const Src a2 = last ? nA : cA + (size_t)(t + 2) * kstep, b2 = last ? nB : cB + (size_t)(t + 2) * kstep;
;             const Src a3 = a2 + kstep, b3 = b2 + kstep;
;             if (last && has_next) H(nxt);
;             if constexpr (SP2) {
;             PG8_TRIP_SP2(PG8_WAIT_V(8));
.LBB0_1461:
	v_add_u32_e32 v138, 0x10000, v136
	v_add_u32_e32 v139, 0x14000, v136
	ds_read_b128 v[140:143], v138
	ds_read_b128 v[144:147], v138 offset:1024
	ds_read_b128 v[148:151], v138 offset:2048
	ds_read_b128 v[152:155], v138 offset:3072
	ds_read_b128 v[156:159], v139
	ds_read_b128 v[160:163], v139 offset:1024
	ds_read_b128 v[164:167], v139 offset:2048
	ds_read_b128 v[168:171], v139 offset:3072
	s_add_i32 s16, s55, 0xfffc0080
	s_cmp_eq_u32 s54, 12
	s_cselect_b32 s59, s50, s16
	s_cselect_b32 s17, s9, s77
	s_cselect_b32 s16, s8, s76
	s_cselect_b32 s19, s11, s29
	s_cselect_b32 s18, s10, s28
	s_cselect_b32 s57, s51, s56
	s_cselect_b32 s20, s4, s12
	s_cselect_b32 s21, s5, s13
	s_cselect_b32 s22, s6, s14
	s_cselect_b32 s23, s7, s15
	s_or_b32 s58, s59, 0x80
	s_mov_b32 m0, s45
	ds_read_b128 v[172:175], v137
	ds_read_b128 v[176:179], v137 offset:1024
	ds_read_b128 v[180:183], v137 offset:2048
	ds_read_b128 v[184:187], v137 offset:3072
	ds_read_b128 v[188:191], v137 offset:4096
	ds_read_b128 v[192:195], v137 offset:5120
	ds_read_b128 v[200:203], v137 offset:6144
	ds_read_b128 v[204:207], v137 offset:7168
	buffer_load_dwordx4 v132, s[12:15], s55 offen lds
	s_mov_b32 m0, s46
	s_nop 0
	buffer_load_dwordx4 v134, s[12:15], s55 offen lds
	s_waitcnt vmcnt(8)
	s_waitcnt lgkmcnt(0)
	s_setprio 1
	s_barrier
	v_mfma_f32_16x16x32_bf16 v[124:127], v[140:143], v[172:175], v[124:127]
	v_mfma_f32_16x16x32_bf16 v[116:119], v[148:151], v[172:175], v[116:119]
	v_mfma_f32_16x16x32_bf16 v[108:111], v[140:143], v[180:183], v[108:111]
	v_mfma_f32_16x16x32_bf16 v[100:103], v[148:151], v[180:183], v[100:103]
	v_mfma_f32_16x16x32_bf16 v[92:95], v[140:143], v[188:191], v[92:95]
	v_mfma_f32_16x16x32_bf16 v[84:87], v[148:151], v[188:191], v[84:87]
	v_mfma_f32_16x16x32_bf16 v[76:79], v[140:143], v[200:203], v[76:79]
	v_mfma_f32_16x16x32_bf16 v[64:67], v[148:151], v[200:203], v[64:67]
	v_mfma_f32_16x16x32_bf16 v[124:127], v[144:147], v[176:179], v[124:127]
	v_mfma_f32_16x16x32_bf16 v[116:119], v[152:155], v[176:179], v[116:119]
	v_mfma_f32_16x16x32_bf16 v[108:111], v[144:147], v[184:187], v[108:111]
	v_mfma_f32_16x16x32_bf16 v[100:103], v[152:155], v[184:187], v[100:103]
	v_mfma_f32_16x16x32_bf16 v[92:95], v[144:147], v[192:195], v[92:95]
	v_mfma_f32_16x16x32_bf16 v[84:87], v[152:155], v[192:195], v[84:87]
	v_mfma_f32_16x16x32_bf16 v[76:79], v[144:147], v[204:207], v[76:79]
	v_mfma_f32_16x16x32_bf16 v[64:67], v[152:155], v[204:207], v[64:67]
	v_mfma_f32_16x16x32_bf16 v[128:131], v[156:159], v[172:175], v[128:131]
	v_mfma_f32_16x16x32_bf16 v[120:123], v[164:167], v[172:175], v[120:123]
	v_mfma_f32_16x16x32_bf16 v[112:115], v[156:159], v[180:183], v[112:115]
	v_mfma_f32_16x16x32_bf16 v[104:107], v[164:167], v[180:183], v[104:107]
	v_mfma_f32_16x16x32_bf16 v[96:99], v[156:159], v[188:191], v[96:99]
	v_mfma_f32_16x16x32_bf16 v[88:91], v[164:167], v[188:191], v[88:91]
	v_mfma_f32_16x16x32_bf16 v[80:83], v[156:159], v[200:203], v[80:83]
	v_mfma_f32_16x16x32_bf16 v[68:71], v[164:167], v[200:203], v[68:71]
	v_mfma_f32_16x16x32_bf16 v[128:131], v[160:163], v[176:179], v[128:131]
	v_mfma_f32_16x16x32_bf16 v[120:123], v[168:171], v[176:179], v[120:123]
	v_mfma_f32_16x16x32_bf16 v[112:115], v[160:163], v[184:187], v[112:115]
	v_mfma_f32_16x16x32_bf16 v[104:107], v[168:171], v[184:187], v[104:107]
	v_mfma_f32_16x16x32_bf16 v[96:99], v[160:163], v[192:195], v[96:99]
	v_mfma_f32_16x16x32_bf16 v[88:91], v[168:171], v[192:195], v[88:91]
	v_mfma_f32_16x16x32_bf16 v[80:83], v[160:163], v[204:207], v[80:83]
	v_mfma_f32_16x16x32_bf16 v[68:71], v[168:171], v[204:207], v[68:71]
	s_setprio 0
	s_barrier
	s_mov_b32 m0, s92
	ds_read_b128 v[172:175], v137 offset:16384
	ds_read_b128 v[176:179], v137 offset:17408
	ds_read_b128 v[180:183], v137 offset:18432
	ds_read_b128 v[184:187], v137 offset:19456
	ds_read_b128 v[188:191], v137 offset:20480
	ds_read_b128 v[192:195], v137 offset:21504
	ds_read_b128 v[200:203], v137 offset:22528
	ds_read_b128 v[204:207], v137 offset:23552
	buffer_load_dwordx4 v133, s[16:19], s57 offen lds
	s_mov_b32 m0, s93
	s_add_i32 s60, s57, 0x40000
	buffer_load_dwordx4 v135, s[16:19], s57 offen lds
	s_mov_b32 m0, s94
	s_nop 0
	buffer_load_dwordx4 v133, s[16:19], s60 offen lds
	s_mov_b32 m0, s95
	s_nop 0
	buffer_load_dwordx4 v135, s[16:19], s60 offen lds
	s_mov_b32 m0, s44
	s_nop 0
	buffer_load_dwordx4 v132, s[20:23], s59 offen lds
	s_mov_b32 m0, s36
	s_nop 0
	buffer_load_dwordx4 v134, s[20:23], s59 offen lds
	s_waitcnt vmcnt(8)
	s_waitcnt lgkmcnt(0)
	s_setprio 1
	s_barrier
	v_mfma_f32_16x16x32_bf16 v[60:63], v[140:143], v[172:175], v[60:63]
	v_mfma_f32_16x16x32_bf16 v[52:55], v[148:151], v[172:175], v[52:55]
	v_mfma_f32_16x16x32_bf16 v[44:47], v[140:143], v[180:183], v[44:47]
	v_mfma_f32_16x16x32_bf16 v[36:39], v[148:151], v[180:183], v[36:39]
	v_mfma_f32_16x16x32_bf16 v[28:31], v[140:143], v[188:191], v[28:31]
	v_mfma_f32_16x16x32_bf16 v[20:23], v[148:151], v[188:191], v[20:23]
	v_mfma_f32_16x16x32_bf16 v[12:15], v[140:143], v[200:203], v[12:15]
	v_mfma_f32_16x16x32_bf16 v[2:5], v[148:151], v[200:203], v[4:7]
	v_mfma_f32_16x16x32_bf16 v[60:63], v[144:147], v[176:179], v[60:63]
	v_mfma_f32_16x16x32_bf16 v[52:55], v[152:155], v[176:179], v[52:55]
	v_mfma_f32_16x16x32_bf16 v[44:47], v[144:147], v[184:187], v[44:47]
	v_mfma_f32_16x16x32_bf16 v[36:39], v[152:155], v[184:187], v[36:39]
	v_mfma_f32_16x16x32_bf16 v[28:31], v[144:147], v[192:195], v[28:31]
	v_mfma_f32_16x16x32_bf16 v[20:23], v[152:155], v[192:195], v[20:23]
	v_mfma_f32_16x16x32_bf16 v[12:15], v[144:147], v[204:207], v[12:15]
	v_mfma_f32_16x16x32_bf16 v[2:5], v[152:155], v[204:207], v[2:5]
	v_mfma_f32_16x16x32_bf16 v[72:75], v[156:159], v[172:175], v[72:75]
	v_mfma_f32_16x16x32_bf16 v[56:59], v[164:167], v[172:175], v[56:59]
	v_mfma_f32_16x16x32_bf16 v[48:51], v[156:159], v[180:183], v[48:51]
	v_mfma_f32_16x16x32_bf16 v[40:43], v[164:167], v[180:183], v[40:43]
	v_mfma_f32_16x16x32_bf16 v[32:35], v[156:159], v[188:191], v[32:35]
	v_mfma_f32_16x16x32_bf16 v[24:27], v[164:167], v[188:191], v[24:27]
	v_mfma_f32_16x16x32_bf16 v[16:19], v[156:159], v[200:203], v[16:19]
	v_mfma_f32_16x16x32_bf16 v[6:9], v[164:167], v[200:203], v[8:11]
	v_mfma_f32_16x16x32_bf16 v[72:75], v[160:163], v[176:179], v[72:75]
	v_mfma_f32_16x16x32_bf16 v[56:59], v[168:171], v[176:179], v[56:59]
	v_mfma_f32_16x16x32_bf16 v[48:51], v[160:163], v[184:187], v[48:51]
	v_mfma_f32_16x16x32_bf16 v[40:43], v[168:171], v[184:187], v[40:43]
	v_mfma_f32_16x16x32_bf16 v[32:35], v[160:163], v[192:195], v[32:35]
	v_mfma_f32_16x16x32_bf16 v[24:27], v[168:171], v[192:195], v[24:27]
	v_mfma_f32_16x16x32_bf16 v[16:19], v[160:163], v[204:207], v[16:19]
	v_mfma_f32_16x16x32_bf16 v[8:11], v[168:171], v[204:207], v[6:9]
	s_setprio 0
	s_barrier
; #define PG8_STAGE(bufoff, gbase, voff) do { const Src _g = (gbase); _Pragma("unroll") for (int _i = 0; _i < 2; ++_i) \
;         __builtin_amdgcn_raw_ptr_buffer_load_lds(_g.r, (LAS unsigned*)(lds + (bufoff) + ldsw + _i * 8192), 16, (voff)[_i], _g.o, 0, 0); } while (0)
; #define PG8_WAIT_V(n) asm volatile("s_waitcnt vmcnt(" #n ")" ::: "memory")
; template <class Epi, bool ALIGN_EPI, bool SP2, class Hook>
; __device__ __forceinline__ void gemm_phase(LAS unsigned char* lds, const Gemm g, const StaticOrder& S, const Epi& E, Acc& acc, const bool fresh, const Hook& H, const int wave_id) {
;     ...
;         for (int t = t0; t < nt; t += 2) {
;             const bool last = (t == nt - 2);
;             const Src a1 = cA + (size_t)(t + 1) * kstep;
;             const Src a2 = last ? nA : cA + (size_t)(t + 2) * kstep, b2 = last ? nB : cB + (size_t)(t + 2) * kstep;
;             const Src a3 = a2 + kstep, b3 = b2 + kstep;
;             if (last && has_next) H(nxt);
;             if constexpr (SP2) {
;             PG8_TRIP_SP2(PG8_WAIT_V(8));
;             } else {
;             PG8_LDB(B0, 0, 0); PG8_SCHED; PG8_LDA(At, 0, 0); PG8_STAGE(PG8_SA(1, 1), a1 + hstepA, voffA);
;             PG8_WAIT_L(8); PG8_BAR; PG8_WAIT_L(0); PG8_MMA(0, 0, At, B0); PG8_BAR; PG8_SCHED;
;             PG8_LDB(B1, 0, 1); PG8_STAGE(PG8_SB(0, 0), b2, voffB);
;             PG8_BAR; PG8_WAIT_L(0); PG8_MMA(0, 1, At, B1); PG8_BAR;
;             PG8_LDA(At, 0, 1); PG8_STAGE(PG8_SA(0, 0), a2, voffA);
;             PG8_BAR; PG8_WAIT_L(0); PG8_MMA(1, 0, At, B0); PG8_BAR; PG8_SCHED;
;             PG8_STAGE(PG8_SB(0, 1), b2 + hstep, voffB);
;             PG8_WAIT_V(6); PG8_BAR; PG8_MMA(1, 1, At, B1); PG8_BAR;
;             PG8_LDB(B0, 1, 0); PG8_SCHED; PG8_LDA(At, 1, 0); PG8_STAGE(PG8_SA(0, 1), a2 + hstepA, voffA);
;             PG8_WAIT_L(8); PG8_BAR; PG8_WAIT_L(0); PG8_MMA(0, 0, At, B0); PG8_BAR; PG8_SCHED;
;             PG8_LDB(B1, 1, 1); PG8_STAGE(PG8_SB(1, 0), b3, voffB);
;             PG8_BAR; PG8_WAIT_L(0); PG8_MMA(0, 1, At, B1); PG8_BAR;
;             PG8_LDA(At, 1, 1); PG8_STAGE(PG8_SA(1, 0), a3, voffA);
;             PG8_BAR; PG8_WAIT_L(0); PG8_MMA(1, 0, At, B0); PG8_BAR; PG8_SCHED;
;             PG8_STAGE(PG8_SB(1, 1), b3 + hstep, voffB);
;             PG8_WAIT_V(6); PG8_BAR; PG8_MMA(1, 1, At, B1); PG8_BAR;
;             }
;         }
;         if constexpr (ALIGN_EPI) { if (wr == 0) PG8_BAR; }
	v_add_u32_e32 v140, 0x18000, v136
	v_add_u32_e32 v141, 0x1c000, v136
	ds_read_b128 v[142:145], v140
	ds_read_b128 v[146:149], v140 offset:1024
	ds_read_b128 v[150:153], v140 offset:2048
	ds_read_b128 v[154:157], v140 offset:3072
	ds_read_b128 v[158:161], v141
	ds_read_b128 v[162:165], v141 offset:1024
	ds_read_b128 v[166:169], v141 offset:2048
	ds_read_b128 v[170:173], v141 offset:3072
	s_add_i32 s59, s59, 0x40000
	s_mov_b32 m0, s37
	ds_read_b128 v[174:177], v137 offset:32768
	ds_read_b128 v[178:181], v137 offset:33792
	ds_read_b128 v[182:185], v137 offset:34816
	ds_read_b128 v[186:189], v137 offset:35840
	ds_read_b128 v[190:193], v137 offset:36864
	ds_read_b128 v[194:197], v137 offset:37888
	ds_read_b128 v[200:203], v137 offset:38912
	ds_read_b128 v[204:207], v137 offset:39936
	buffer_load_dwordx4 v132, s[20:23], s59 offen lds
	s_mov_b32 m0, s38
	s_nop 0
	buffer_load_dwordx4 v134, s[20:23], s59 offen lds
	s_waitcnt vmcnt(8)
	s_waitcnt lgkmcnt(0)
	s_setprio 1
	s_barrier
	v_mfma_f32_16x16x32_bf16 v[124:127], v[142:145], v[174:177], v[124:127]
	v_mfma_f32_16x16x32_bf16 v[116:119], v[150:153], v[174:177], v[116:119]
	v_mfma_f32_16x16x32_bf16 v[108:111], v[142:145], v[182:185], v[108:111]
	v_mfma_f32_16x16x32_bf16 v[100:103], v[150:153], v[182:185], v[100:103]
	v_mfma_f32_16x16x32_bf16 v[92:95], v[142:145], v[190:193], v[92:95]
	v_mfma_f32_16x16x32_bf16 v[84:87], v[150:153], v[190:193], v[84:87]
	v_mfma_f32_16x16x32_bf16 v[76:79], v[142:145], v[200:203], v[76:79]
	v_mfma_f32_16x16x32_bf16 v[64:67], v[150:153], v[200:203], v[64:67]
	v_mfma_f32_16x16x32_bf16 v[124:127], v[146:149], v[178:181], v[124:127]
	v_mfma_f32_16x16x32_bf16 v[116:119], v[154:157], v[178:181], v[116:119]
	v_mfma_f32_16x16x32_bf16 v[108:111], v[146:149], v[186:189], v[108:111]
	v_mfma_f32_16x16x32_bf16 v[100:103], v[154:157], v[186:189], v[100:103]
	v_mfma_f32_16x16x32_bf16 v[92:95], v[146:149], v[194:197], v[92:95]
	v_mfma_f32_16x16x32_bf16 v[84:87], v[154:157], v[194:197], v[84:87]
	v_mfma_f32_16x16x32_bf16 v[76:79], v[146:149], v[204:207], v[76:79]
	v_mfma_f32_16x16x32_bf16 v[64:67], v[154:157], v[204:207], v[64:67]
	v_mfma_f32_16x16x32_bf16 v[128:131], v[158:161], v[174:177], v[128:131]
	v_mfma_f32_16x16x32_bf16 v[120:123], v[166:169], v[174:177], v[120:123]
	v_mfma_f32_16x16x32_bf16 v[112:115], v[158:161], v[182:185], v[112:115]
	v_mfma_f32_16x16x32_bf16 v[104:107], v[166:169], v[182:185], v[104:107]
	v_mfma_f32_16x16x32_bf16 v[96:99], v[158:161], v[190:193], v[96:99]
	v_mfma_f32_16x16x32_bf16 v[88:91], v[166:169], v[190:193], v[88:91]
	v_mfma_f32_16x16x32_bf16 v[80:83], v[158:161], v[200:203], v[80:83]
	v_mfma_f32_16x16x32_bf16 v[68:71], v[166:169], v[200:203], v[68:71]
	v_mfma_f32_16x16x32_bf16 v[128:131], v[162:165], v[178:181], v[128:131]
	v_mfma_f32_16x16x32_bf16 v[120:123], v[170:173], v[178:181], v[120:123]
	v_mfma_f32_16x16x32_bf16 v[112:115], v[162:165], v[186:189], v[112:115]
	v_mfma_f32_16x16x32_bf16 v[104:107], v[170:173], v[186:189], v[104:107]
	v_mfma_f32_16x16x32_bf16 v[96:99], v[162:165], v[194:197], v[96:99]
	v_mfma_f32_16x16x32_bf16 v[88:91], v[170:173], v[194:197], v[88:91]
	v_mfma_f32_16x16x32_bf16 v[80:83], v[162:165], v[204:207], v[80:83]
	v_mfma_f32_16x16x32_bf16 v[68:71], v[170:173], v[204:207], v[68:71]
	s_setprio 0
	s_barrier
	s_mov_b32 m0, s39
	s_or_b32 s59, s57, 0x80
	ds_read_b128 v[174:177], v137 offset:49152
	ds_read_b128 v[178:181], v137 offset:50176
	ds_read_b128 v[182:185], v137 offset:51200
	ds_read_b128 v[186:189], v137 offset:52224
	ds_read_b128 v[190:193], v137 offset:53248
	ds_read_b128 v[194:197], v137 offset:54272
	ds_read_b128 v[200:203], v137 offset:55296
	ds_read_b128 v[204:207], v137 offset:56320
	buffer_load_dwordx4 v133, s[16:19], s59 offen lds
	s_mov_b32 m0, s40
	s_add_i32 s57, s57, 0x40080
	buffer_load_dwordx4 v135, s[16:19], s59 offen lds
	s_mov_b32 m0, s43
	s_nop 0
	buffer_load_dwordx4 v133, s[16:19], s57 offen lds
	s_mov_b32 m0, s42
	s_nop 0
	buffer_load_dwordx4 v135, s[16:19], s57 offen lds
	s_mov_b32 m0, s41
	s_nop 0
	buffer_load_dwordx4 v132, s[20:23], s58 offen lds
	s_mov_b32 m0, s33
	s_nop 0
	buffer_load_dwordx4 v134, s[20:23], s58 offen lds
	s_waitcnt vmcnt(8)
	s_waitcnt lgkmcnt(0)
	s_setprio 1
	s_barrier
	v_mfma_f32_16x16x32_bf16 v[60:63], v[142:145], v[174:177], v[60:63]
	v_mfma_f32_16x16x32_bf16 v[52:55], v[150:153], v[174:177], v[52:55]
	v_mfma_f32_16x16x32_bf16 v[44:47], v[142:145], v[182:185], v[44:47]
	v_mfma_f32_16x16x32_bf16 v[36:39], v[150:153], v[182:185], v[36:39]
	v_mfma_f32_16x16x32_bf16 v[28:31], v[142:145], v[190:193], v[28:31]
	v_mfma_f32_16x16x32_bf16 v[20:23], v[150:153], v[190:193], v[20:23]
	v_mfma_f32_16x16x32_bf16 v[12:15], v[142:145], v[200:203], v[12:15]
	v_mfma_f32_16x16x32_bf16 v[2:5], v[150:153], v[200:203], v[2:5]
	v_mfma_f32_16x16x32_bf16 v[60:63], v[146:149], v[178:181], v[60:63]
	v_mfma_f32_16x16x32_bf16 v[52:55], v[154:157], v[178:181], v[52:55]
	v_mfma_f32_16x16x32_bf16 v[44:47], v[146:149], v[186:189], v[44:47]
	v_mfma_f32_16x16x32_bf16 v[36:39], v[154:157], v[186:189], v[36:39]
	v_mfma_f32_16x16x32_bf16 v[28:31], v[146:149], v[194:197], v[28:31]
	v_mfma_f32_16x16x32_bf16 v[20:23], v[154:157], v[194:197], v[20:23]
	v_mfma_f32_16x16x32_bf16 v[12:15], v[146:149], v[204:207], v[12:15]
	v_mfma_f32_16x16x32_bf16 v[4:7], v[154:157], v[204:207], v[2:5]
	v_mfma_f32_16x16x32_bf16 v[72:75], v[158:161], v[174:177], v[72:75]
	v_mfma_f32_16x16x32_bf16 v[56:59], v[166:169], v[174:177], v[56:59]
	v_mfma_f32_16x16x32_bf16 v[48:51], v[158:161], v[182:185], v[48:51]
	v_mfma_f32_16x16x32_bf16 v[40:43], v[166:169], v[182:185], v[40:43]
	v_mfma_f32_16x16x32_bf16 v[32:35], v[158:161], v[190:193], v[32:35]
	v_mfma_f32_16x16x32_bf16 v[24:27], v[166:169], v[190:193], v[24:27]
	v_mfma_f32_16x16x32_bf16 v[16:19], v[158:161], v[200:203], v[16:19]
	v_mfma_f32_16x16x32_bf16 v[8:11], v[166:169], v[200:203], v[8:11]
	v_mfma_f32_16x16x32_bf16 v[72:75], v[162:165], v[178:181], v[72:75]
	v_mfma_f32_16x16x32_bf16 v[56:59], v[170:173], v[178:181], v[56:59]
	v_mfma_f32_16x16x32_bf16 v[48:51], v[162:165], v[186:189], v[48:51]
	v_mfma_f32_16x16x32_bf16 v[40:43], v[170:173], v[186:189], v[40:43]
	v_mfma_f32_16x16x32_bf16 v[32:35], v[162:165], v[194:197], v[32:35]
	v_mfma_f32_16x16x32_bf16 v[24:27], v[170:173], v[194:197], v[24:27]
	v_mfma_f32_16x16x32_bf16 v[16:19], v[162:165], v[204:207], v[16:19]
	v_mfma_f32_16x16x32_bf16 v[8:11], v[170:173], v[204:207], v[8:11]
	s_setprio 0
	s_barrier
	s_add_i32 s54, s54, 2
	s_addk_i32 s55, 0x100
	s_addk_i32 s56, 0x100
	s_cmp_gt_u32 s54, 13
	s_cbranch_scc0 .LBB0_1461
	v_readlane_b32 s12, v251, 45
	v_readlane_b32 s13, v251, 46
	s_and_b64 vcc, exec, s[12:13]
	s_cbranch_vccz .LBB0_1464
	s_barrier

; __device__ __forceinline__ const bf16_t* selA(const Gemm& g, int s) { return sel3(g.A0, g.A1, g.A2, s); }
; __device__ __forceinline__ const bf16_t* selB(const Gemm& g, int s) { return sel3(g.B0, g.B1, g.B2, s); }
; __device__ __forceinline__ Src make_src(const bf16_t* p, size_t off) { Src s_; s_.r = __builtin_amdgcn_make_buffer_rsrc((void*)p, (short)0, 0x7fffffff, 0x00020000); s_.o = (unsigned)off; return s_; }
; #define PG8_WAIT_V(n) asm volatile("s_waitcnt vmcnt(" #n ")" ::: "memory")
; template <class Epi, bool ALIGN_EPI, bool SP2, class Hook>
; __device__ __forceinline__ void gemm_phase(LAS unsigned char* lds, const Gemm g, const StaticOrder& S, const Epi& E, Acc& acc, const bool fresh, const Hook& H, const int wave_id) {
;     ...
;         const bool has_next = S.next(ui + 1, nxt);
;         const Src nA = has_next ? make_src(selA(g, nxt.seg), (size_t)nxt.pm * tstepA) : cA, nB = has_next ? make_src(selB(g, nxt.seg), (size_t)nxt.pn * tstep) : cB;
;         for (int t = t0; t < nt; t += 2) {
;             const bool last = (t == nt - 2);
;             const Src a1 = cA + (size_t)(t + 1) * kstep;
;             const Src a2 = last ? nA : cA + (size_t)(t + 2) * kstep, b2 = last ? nB : cB + (size_t)(t + 2) * kstep;
;             const Src a3 = a2 + kstep, b3 = b2 + kstep;
;             if (last && has_next) H(nxt);
;             if constexpr (SP2) {
;             PG8_TRIP_SP2(PG8_WAIT_V(8));
.LBB0_1572:
	v_add_u32_e32 v142, 0x10000, v161
	v_add_u32_e32 v163, 0x14000, v161
	ds_read_b128 v[130:133], v142
	ds_read_b128 v[134:137], v142 offset:1024
	ds_read_b128 v[138:141], v142 offset:2048
	ds_read_b128 v[142:145], v142 offset:3072
	ds_read_b128 v[146:149], v163
	ds_read_b128 v[150:153], v163 offset:1024
	ds_read_b128 v[154:157], v163 offset:2048
	ds_read_b128 v[164:167], v163 offset:3072
	s_add_i32 s16, s2, 0xfff40080
	s_cmp_eq_u32 s61, 40
	s_cselect_b32 s64, s57, s16
	s_cselect_b32 s17, s35, s9
	s_cselect_b32 s16, s34, s8
	s_cselect_b32 s19, s51, s53
	s_cselect_b32 s18, s50, s52
	s_cselect_b32 s62, s58, s3
	s_cselect_b32 s20, s10, s12
	s_cselect_b32 s21, s11, s13
	s_cselect_b32 s22, s30, s14
	s_cselect_b32 s23, s31, s15
	s_or_b32 s63, s64, 0x80
	s_mov_b32 m0, s45
	ds_read_b128 v[168:171], v162
	ds_read_b128 v[172:175], v162 offset:1024
	ds_read_b128 v[176:179], v162 offset:2048
	ds_read_b128 v[180:183], v162 offset:3072
	ds_read_b128 v[184:187], v162 offset:4096
	ds_read_b128 v[188:191], v162 offset:5120
	ds_read_b128 v[192:195], v162 offset:6144
	ds_read_b128 v[200:203], v162 offset:7168
	buffer_load_dwordx4 v0, s[12:15], s2 offen lds
	s_mov_b32 m0, s46
	s_nop 0
	buffer_load_dwordx4 v159, s[12:15], s2 offen lds
	s_waitcnt vmcnt(8)
	s_waitcnt lgkmcnt(0)
	s_setprio 1
	s_barrier
	v_mfma_f32_16x16x32_bf16 v[126:129], v[130:133], v[168:171], v[126:129]
	v_mfma_f32_16x16x32_bf16 v[122:125], v[138:141], v[168:171], v[122:125]
	v_mfma_f32_16x16x32_bf16 v[110:113], v[130:133], v[176:179], v[110:113]
	v_mfma_f32_16x16x32_bf16 v[106:109], v[138:141], v[176:179], v[106:109]
	v_mfma_f32_16x16x32_bf16 v[94:97], v[130:133], v[184:187], v[94:97]
	v_mfma_f32_16x16x32_bf16 v[90:93], v[138:141], v[184:187], v[90:93]
	v_mfma_f32_16x16x32_bf16 v[78:81], v[130:133], v[192:195], v[78:81]
	v_mfma_f32_16x16x32_bf16 v[74:77], v[138:141], v[192:195], v[74:77]
	v_mfma_f32_16x16x32_bf16 v[126:129], v[134:137], v[172:175], v[126:129]
	v_mfma_f32_16x16x32_bf16 v[122:125], v[142:145], v[172:175], v[122:125]
	v_mfma_f32_16x16x32_bf16 v[110:113], v[134:137], v[180:183], v[110:113]
	v_mfma_f32_16x16x32_bf16 v[106:109], v[142:145], v[180:183], v[106:109]
	v_mfma_f32_16x16x32_bf16 v[94:97], v[134:137], v[188:191], v[94:97]
	v_mfma_f32_16x16x32_bf16 v[90:93], v[142:145], v[188:191], v[90:93]
	v_mfma_f32_16x16x32_bf16 v[78:81], v[134:137], v[200:203], v[78:81]
	v_mfma_f32_16x16x32_bf16 v[74:77], v[142:145], v[200:203], v[74:77]
	v_mfma_f32_16x16x32_bf16 v[118:121], v[146:149], v[168:171], v[118:121]
	v_mfma_f32_16x16x32_bf16 v[114:117], v[154:157], v[168:171], v[114:117]
	v_mfma_f32_16x16x32_bf16 v[102:105], v[146:149], v[176:179], v[102:105]
	v_mfma_f32_16x16x32_bf16 v[98:101], v[154:157], v[176:179], v[98:101]
	v_mfma_f32_16x16x32_bf16 v[86:89], v[146:149], v[184:187], v[86:89]
	v_mfma_f32_16x16x32_bf16 v[82:85], v[154:157], v[184:187], v[82:85]
	v_mfma_f32_16x16x32_bf16 v[70:73], v[146:149], v[192:195], v[70:73]
	v_mfma_f32_16x16x32_bf16 v[66:69], v[154:157], v[192:195], v[66:69]
	v_mfma_f32_16x16x32_bf16 v[118:121], v[150:153], v[172:175], v[118:121]
	v_mfma_f32_16x16x32_bf16 v[114:117], v[164:167], v[172:175], v[114:117]
	v_mfma_f32_16x16x32_bf16 v[102:105], v[150:153], v[180:183], v[102:105]
	v_mfma_f32_16x16x32_bf16 v[98:101], v[164:167], v[180:183], v[98:101]
	v_mfma_f32_16x16x32_bf16 v[86:89], v[150:153], v[188:191], v[86:89]
	v_mfma_f32_16x16x32_bf16 v[82:85], v[164:167], v[188:191], v[82:85]
	v_mfma_f32_16x16x32_bf16 v[70:73], v[150:153], v[200:203], v[70:73]
	v_mfma_f32_16x16x32_bf16 v[66:69], v[164:167], v[200:203], v[66:69]
	s_setprio 0
	s_barrier
	s_mov_b32 m0, s92
	ds_read_b128 v[168:171], v162 offset:16384
	ds_read_b128 v[172:175], v162 offset:17408
	ds_read_b128 v[176:179], v162 offset:18432
	ds_read_b128 v[180:183], v162 offset:19456
	ds_read_b128 v[184:187], v162 offset:20480
	ds_read_b128 v[188:191], v162 offset:21504
	ds_read_b128 v[192:195], v162 offset:22528
	ds_read_b128 v[200:203], v162 offset:23552
	buffer_load_dwordx4 v158, s[16:19], s62 offen lds
	s_mov_b32 m0, s93
	s_add_i32 s65, s62, 0xb0000
	buffer_load_dwordx4 v160, s[16:19], s62 offen lds
	s_mov_b32 m0, s94
	s_nop 0
	buffer_load_dwordx4 v158, s[16:19], s65 offen lds
	s_mov_b32 m0, s95
	s_nop 0
	buffer_load_dwordx4 v160, s[16:19], s65 offen lds
	s_mov_b32 m0, s44
	s_nop 0
	buffer_load_dwordx4 v0, s[20:23], s64 offen lds
	s_mov_b32 m0, s36
	s_nop 0
	buffer_load_dwordx4 v159, s[20:23], s64 offen lds
	s_waitcnt vmcnt(8)
	s_waitcnt lgkmcnt(0)
	s_setprio 1
	s_barrier
	v_mfma_f32_16x16x32_bf16 v[62:65], v[130:133], v[168:171], v[62:65]
	v_mfma_f32_16x16x32_bf16 v[58:61], v[138:141], v[168:171], v[58:61]
	v_mfma_f32_16x16x32_bf16 v[46:49], v[130:133], v[176:179], v[46:49]
	v_mfma_f32_16x16x32_bf16 v[42:45], v[138:141], v[176:179], v[42:45]
	v_mfma_f32_16x16x32_bf16 v[30:33], v[130:133], v[184:187], v[30:33]
	v_mfma_f32_16x16x32_bf16 v[26:29], v[138:141], v[184:187], v[26:29]
	v_mfma_f32_16x16x32_bf16 v[14:17], v[130:133], v[192:195], v[14:17]
	v_mfma_f32_16x16x32_bf16 v[10:13], v[138:141], v[192:195], v[10:13]
	v_mfma_f32_16x16x32_bf16 v[62:65], v[134:137], v[172:175], v[62:65]
	v_mfma_f32_16x16x32_bf16 v[58:61], v[142:145], v[172:175], v[58:61]
	v_mfma_f32_16x16x32_bf16 v[46:49], v[134:137], v[180:183], v[46:49]
	v_mfma_f32_16x16x32_bf16 v[42:45], v[142:145], v[180:183], v[42:45]
	v_mfma_f32_16x16x32_bf16 v[30:33], v[134:137], v[188:191], v[30:33]
	v_mfma_f32_16x16x32_bf16 v[26:29], v[142:145], v[188:191], v[26:29]
	v_mfma_f32_16x16x32_bf16 v[14:17], v[134:137], v[200:203], v[14:17]
	v_mfma_f32_16x16x32_bf16 v[10:13], v[142:145], v[200:203], v[10:13]
	v_mfma_f32_16x16x32_bf16 v[54:57], v[146:149], v[168:171], v[54:57]
	v_mfma_f32_16x16x32_bf16 v[50:53], v[154:157], v[168:171], v[50:53]
	v_mfma_f32_16x16x32_bf16 v[38:41], v[146:149], v[176:179], v[38:41]
	v_mfma_f32_16x16x32_bf16 v[34:37], v[154:157], v[176:179], v[34:37]
	v_mfma_f32_16x16x32_bf16 v[22:25], v[146:149], v[184:187], v[22:25]
	v_mfma_f32_16x16x32_bf16 v[18:21], v[154:157], v[184:187], v[18:21]
	v_mfma_f32_16x16x32_bf16 v[6:9], v[146:149], v[192:195], v[6:9]
	v_mfma_f32_16x16x32_bf16 v[2:5], v[154:157], v[192:195], v[2:5]
	v_mfma_f32_16x16x32_bf16 v[54:57], v[150:153], v[172:175], v[54:57]
	v_mfma_f32_16x16x32_bf16 v[50:53], v[164:167], v[172:175], v[50:53]
	v_mfma_f32_16x16x32_bf16 v[38:41], v[150:153], v[180:183], v[38:41]
	v_mfma_f32_16x16x32_bf16 v[34:37], v[164:167], v[180:183], v[34:37]
	v_mfma_f32_16x16x32_bf16 v[22:25], v[150:153], v[188:191], v[22:25]
	v_mfma_f32_16x16x32_bf16 v[18:21], v[164:167], v[188:191], v[18:21]
	v_mfma_f32_16x16x32_bf16 v[6:9], v[150:153], v[200:203], v[6:9]
	v_mfma_f32_16x16x32_bf16 v[2:5], v[164:167], v[200:203], v[2:5]
	s_setprio 0
	s_barrier
; #define PG8_STAGE(bufoff, gbase, voff) do { const Src _g = (gbase); _Pragma("unroll") for (int _i = 0; _i < 2; ++_i) \
;         __builtin_amdgcn_raw_ptr_buffer_load_lds(_g.r, (LAS unsigned*)(lds + (bufoff) + ldsw + _i * 8192), 16, (voff)[_i], _g.o, 0, 0); } while (0)
; #define PG8_WAIT_V(n) asm volatile("s_waitcnt vmcnt(" #n ")" ::: "memory")
; template <class Epi, bool ALIGN_EPI, bool SP2, class Hook>
; __device__ __forceinline__ void gemm_phase(LAS unsigned char* lds, const Gemm g, const StaticOrder& S, const Epi& E, Acc& acc, const bool fresh, const Hook& H, const int wave_id) {
;     ...
;         for (int t = t0; t < nt; t += 2) {
;             const bool last = (t == nt - 2);
;             const Src a1 = cA + (size_t)(t + 1) * kstep;
;             const Src a2 = last ? nA : cA + (size_t)(t + 2) * kstep, b2 = last ? nB : cB + (size_t)(t + 2) * kstep;
;             const Src a3 = a2 + kstep, b3 = b2 + kstep;
;             if (last && has_next) H(nxt);
;             if constexpr (SP2) {
;             PG8_TRIP_SP2(PG8_WAIT_V(8));
;             } else {
;             PG8_LDB(B0, 0, 0); PG8_SCHED; PG8_LDA(At, 0, 0); PG8_STAGE(PG8_SA(1, 1), a1 + hstepA, voffA);
;             PG8_WAIT_L(8); PG8_BAR; PG8_WAIT_L(0); PG8_MMA(0, 0, At, B0); PG8_BAR; PG8_SCHED;
;             PG8_LDB(B1, 0, 1); PG8_STAGE(PG8_SB(0, 0), b2, voffB);
;             PG8_BAR; PG8_WAIT_L(0); PG8_MMA(0, 1, At, B1); PG8_BAR;
;             PG8_LDA(At, 0, 1); PG8_STAGE(PG8_SA(0, 0), a2, voffA);
;             PG8_BAR; PG8_WAIT_L(0); PG8_MMA(1, 0, At, B0); PG8_BAR; PG8_SCHED;
;             PG8_STAGE(PG8_SB(0, 1), b2 + hstep, voffB);
;             PG8_WAIT_V(6); PG8_BAR; PG8_MMA(1, 1, At, B1); PG8_BAR;
;             PG8_LDB(B0, 1, 0); PG8_SCHED; PG8_LDA(At, 1, 0); PG8_STAGE(PG8_SA(0, 1), a2 + hstepA, voffA);
;             PG8_WAIT_L(8); PG8_BAR; PG8_WAIT_L(0); PG8_MMA(0, 0, At, B0); PG8_BAR; PG8_SCHED;
;             PG8_LDB(B1, 1, 1); PG8_STAGE(PG8_SB(1, 0), b3, voffB);
;             PG8_BAR; PG8_WAIT_L(0); PG8_MMA(0, 1, At, B1); PG8_BAR;
;             PG8_LDA(At, 1, 1); PG8_STAGE(PG8_SA(1, 0), a3, voffA);
;             PG8_BAR; PG8_WAIT_L(0); PG8_MMA(1, 0, At, B0); PG8_BAR; PG8_SCHED;
;             PG8_STAGE(PG8_SB(1, 1), b3 + hstep, voffB);
;             PG8_WAIT_V(6); PG8_BAR; PG8_MMA(1, 1, At, B1); PG8_BAR;
;             }
;         }
;         if constexpr (ALIGN_EPI) { if (wr == 0) PG8_BAR; }
	v_add_u32_e32 v142, 0x18000, v161
	v_add_u32_e32 v163, 0x1c000, v161
	ds_read_b128 v[130:133], v142
	ds_read_b128 v[134:137], v142 offset:1024
	ds_read_b128 v[138:141], v142 offset:2048
	ds_read_b128 v[142:145], v142 offset:3072
	ds_read_b128 v[146:149], v163
	ds_read_b128 v[150:153], v163 offset:1024
	ds_read_b128 v[154:157], v163 offset:2048
	ds_read_b128 v[164:167], v163 offset:3072
	s_add_i32 s64, s64, 0xc0000
	s_mov_b32 m0, s37
	ds_read_b128 v[168:171], v162 offset:32768
	ds_read_b128 v[172:175], v162 offset:33792
	ds_read_b128 v[176:179], v162 offset:34816
	ds_read_b128 v[180:183], v162 offset:35840
	ds_read_b128 v[184:187], v162 offset:36864
	ds_read_b128 v[188:191], v162 offset:37888
	ds_read_b128 v[192:195], v162 offset:38912
	ds_read_b128 v[200:203], v162 offset:39936
	buffer_load_dwordx4 v0, s[20:23], s64 offen lds
	s_mov_b32 m0, s38
	s_nop 0
	buffer_load_dwordx4 v159, s[20:23], s64 offen lds
	s_waitcnt vmcnt(8)
	s_waitcnt lgkmcnt(0)
	s_setprio 1
	s_barrier
	v_mfma_f32_16x16x32_bf16 v[126:129], v[130:133], v[168:171], v[126:129]
	v_mfma_f32_16x16x32_bf16 v[122:125], v[138:141], v[168:171], v[122:125]
	v_mfma_f32_16x16x32_bf16 v[110:113], v[130:133], v[176:179], v[110:113]
	v_mfma_f32_16x16x32_bf16 v[106:109], v[138:141], v[176:179], v[106:109]
	v_mfma_f32_16x16x32_bf16 v[94:97], v[130:133], v[184:187], v[94:97]
	v_mfma_f32_16x16x32_bf16 v[90:93], v[138:141], v[184:187], v[90:93]
	v_mfma_f32_16x16x32_bf16 v[78:81], v[130:133], v[192:195], v[78:81]
	v_mfma_f32_16x16x32_bf16 v[74:77], v[138:141], v[192:195], v[74:77]
	v_mfma_f32_16x16x32_bf16 v[126:129], v[134:137], v[172:175], v[126:129]
	v_mfma_f32_16x16x32_bf16 v[122:125], v[142:145], v[172:175], v[122:125]
	v_mfma_f32_16x16x32_bf16 v[110:113], v[134:137], v[180:183], v[110:113]
	v_mfma_f32_16x16x32_bf16 v[106:109], v[142:145], v[180:183], v[106:109]
	v_mfma_f32_16x16x32_bf16 v[94:97], v[134:137], v[188:191], v[94:97]
	v_mfma_f32_16x16x32_bf16 v[90:93], v[142:145], v[188:191], v[90:93]
	v_mfma_f32_16x16x32_bf16 v[78:81], v[134:137], v[200:203], v[78:81]
	v_mfma_f32_16x16x32_bf16 v[74:77], v[142:145], v[200:203], v[74:77]
	v_mfma_f32_16x16x32_bf16 v[118:121], v[146:149], v[168:171], v[118:121]
	v_mfma_f32_16x16x32_bf16 v[114:117], v[154:157], v[168:171], v[114:117]
	v_mfma_f32_16x16x32_bf16 v[102:105], v[146:149], v[176:179], v[102:105]
	v_mfma_f32_16x16x32_bf16 v[98:101], v[154:157], v[176:179], v[98:101]
	v_mfma_f32_16x16x32_bf16 v[86:89], v[146:149], v[184:187], v[86:89]
	v_mfma_f32_16x16x32_bf16 v[82:85], v[154:157], v[184:187], v[82:85]
	v_mfma_f32_16x16x32_bf16 v[70:73], v[146:149], v[192:195], v[70:73]
	v_mfma_f32_16x16x32_bf16 v[66:69], v[154:157], v[192:195], v[66:69]
	v_mfma_f32_16x16x32_bf16 v[118:121], v[150:153], v[172:175], v[118:121]
	v_mfma_f32_16x16x32_bf16 v[114:117], v[164:167], v[172:175], v[114:117]
	v_mfma_f32_16x16x32_bf16 v[102:105], v[150:153], v[180:183], v[102:105]
	v_mfma_f32_16x16x32_bf16 v[98:101], v[164:167], v[180:183], v[98:101]
	v_mfma_f32_16x16x32_bf16 v[86:89], v[150:153], v[188:191], v[86:89]
	v_mfma_f32_16x16x32_bf16 v[82:85], v[164:167], v[188:191], v[82:85]
	v_mfma_f32_16x16x32_bf16 v[70:73], v[150:153], v[200:203], v[70:73]
	v_mfma_f32_16x16x32_bf16 v[66:69], v[164:167], v[200:203], v[66:69]
	s_setprio 0
	s_barrier
	s_mov_b32 m0, s39
	s_or_b32 s64, s62, 0x80
	ds_read_b128 v[168:171], v162 offset:49152
	ds_read_b128 v[172:175], v162 offset:50176
	ds_read_b128 v[176:179], v162 offset:51200
	ds_read_b128 v[180:183], v162 offset:52224
	ds_read_b128 v[184:187], v162 offset:53248
	ds_read_b128 v[188:191], v162 offset:54272
	ds_read_b128 v[192:195], v162 offset:55296
	ds_read_b128 v[200:203], v162 offset:56320
	buffer_load_dwordx4 v158, s[16:19], s64 offen lds
	s_mov_b32 m0, s40
	s_add_i32 s62, s62, 0xb0080
	buffer_load_dwordx4 v160, s[16:19], s64 offen lds
	s_mov_b32 m0, s43
	s_nop 0
	buffer_load_dwordx4 v158, s[16:19], s62 offen lds
	s_mov_b32 m0, s42
	s_nop 0
	buffer_load_dwordx4 v160, s[16:19], s62 offen lds
	s_mov_b32 m0, s41
	s_nop 0
	buffer_load_dwordx4 v0, s[20:23], s63 offen lds
	s_mov_b32 m0, s33
	s_nop 0
	buffer_load_dwordx4 v159, s[20:23], s63 offen lds
	s_waitcnt vmcnt(8)
	s_waitcnt lgkmcnt(0)
	s_setprio 1
	s_barrier
	v_mfma_f32_16x16x32_bf16 v[62:65], v[130:133], v[168:171], v[62:65]
	v_mfma_f32_16x16x32_bf16 v[58:61], v[138:141], v[168:171], v[58:61]
	v_mfma_f32_16x16x32_bf16 v[46:49], v[130:133], v[176:179], v[46:49]
	v_mfma_f32_16x16x32_bf16 v[42:45], v[138:141], v[176:179], v[42:45]
	v_mfma_f32_16x16x32_bf16 v[30:33], v[130:133], v[184:187], v[30:33]
	v_mfma_f32_16x16x32_bf16 v[26:29], v[138:141], v[184:187], v[26:29]
	v_mfma_f32_16x16x32_bf16 v[14:17], v[130:133], v[192:195], v[14:17]
	v_mfma_f32_16x16x32_bf16 v[10:13], v[138:141], v[192:195], v[10:13]
	v_mfma_f32_16x16x32_bf16 v[62:65], v[134:137], v[172:175], v[62:65]
	v_mfma_f32_16x16x32_bf16 v[58:61], v[142:145], v[172:175], v[58:61]
	v_mfma_f32_16x16x32_bf16 v[46:49], v[134:137], v[180:183], v[46:49]
	v_mfma_f32_16x16x32_bf16 v[42:45], v[142:145], v[180:183], v[42:45]
	v_mfma_f32_16x16x32_bf16 v[30:33], v[134:137], v[188:191], v[30:33]
	v_mfma_f32_16x16x32_bf16 v[26:29], v[142:145], v[188:191], v[26:29]
	v_mfma_f32_16x16x32_bf16 v[14:17], v[134:137], v[200:203], v[14:17]
	v_mfma_f32_16x16x32_bf16 v[10:13], v[142:145], v[200:203], v[10:13]
	v_mfma_f32_16x16x32_bf16 v[54:57], v[146:149], v[168:171], v[54:57]
	v_mfma_f32_16x16x32_bf16 v[50:53], v[154:157], v[168:171], v[50:53]
	v_mfma_f32_16x16x32_bf16 v[38:41], v[146:149], v[176:179], v[38:41]
	v_mfma_f32_16x16x32_bf16 v[34:37], v[154:157], v[176:179], v[34:37]
	v_mfma_f32_16x16x32_bf16 v[22:25], v[146:149], v[184:187], v[22:25]
	v_mfma_f32_16x16x32_bf16 v[18:21], v[154:157], v[184:187], v[18:21]
	v_mfma_f32_16x16x32_bf16 v[6:9], v[146:149], v[192:195], v[6:9]
	v_mfma_f32_16x16x32_bf16 v[2:5], v[154:157], v[192:195], v[2:5]
	v_mfma_f32_16x16x32_bf16 v[54:57], v[150:153], v[172:175], v[54:57]
	v_mfma_f32_16x16x32_bf16 v[50:53], v[164:167], v[172:175], v[50:53]
	v_mfma_f32_16x16x32_bf16 v[38:41], v[150:153], v[180:183], v[38:41]
	v_mfma_f32_16x16x32_bf16 v[34:37], v[164:167], v[180:183], v[34:37]
	v_mfma_f32_16x16x32_bf16 v[22:25], v[150:153], v[188:191], v[22:25]
	v_mfma_f32_16x16x32_bf16 v[18:21], v[164:167], v[188:191], v[18:21]
	v_mfma_f32_16x16x32_bf16 v[6:9], v[150:153], v[200:203], v[6:9]
	v_mfma_f32_16x16x32_bf16 v[2:5], v[164:167], v[200:203], v[2:5]
	s_setprio 0
	s_barrier
	s_add_i32 s61, s61, 2
	s_addk_i32 s2, 0x100
	s_addk_i32 s3, 0x100
	s_cmp_gt_u32 s61, 41
	s_cbranch_scc0 .LBB0_1572
	v_readlane_b32 s2, v251, 45
	v_readlane_b32 s3, v251, 46
	s_and_b64 vcc, exec, s[2:3]
	s_cbranch_vccz .LBB0_1575
	s_barrier

; __device__ __forceinline__ const bf16_t* selA(const Gemm& g, int s) { return sel3(g.A0, g.A1, g.A2, s); }
; __device__ __forceinline__ const bf16_t* selB(const Gemm& g, int s) { return sel3(g.B0, g.B1, g.B2, s); }
; __device__ __forceinline__ Src make_src(const bf16_t* p, size_t off) { Src s_; s_.r = __builtin_amdgcn_make_buffer_rsrc((void*)p, (short)0, 0x7fffffff, 0x00020000); s_.o = (unsigned)off; return s_; }
; #define PG8_WAIT_V(n) asm volatile("s_waitcnt vmcnt(" #n ")" ::: "memory")
; template <class Epi, bool ALIGN_EPI, bool SP2, class Hook>
; __device__ __forceinline__ void gemm_phase(LAS unsigned char* lds, const Gemm g, const StaticOrder& S, const Epi& E, Acc& acc, const bool fresh, const Hook& H, const int wave_id) {
;     ...
;         const bool has_next = S.next(ui + 1, nxt);
;         const Src nA = has_next ? make_src(selA(g, nxt.seg), (size_t)nxt.pm * tstepA) : cA, nB = has_next ? make_src(selB(g, nxt.seg), (size_t)nxt.pn * tstep) : cB;
;         for (int t = t0; t < nt; t += 2) {
;             const bool last = (t == nt - 2);
;             const Src a1 = cA + (size_t)(t + 1) * kstep;
;             const Src a2 = last ? nA : cA + (size_t)(t + 2) * kstep, b2 = last ? nB : cB + (size_t)(t + 2) * kstep;
;             const Src a3 = a2 + kstep, b3 = b2 + kstep;
;             if (last && has_next) H(nxt);
;             if constexpr (SP2) {
;             PG8_TRIP_SP2(PG8_WAIT_V(8));
.LBB0_1614:
	v_add_u32_e32 v0, 0x10000, v172
	ds_read_b128 v[130:133], v0
	ds_read_b128 v[134:137], v0 offset:1024
	ds_read_b128 v[138:141], v0 offset:2048
	ds_read_b128 v[142:145], v0 offset:3072
	v_add_u32_e32 v0, 0x14000, v172
	ds_read_b128 v[146:149], v0
	ds_read_b128 v[150:153], v0 offset:1024
	ds_read_b128 v[154:157], v0 offset:2048
	ds_read_b128 v[158:161], v0 offset:3072
	s_add_i32 s12, s2, 0xfff40080
	s_cmp_eq_u32 s59, 40
	s_cselect_b32 s62, s55, s12
	s_cselect_b32 s13, s31, s77
	s_cselect_b32 s12, s30, s76
	s_cselect_b32 s15, s35, s51
	s_cselect_b32 s14, s34, s50
	s_cselect_b32 s60, s56, s3
	s_cselect_b32 s16, s20, s8
	s_cselect_b32 s17, s21, s9
	s_cselect_b32 s18, s22, s10
	s_cselect_b32 s19, s23, s11
	s_or_b32 s61, s62, 0x80
	s_mov_b32 m0, s45
	ds_read_b128 v[162:165], v173
	ds_read_b128 v[174:177], v173 offset:1024
	ds_read_b128 v[178:181], v173 offset:2048
	ds_read_b128 v[182:185], v173 offset:3072
	ds_read_b128 v[186:189], v173 offset:4096
	ds_read_b128 v[190:193], v173 offset:5120
	ds_read_b128 v[194:197], v173 offset:6144
	ds_read_b128 v[200:203], v173 offset:7168
	buffer_load_dwordx4 v168, s[8:11], s2 offen lds
	s_mov_b32 m0, s46
	s_nop 0
	buffer_load_dwordx4 v170, s[8:11], s2 offen lds
	s_waitcnt vmcnt(8)
	s_waitcnt lgkmcnt(0)
	s_setprio 1
	s_barrier
	v_mfma_f32_16x16x32_bf16 v[126:129], v[130:133], v[162:165], v[126:129]
	v_mfma_f32_16x16x32_bf16 v[122:125], v[138:141], v[162:165], v[122:125]
	v_mfma_f32_16x16x32_bf16 v[110:113], v[130:133], v[178:181], v[110:113]
	v_mfma_f32_16x16x32_bf16 v[106:109], v[138:141], v[178:181], v[106:109]
	v_mfma_f32_16x16x32_bf16 v[94:97], v[130:133], v[186:189], v[94:97]
	v_mfma_f32_16x16x32_bf16 v[90:93], v[138:141], v[186:189], v[90:93]
	v_mfma_f32_16x16x32_bf16 v[78:81], v[130:133], v[194:197], v[78:81]
	v_mfma_f32_16x16x32_bf16 v[74:77], v[138:141], v[194:197], v[74:77]
	v_mfma_f32_16x16x32_bf16 v[126:129], v[134:137], v[174:177], v[126:129]
	v_mfma_f32_16x16x32_bf16 v[122:125], v[142:145], v[174:177], v[122:125]
	v_mfma_f32_16x16x32_bf16 v[110:113], v[134:137], v[182:185], v[110:113]
	v_mfma_f32_16x16x32_bf16 v[106:109], v[142:145], v[182:185], v[106:109]
	v_mfma_f32_16x16x32_bf16 v[94:97], v[134:137], v[190:193], v[94:97]
	v_mfma_f32_16x16x32_bf16 v[90:93], v[142:145], v[190:193], v[90:93]
	v_mfma_f32_16x16x32_bf16 v[78:81], v[134:137], v[200:203], v[78:81]
	v_mfma_f32_16x16x32_bf16 v[74:77], v[142:145], v[200:203], v[74:77]
	v_mfma_f32_16x16x32_bf16 v[118:121], v[146:149], v[162:165], v[118:121]
	v_mfma_f32_16x16x32_bf16 v[114:117], v[154:157], v[162:165], v[114:117]
	v_mfma_f32_16x16x32_bf16 v[102:105], v[146:149], v[178:181], v[102:105]
	v_mfma_f32_16x16x32_bf16 v[98:101], v[154:157], v[178:181], v[98:101]
	v_mfma_f32_16x16x32_bf16 v[86:89], v[146:149], v[186:189], v[86:89]
	v_mfma_f32_16x16x32_bf16 v[82:85], v[154:157], v[186:189], v[82:85]
	v_mfma_f32_16x16x32_bf16 v[70:73], v[146:149], v[194:197], v[70:73]
	v_mfma_f32_16x16x32_bf16 v[66:69], v[154:157], v[194:197], v[66:69]
	v_mfma_f32_16x16x32_bf16 v[118:121], v[150:153], v[174:177], v[118:121]
	v_mfma_f32_16x16x32_bf16 v[114:117], v[158:161], v[174:177], v[114:117]
	v_mfma_f32_16x16x32_bf16 v[102:105], v[150:153], v[182:185], v[102:105]
	v_mfma_f32_16x16x32_bf16 v[98:101], v[158:161], v[182:185], v[98:101]
	v_mfma_f32_16x16x32_bf16 v[86:89], v[150:153], v[190:193], v[86:89]
	v_mfma_f32_16x16x32_bf16 v[82:85], v[158:161], v[190:193], v[82:85]
	v_mfma_f32_16x16x32_bf16 v[70:73], v[150:153], v[200:203], v[70:73]
	v_mfma_f32_16x16x32_bf16 v[66:69], v[158:161], v[200:203], v[66:69]
	s_setprio 0
	s_barrier
	s_mov_b32 m0, s92
	ds_read_b128 v[162:165], v173 offset:16384
	ds_read_b128 v[174:177], v173 offset:17408
	ds_read_b128 v[178:181], v173 offset:18432
	ds_read_b128 v[182:185], v173 offset:19456
	ds_read_b128 v[186:189], v173 offset:20480
	ds_read_b128 v[190:193], v173 offset:21504
	ds_read_b128 v[194:197], v173 offset:22528
	ds_read_b128 v[200:203], v173 offset:23552
	buffer_load_dwordx4 v169, s[12:15], s60 offen lds
	s_mov_b32 m0, s93
	s_add_i32 s63, s60, 0xb0000
	buffer_load_dwordx4 v171, s[12:15], s60 offen lds
	s_mov_b32 m0, s94
	s_nop 0
	buffer_load_dwordx4 v169, s[12:15], s63 offen lds
	s_mov_b32 m0, s95
	s_nop 0
	buffer_load_dwordx4 v171, s[12:15], s63 offen lds
	s_mov_b32 m0, s44
	s_nop 0
	buffer_load_dwordx4 v168, s[16:19], s62 offen lds
	s_mov_b32 m0, s36
	s_nop 0
	buffer_load_dwordx4 v170, s[16:19], s62 offen lds
	s_waitcnt vmcnt(8)
	s_waitcnt lgkmcnt(0)
	s_setprio 1
	s_barrier
	v_mfma_f32_16x16x32_bf16 v[62:65], v[130:133], v[162:165], v[62:65]
	v_mfma_f32_16x16x32_bf16 v[58:61], v[138:141], v[162:165], v[58:61]
	v_mfma_f32_16x16x32_bf16 v[46:49], v[130:133], v[178:181], v[46:49]
	v_mfma_f32_16x16x32_bf16 v[42:45], v[138:141], v[178:181], v[42:45]
	v_mfma_f32_16x16x32_bf16 v[30:33], v[130:133], v[186:189], v[30:33]
	v_mfma_f32_16x16x32_bf16 v[26:29], v[138:141], v[186:189], v[26:29]
	v_mfma_f32_16x16x32_bf16 v[14:17], v[130:133], v[194:197], v[14:17]
	v_mfma_f32_16x16x32_bf16 v[10:13], v[138:141], v[194:197], v[10:13]
	v_mfma_f32_16x16x32_bf16 v[62:65], v[134:137], v[174:177], v[62:65]
	v_mfma_f32_16x16x32_bf16 v[58:61], v[142:145], v[174:177], v[58:61]
	v_mfma_f32_16x16x32_bf16 v[46:49], v[134:137], v[182:185], v[46:49]
	v_mfma_f32_16x16x32_bf16 v[42:45], v[142:145], v[182:185], v[42:45]
	v_mfma_f32_16x16x32_bf16 v[30:33], v[134:137], v[190:193], v[30:33]
	v_mfma_f32_16x16x32_bf16 v[26:29], v[142:145], v[190:193], v[26:29]
	v_mfma_f32_16x16x32_bf16 v[14:17], v[134:137], v[200:203], v[14:17]
	v_mfma_f32_16x16x32_bf16 v[10:13], v[142:145], v[200:203], v[10:13]
	v_mfma_f32_16x16x32_bf16 v[54:57], v[146:149], v[162:165], v[54:57]
	v_mfma_f32_16x16x32_bf16 v[50:53], v[154:157], v[162:165], v[50:53]
	v_mfma_f32_16x16x32_bf16 v[38:41], v[146:149], v[178:181], v[38:41]
	v_mfma_f32_16x16x32_bf16 v[34:37], v[154:157], v[178:181], v[34:37]
	v_mfma_f32_16x16x32_bf16 v[22:25], v[146:149], v[186:189], v[22:25]
	v_mfma_f32_16x16x32_bf16 v[18:21], v[154:157], v[186:189], v[18:21]
	v_mfma_f32_16x16x32_bf16 v[6:9], v[146:149], v[194:197], v[6:9]
	v_mfma_f32_16x16x32_bf16 v[2:5], v[154:157], v[194:197], v[2:5]
	v_mfma_f32_16x16x32_bf16 v[54:57], v[150:153], v[174:177], v[54:57]
	v_mfma_f32_16x16x32_bf16 v[50:53], v[158:161], v[174:177], v[50:53]
	v_mfma_f32_16x16x32_bf16 v[38:41], v[150:153], v[182:185], v[38:41]
	v_mfma_f32_16x16x32_bf16 v[34:37], v[158:161], v[182:185], v[34:37]
	v_mfma_f32_16x16x32_bf16 v[22:25], v[150:153], v[190:193], v[22:25]
	v_mfma_f32_16x16x32_bf16 v[18:21], v[158:161], v[190:193], v[18:21]
	v_mfma_f32_16x16x32_bf16 v[6:9], v[150:153], v[200:203], v[6:9]
	v_mfma_f32_16x16x32_bf16 v[2:5], v[158:161], v[200:203], v[2:5]
	s_setprio 0
	s_barrier
; #define PG8_STAGE(bufoff, gbase, voff) do { const Src _g = (gbase); _Pragma("unroll") for (int _i = 0; _i < 2; ++_i) \
;         __builtin_amdgcn_raw_ptr_buffer_load_lds(_g.r, (LAS unsigned*)(lds + (bufoff) + ldsw + _i * 8192), 16, (voff)[_i], _g.o, 0, 0); } while (0)
; #define PG8_WAIT_V(n) asm volatile("s_waitcnt vmcnt(" #n ")" ::: "memory")
; template <class Epi, bool ALIGN_EPI, bool SP2, class Hook>
; __device__ __forceinline__ void gemm_phase(LAS unsigned char* lds, const Gemm g, const StaticOrder& S, const Epi& E, Acc& acc, const bool fresh, const Hook& H, const int wave_id) {
;     ...
;         for (int t = t0; t < nt; t += 2) {
;             const bool last = (t == nt - 2);
;             const Src a1 = cA + (size_t)(t + 1) * kstep;
;             const Src a2 = last ? nA : cA + (size_t)(t + 2) * kstep, b2 = last ? nB : cB + (size_t)(t + 2) * kstep;
;             const Src a3 = a2 + kstep, b3 = b2 + kstep;
;             if (last && has_next) H(nxt);
;             if constexpr (SP2) {
;             PG8_TRIP_SP2(PG8_WAIT_V(8));
;             } else {
;             PG8_LDB(B0, 0, 0); PG8_SCHED; PG8_LDA(At, 0, 0); PG8_STAGE(PG8_SA(1, 1), a1 + hstepA, voffA);
;             PG8_WAIT_L(8); PG8_BAR; PG8_WAIT_L(0); PG8_MMA(0, 0, At, B0); PG8_BAR; PG8_SCHED;
;             PG8_LDB(B1, 0, 1); PG8_STAGE(PG8_SB(0, 0), b2, voffB);
;             PG8_BAR; PG8_WAIT_L(0); PG8_MMA(0, 1, At, B1); PG8_BAR;
;             PG8_LDA(At, 0, 1); PG8_STAGE(PG8_SA(0, 0), a2, voffA);
;             PG8_BAR; PG8_WAIT_L(0); PG8_MMA(1, 0, At, B0); PG8_BAR; PG8_SCHED;
;             PG8_STAGE(PG8_SB(0, 1), b2 + hstep, voffB);
;             PG8_WAIT_V(6); PG8_BAR; PG8_MMA(1, 1, At, B1); PG8_BAR;
;             PG8_LDB(B0, 1, 0); PG8_SCHED; PG8_LDA(At, 1, 0); PG8_STAGE(PG8_SA(0, 1), a2 + hstepA, voffA);
;             PG8_WAIT_L(8); PG8_BAR; PG8_WAIT_L(0); PG8_MMA(0, 0, At, B0); PG8_BAR; PG8_SCHED;
;             PG8_LDB(B1, 1, 1); PG8_STAGE(PG8_SB(1, 0), b3, voffB);
;             PG8_BAR; PG8_WAIT_L(0); PG8_MMA(0, 1, At, B1); PG8_BAR;
;             PG8_LDA(At, 1, 1); PG8_STAGE(PG8_SA(1, 0), a3, voffA);
;             PG8_BAR; PG8_WAIT_L(0); PG8_MMA(1, 0, At, B0); PG8_BAR; PG8_SCHED;
;             PG8_STAGE(PG8_SB(1, 1), b3 + hstep, voffB);
;             PG8_WAIT_V(6); PG8_BAR; PG8_MMA(1, 1, At, B1); PG8_BAR;
;             }
;         }
;         if constexpr (ALIGN_EPI) { if (wr == 0) PG8_BAR; }
	v_add_u32_e32 v0, 0x18000, v172
	ds_read_b128 v[130:133], v0
	ds_read_b128 v[134:137], v0 offset:1024
	ds_read_b128 v[138:141], v0 offset:2048
	ds_read_b128 v[142:145], v0 offset:3072
	v_add_u32_e32 v0, 0x1c000, v172
	ds_read_b128 v[146:149], v0
	ds_read_b128 v[150:153], v0 offset:1024
	ds_read_b128 v[154:157], v0 offset:2048
	ds_read_b128 v[158:161], v0 offset:3072
	s_add_i32 s62, s62, 0xc0000
	s_mov_b32 m0, s37
	ds_read_b128 v[162:165], v173 offset:32768
	ds_read_b128 v[174:177], v173 offset:33792
	ds_read_b128 v[178:181], v173 offset:34816
	ds_read_b128 v[182:185], v173 offset:35840
	ds_read_b128 v[186:189], v173 offset:36864
	ds_read_b128 v[190:193], v173 offset:37888
	ds_read_b128 v[194:197], v173 offset:38912
	ds_read_b128 v[200:203], v173 offset:39936
	buffer_load_dwordx4 v168, s[16:19], s62 offen lds
	s_mov_b32 m0, s38
	s_nop 0
	buffer_load_dwordx4 v170, s[16:19], s62 offen lds
	s_waitcnt vmcnt(8)
	s_waitcnt lgkmcnt(0)
	s_setprio 1
	s_barrier
	v_mfma_f32_16x16x32_bf16 v[126:129], v[130:133], v[162:165], v[126:129]
	v_mfma_f32_16x16x32_bf16 v[122:125], v[138:141], v[162:165], v[122:125]
	v_mfma_f32_16x16x32_bf16 v[110:113], v[130:133], v[178:181], v[110:113]
	v_mfma_f32_16x16x32_bf16 v[106:109], v[138:141], v[178:181], v[106:109]
	v_mfma_f32_16x16x32_bf16 v[94:97], v[130:133], v[186:189], v[94:97]
	v_mfma_f32_16x16x32_bf16 v[90:93], v[138:141], v[186:189], v[90:93]
	v_mfma_f32_16x16x32_bf16 v[78:81], v[130:133], v[194:197], v[78:81]
	v_mfma_f32_16x16x32_bf16 v[74:77], v[138:141], v[194:197], v[74:77]
	v_mfma_f32_16x16x32_bf16 v[126:129], v[134:137], v[174:177], v[126:129]
	v_mfma_f32_16x16x32_bf16 v[122:125], v[142:145], v[174:177], v[122:125]
	v_mfma_f32_16x16x32_bf16 v[110:113], v[134:137], v[182:185], v[110:113]
	v_mfma_f32_16x16x32_bf16 v[106:109], v[142:145], v[182:185], v[106:109]
	v_mfma_f32_16x16x32_bf16 v[94:97], v[134:137], v[190:193], v[94:97]
	v_mfma_f32_16x16x32_bf16 v[90:93], v[142:145], v[190:193], v[90:93]
	v_mfma_f32_16x16x32_bf16 v[78:81], v[134:137], v[200:203], v[78:81]
	v_mfma_f32_16x16x32_bf16 v[74:77], v[142:145], v[200:203], v[74:77]
	v_mfma_f32_16x16x32_bf16 v[118:121], v[146:149], v[162:165], v[118:121]
	v_mfma_f32_16x16x32_bf16 v[114:117], v[154:157], v[162:165], v[114:117]
	v_mfma_f32_16x16x32_bf16 v[102:105], v[146:149], v[178:181], v[102:105]
	v_mfma_f32_16x16x32_bf16 v[98:101], v[154:157], v[178:181], v[98:101]
	v_mfma_f32_16x16x32_bf16 v[86:89], v[146:149], v[186:189], v[86:89]
	v_mfma_f32_16x16x32_bf16 v[82:85], v[154:157], v[186:189], v[82:85]
	v_mfma_f32_16x16x32_bf16 v[70:73], v[146:149], v[194:197], v[70:73]
	v_mfma_f32_16x16x32_bf16 v[66:69], v[154:157], v[194:197], v[66:69]
	v_mfma_f32_16x16x32_bf16 v[118:121], v[150:153], v[174:177], v[118:121]
	v_mfma_f32_16x16x32_bf16 v[114:117], v[158:161], v[174:177], v[114:117]
	v_mfma_f32_16x16x32_bf16 v[102:105], v[150:153], v[182:185], v[102:105]
	v_mfma_f32_16x16x32_bf16 v[98:101], v[158:161], v[182:185], v[98:101]
	v_mfma_f32_16x16x32_bf16 v[86:89], v[150:153], v[190:193], v[86:89]
	v_mfma_f32_16x16x32_bf16 v[82:85], v[158:161], v[190:193], v[82:85]
	v_mfma_f32_16x16x32_bf16 v[70:73], v[150:153], v[200:203], v[70:73]
	v_mfma_f32_16x16x32_bf16 v[66:69], v[158:161], v[200:203], v[66:69]
	s_setprio 0
	s_barrier
	s_mov_b32 m0, s39
	s_or_b32 s62, s60, 0x80
	ds_read_b128 v[162:165], v173 offset:49152
	ds_read_b128 v[174:177], v173 offset:50176
	ds_read_b128 v[178:181], v173 offset:51200
	ds_read_b128 v[182:185], v173 offset:52224
	ds_read_b128 v[186:189], v173 offset:53248
	ds_read_b128 v[190:193], v173 offset:54272
	ds_read_b128 v[194:197], v173 offset:55296
	ds_read_b128 v[200:203], v173 offset:56320
	buffer_load_dwordx4 v169, s[12:15], s62 offen lds
	s_mov_b32 m0, s40
	s_add_i32 s60, s60, 0xb0080
	buffer_load_dwordx4 v171, s[12:15], s62 offen lds
	s_mov_b32 m0, s43
	s_nop 0
	buffer_load_dwordx4 v169, s[12:15], s60 offen lds
	s_mov_b32 m0, s42
	s_nop 0
	buffer_load_dwordx4 v171, s[12:15], s60 offen lds
	s_mov_b32 m0, s41
	s_nop 0
	buffer_load_dwordx4 v168, s[16:19], s61 offen lds
	s_mov_b32 m0, s33
	s_nop 0
	buffer_load_dwordx4 v170, s[16:19], s61 offen lds
	s_waitcnt vmcnt(8)
	s_waitcnt lgkmcnt(0)
	s_setprio 1
	s_barrier
	v_mfma_f32_16x16x32_bf16 v[62:65], v[130:133], v[162:165], v[62:65]
	v_mfma_f32_16x16x32_bf16 v[58:61], v[138:141], v[162:165], v[58:61]
	v_mfma_f32_16x16x32_bf16 v[46:49], v[130:133], v[178:181], v[46:49]
	v_mfma_f32_16x16x32_bf16 v[42:45], v[138:141], v[178:181], v[42:45]
	v_mfma_f32_16x16x32_bf16 v[30:33], v[130:133], v[186:189], v[30:33]
	v_mfma_f32_16x16x32_bf16 v[26:29], v[138:141], v[186:189], v[26:29]
	v_mfma_f32_16x16x32_bf16 v[14:17], v[130:133], v[194:197], v[14:17]
	v_mfma_f32_16x16x32_bf16 v[10:13], v[138:141], v[194:197], v[10:13]
	v_mfma_f32_16x16x32_bf16 v[62:65], v[134:137], v[174:177], v[62:65]
	v_mfma_f32_16x16x32_bf16 v[58:61], v[142:145], v[174:177], v[58:61]
	v_mfma_f32_16x16x32_bf16 v[46:49], v[134:137], v[182:185], v[46:49]
	v_mfma_f32_16x16x32_bf16 v[42:45], v[142:145], v[182:185], v[42:45]
	v_mfma_f32_16x16x32_bf16 v[30:33], v[134:137], v[190:193], v[30:33]
	v_mfma_f32_16x16x32_bf16 v[26:29], v[142:145], v[190:193], v[26:29]
	v_mfma_f32_16x16x32_bf16 v[14:17], v[134:137], v[200:203], v[14:17]
	v_mfma_f32_16x16x32_bf16 v[10:13], v[142:145], v[200:203], v[10:13]
	v_mfma_f32_16x16x32_bf16 v[54:57], v[146:149], v[162:165], v[54:57]
	v_mfma_f32_16x16x32_bf16 v[50:53], v[154:157], v[162:165], v[50:53]
	v_mfma_f32_16x16x32_bf16 v[38:41], v[146:149], v[178:181], v[38:41]
	v_mfma_f32_16x16x32_bf16 v[34:37], v[154:157], v[178:181], v[34:37]
	v_mfma_f32_16x16x32_bf16 v[22:25], v[146:149], v[186:189], v[22:25]
	v_mfma_f32_16x16x32_bf16 v[18:21], v[154:157], v[186:189], v[18:21]
	v_mfma_f32_16x16x32_bf16 v[6:9], v[146:149], v[194:197], v[6:9]
	v_mfma_f32_16x16x32_bf16 v[2:5], v[154:157], v[194:197], v[2:5]
	v_mfma_f32_16x16x32_bf16 v[54:57], v[150:153], v[174:177], v[54:57]
	v_mfma_f32_16x16x32_bf16 v[50:53], v[158:161], v[174:177], v[50:53]
	v_mfma_f32_16x16x32_bf16 v[38:41], v[150:153], v[182:185], v[38:41]
	v_mfma_f32_16x16x32_bf16 v[34:37], v[158:161], v[182:185], v[34:37]
	v_mfma_f32_16x16x32_bf16 v[22:25], v[150:153], v[190:193], v[22:25]
	v_mfma_f32_16x16x32_bf16 v[18:21], v[158:161], v[190:193], v[18:21]
	v_mfma_f32_16x16x32_bf16 v[6:9], v[150:153], v[200:203], v[6:9]
	v_mfma_f32_16x16x32_bf16 v[2:5], v[158:161], v[200:203], v[2:5]
	s_setprio 0
	s_barrier
	s_add_i32 s59, s59, 2
	s_addk_i32 s2, 0x100
	s_addk_i32 s3, 0x100
	s_cmp_gt_u32 s59, 41
	s_cbranch_scc0 .LBB0_1614
	v_readlane_b32 s2, v251, 45
	v_readlane_b32 s3, v251, 46
	s_and_b64 vcc, exec, s[2:3]
	s_cbranch_vccz .LBB0_1617
	s_barrier
